# v14
# speedup vs baseline: 1.0229x; 1.0158x over previous
; __device__ __forceinline__ unsigned xb_add(unsigned* p, unsigned v) { return __hip_atomic_fetch_add(p, v, __ATOMIC_RELAXED, __HIP_MEMORY_SCOPE_AGENT); }
; __device__ __forceinline__ unsigned xb_xcc_id() { return (unsigned)__builtin_amdgcn_s_getreg((3 << 11) | 20) & 0xFu; }
;   __shared__ uint4 sh;
;   if (tid == 0) {
;     const unsigned x = xb_xcc_id();
;     xb_add(&bar[XB_XCNT(x)], 1u);
.LBB0_2:
	s_or_b64 exec, exec, s[2:3]
	s_add_u32 s2, s96, 0x2f001000
	v_readlane_b32 s4, v252, 14
	s_addc_u32 s3, s97, 0
	v_mbcnt_lo_u32_b32 v1, -1, 0
	v_mbcnt_hi_u32_b32 v1, -1, v1
	s_and_b32 s33, s4, 0xffffffc0
	s_lshl_b32 s100, s33, 4
	s_add_i32 s100, s100, 16
	v_or_b32_e32 v1, s33, v1
	v_cmp_eq_u32_e32 vcc, 0, v1
	s_and_saveexec_b64 s[4:5], vcc
	s_cbranch_execz .LBB0_22
	s_getreg_b32 s6, hwreg(HW_REG_XCC_ID, 0, 4)
	s_mov_b64 s[8:9], exec
	s_and_b32 s26, s6, 15
	s_lshl_b32 s6, s26, 8
	v_mbcnt_lo_u32_b32 v1, s8, 0
	s_add_u32 s6, s2, s6
	v_mbcnt_hi_u32_b32 v1, s9, v1
	s_addc_u32 s7, s3, 0
	v_cmp_eq_u32_e32 vcc, 0, v1
	s_and_saveexec_b64 s[10:11], vcc
	s_cbranch_execz .LBB0_5
	s_bcnt1_i32_b64 s8, s[8:9]
	v_mov_b32_e32 v1, 0
	v_mov_b32_e32 v2, s8
	global_atomic_add v1, v2, s[6:7] offset:1024

; #define WAIT_V(n) asm volatile("s_waitcnt vmcnt(" #n ")" ::: "memory")
; #define BAR __builtin_amdgcn_s_barrier()
; __device__ __forceinline__ void mainloop_8phase(const u16* __restrict__ A, const u16* __restrict__ Bt, int K,
;                                                 f32x4 (&acc)[2][2][4][2], int wid_s, int ld) {
;     ...
;   int tid = get_tid(wid_s), wid = tid >> 6, lane = tid & 63, wr = wid >> 2, wc = wid & 3, fr = lane & 15, fq = lane >> 4;
;   unsigned goff0, goff1;
;   {
;     int r0, c0, r1, c1;
;     stage_rc(tid * 16, r0, c0);
;     stage_rc(tid * 16 + 8192, r1, c1);
;     goff0 = (unsigned)(r0 * ld + c0) * 2u;
;     goff1 = (unsigned)(r1 * ld + c1) * 2u;
;   }
;   __amdgpu_buffer_rsrc_t rs_A, rs_Bt;
;   {
;     unsigned long ua = (unsigned long)A, ub = (unsigned long)Bt;
;     unsigned alo = __builtin_amdgcn_readfirstlane((unsigned)ua), ahi = __builtin_amdgcn_readfirstlane((unsigned)(ua >> 32));
;     unsigned blo = __builtin_amdgcn_readfirstlane((unsigned)ub), bhi = __builtin_amdgcn_readfirstlane((unsigned)(ub >> 32));
;     rs_A = __builtin_amdgcn_make_buffer_rsrc((void*)(((unsigned long)ahi << 32) | alo), (short)0, 0x7ffffff0, 0x00020000);
;     rs_Bt = __builtin_amdgcn_make_buffer_rsrc((void*)(((unsigned long)bhi << 32) | blo), (short)0, 0x7ffffff0, 0x00020000);
;   }
;   bf16x8 At[4][2], B0[2][2], B1[2][2];
;   const int brow = 0, bcol = 0;
;   int nt = K / G_BK;
;   if (wr == 1) BAR;
;   WAIT_V(0); BAR;
;   STAGE(SB(1, 0), Bt, bcol, 1); STAGE(SA(1, 0), A, brow, 1); STAGE(SB(1, 1), Bt, bcol + G_HALF, 1);
;   WAIT_V(6); BAR;
.LBB0_57:
	s_or_b64 exec, exec, s[0:1]
	v_bfe_i32 v8, v0, 27, 1
	v_lshlrev_b32_e32 v6, 4, v0
	v_lshrrev_b32_e32 v8, 22, v8
	v_add_u32_e32 v8, v6, v8
	v_and_b32_e32 v8, 0xfffffc00, v8
	v_sub_u32_e32 v8, v6, v8
	v_lshrrev_b32_e32 v9, 4, v8
	v_ashrrev_i32_e32 v7, 31, v0
	v_bitop3_b32 v8, v9, v8, 32 bitop3:0x6c
	v_lshrrev_b32_e32 v7, 26, v7
	v_ashrrev_i32_e32 v10, 31, v8
	v_add_u32_e32 v7, v0, v7
	v_lshrrev_b32_e32 v10, 26, v10
	v_ashrrev_i32_e32 v7, 6, v7
	v_add_u32_e32 v10, v8, v10
	v_lshlrev_b32_e32 v9, 3, v7
	v_lshrrev_b32_e32 v11, 6, v10
	v_and_b32_e32 v10, 0xc0, v10
	v_and_b32_e32 v9, 0xffff0, v9
	v_sub_u32_e32 v8, v8, v10
	v_add_u32_e32 v10, 0x2000, v6
	v_add_u32_e32 v9, v11, v9
	v_ashrrev_i32_e32 v11, 31, v10
	v_lshrrev_b32_e32 v11, 22, v11
	v_add_u32_e32 v11, v10, v11
	v_ashrrev_i32_e32 v11, 10, v11
	v_mul_i32_i24_e32 v12, 0x400, v11
	v_sub_u32_e32 v10, v10, v12
	v_lshrrev_b32_e32 v12, 4, v10
	v_bitop3_b32 v10, v12, v10, 32 bitop3:0x6c
	v_ashrrev_i32_e32 v13, 31, v10
	v_lshrrev_b32_e32 v13, 26, v13
	v_add_u32_e32 v13, v10, v13
	v_lshlrev_b32_e32 v7, 5, v7
	v_lshlrev_b32_e32 v12, 3, v11
	v_lshrrev_b32_e32 v14, 6, v13
	v_and_b32_e32 v13, 0xc0, v13
	v_readlane_b32 s6, v254, 43
	v_and_b32_e32 v7, 32, v7
	v_ashrrev_i16_sdwa v8, v244, sext(v8) dst_sel:DWORD dst_unused:UNUSED_PAD src0_sel:DWORD src1_sel:BYTE_0
	v_and_b32_e32 v12, 0xffff0, v12
	v_lshlrev_b32_e32 v11, 5, v11
	v_sub_u32_e32 v10, v10, v13
	s_waitcnt vmcnt(15)
	v_add_u32_e32 v138, s6, v6
	v_bfe_i32 v8, v8, 0, 16
	v_add_u32_e32 v12, v14, v12
	v_and_b32_e32 v11, 32, v11
	v_ashrrev_i16_sdwa v10, v244, sext(v10) dst_sel:DWORD dst_unused:UNUSED_PAD src0_sel:DWORD src1_sel:BYTE_0
	v_lshl_or_b32 v7, v9, 11, v7
	s_and_b32 s5, s13, 0xffff
	v_readfirstlane_b32 s0, v138
	v_add_u32_e32 v139, 0x2000, v138
	v_add_u32_e32 v140, 16, v6
	v_bfe_i32 v10, v10, 0, 16
	v_add_lshl_u32 v137, v7, v8, 1
	v_lshl_or_b32 v7, v12, 11, v11
	s_mov_b32 s20, s12
	s_mov_b32 s21, s5
	s_mov_b32 s22, s90
	s_mov_b32 s23, s91
	s_mov_b32 m0, s0
	s_movk_i32 s1, 0x80
	v_readfirstlane_b32 s0, v139
	v_add_u32_e32 v141, 0x8000, v140
	v_add_lshl_u32 v136, v7, v10, 1
	s_and_b32 s89, s11, 0xffff
	s_waitcnt vmcnt(0)
	s_barrier
	buffer_load_dwordx4 v137, s[20:23], s1 offen lds
	s_mov_b32 m0, s0
	v_readfirstlane_b32 s0, v141
	v_add_u32_e32 v142, 0xa000, v140
	v_readlane_b32 s7, v254, 44
	s_mov_b32 s16, s10
	s_mov_b32 s17, s89
	s_mov_b32 s18, s90
	s_mov_b32 s19, s91
	buffer_load_dwordx4 v136, s[20:23], s1 offen lds
	s_mov_b32 m0, s0
	v_readfirstlane_b32 s0, v142
	v_add_u32_e32 v143, s7, v6
	buffer_load_dwordx4 v137, s[16:19], s1 offen lds
	s_mov_b32 m0, s0
	v_readfirstlane_b32 s0, v143
	v_add_u32_e32 v146, 0x2000, v143
	buffer_load_dwordx4 v136, s[16:19], s1 offen lds
	s_mov_b32 m0, s0
	s_mov_b32 s1, 0x80080
	v_readfirstlane_b32 s0, v146
	buffer_load_dwordx4 v137, s[20:23], s1 offen lds
	s_mov_b32 m0, s0
	v_and_b32_e32 v4, 15, v2
	buffer_load_dwordx4 v136, s[20:23], s1 offen lds
	v_lshlrev_b32_e32 v7, 2, v2
	v_and_b32_e32 v5, 48, v2
	v_lshlrev_b32_e32 v4, 6, v4
	v_and_b32_e32 v7, 32, v7
	v_bitop3_b32 v4, v4, v7, v5 bitop3:0x36
	v_readlane_b32 s0, v254, 41
	v_lshlrev_b32_e32 v2, 6, v2
	s_waitcnt vmcnt(6)
	v_readlane_b32 s1, v254, 42
	v_add_u32_e32 v8, s0, v4
	v_add_u32_e32 v148, s0, v6
	s_movk_i32 s0, 0x3c0
	v_lshlrev_b32_e32 v11, 6, v0
	v_lshlrev_b32_e32 v3, 13, v3
	v_and_or_b32 v2, v2, s0, v5
	v_add_u32_e32 v9, s1, v4
	v_add_u32_e32 v151, s1, v6
	v_add_u32_e32 v6, s6, v4
	v_add_u32_e32 v10, s7, v4
	v_and_b32_e32 v11, 0x3000, v11
	v_add_u32_e32 v4, 16, v4
	v_xad_u32 v5, v2, v7, 16
	v_or_b32_e32 v7, 0x800, v3
	v_or_b32_e32 v12, 0x1000, v3
	v_or_b32_e32 v13, 0x1800, v3
	v_mov_b32_e32 v2, 0
	s_mov_b32 s88, s10
	s_mov_b32 s4, s12
	v_add_u32_e32 v145, 0xc000, v140
	v_add_u32_e32 v144, 0xe000, v140
	v_add_u32_e32 v149, 0x2000, v148
	v_add_u32_e32 v150, 0x2000, v140
	v_add_u32_e32 v152, 0x2000, v151
	v_add_u32_e32 v153, 0x4000, v140
	v_add_u32_e32 v154, 0x6000, v140
	s_mov_b32 s0, -2
	s_mov_b32 s1, 0x80180
	v_add_u32_e32 v155, v8, v11
	s_waitcnt lgkmcnt(0)
	v_add_u32_e32 v133, v4, v3
	v_add_u32_e32 v132, v5, v7
	v_add_u32_e32 v131, v5, v12
	v_add_u32_e32 v130, v5, v13
	v_add_u32_e32 v147, v9, v11
	v_add_u32_e32 v135, v6, v11
	v_add_u32_e32 v134, v10, v11
	v_mov_b32_e32 v3, v2
	v_mov_b32_e32 v4, v2
	v_mov_b32_e32 v5, v2
	v_mov_b32_e32 v6, v2
	v_mov_b32_e32 v7, v2
	v_mov_b32_e32 v8, v2
	v_mov_b32_e32 v9, v2
	v_mov_b32_e32 v10, v2
	v_mov_b32_e32 v11, v2
	v_mov_b32_e32 v12, v2
	v_mov_b32_e32 v13, v2
	v_mov_b32_e32 v14, v2
	v_mov_b32_e32 v15, v2
	v_mov_b32_e32 v16, v2
	v_mov_b32_e32 v17, v2
	v_mov_b32_e32 v18, v2
	v_mov_b32_e32 v19, v2
	v_mov_b32_e32 v20, v2
	v_mov_b32_e32 v21, v2
	v_mov_b32_e32 v22, v2
	v_mov_b32_e32 v23, v2
	v_mov_b32_e32 v24, v2
	v_mov_b32_e32 v25, v2
	v_mov_b32_e32 v26, v2
	v_mov_b32_e32 v27, v2
	v_mov_b32_e32 v28, v2
	v_mov_b32_e32 v29, v2
	v_mov_b32_e32 v30, v2
	v_mov_b32_e32 v31, v2
	v_mov_b32_e32 v32, v2
	v_mov_b32_e32 v33, v2
	v_mov_b32_e32 v34, v2
	v_mov_b32_e32 v35, v2
	v_mov_b32_e32 v36, v2
	v_mov_b32_e32 v37, v2
	v_mov_b32_e32 v38, v2
	v_mov_b32_e32 v39, v2
	v_mov_b32_e32 v40, v2
	v_mov_b32_e32 v41, v2
	v_mov_b32_e32 v42, v2
	v_mov_b32_e32 v43, v2
	v_mov_b32_e32 v44, v2
	v_mov_b32_e32 v45, v2
	v_mov_b32_e32 v46, v2
	v_mov_b32_e32 v47, v2
	v_mov_b32_e32 v48, v2
	v_mov_b32_e32 v49, v2
	v_mov_b32_e32 v50, v2
	v_mov_b32_e32 v51, v2
	v_mov_b32_e32 v52, v2
	v_mov_b32_e32 v53, v2
	v_mov_b32_e32 v54, v2
	v_mov_b32_e32 v55, v2
	v_mov_b32_e32 v56, v2
	v_mov_b32_e32 v57, v2
	v_mov_b32_e32 v58, v2
	v_mov_b32_e32 v59, v2
	v_mov_b32_e32 v60, v2
	v_mov_b32_e32 v61, v2
	v_mov_b32_e32 v62, v2
	v_mov_b32_e32 v63, v2
	v_mov_b32_e32 v64, v2
	v_mov_b32_e32 v65, v2
	v_mov_b32_e32 v66, v2
	v_mov_b32_e32 v67, v2
	s_waitcnt vmcnt(17)
; #define WAIT_V(n) asm volatile("s_waitcnt vmcnt(" #n ")" ::: "memory")
; #define WAIT_L(n) asm volatile("s_waitcnt lgkmcnt(" #n ")" ::: "memory")
; #define BAR __builtin_amdgcn_s_barrier()
; #define SCHED __builtin_amdgcn_sched_barrier(0)
; __device__ __forceinline__ void mainloop_8phase(const u16* __restrict__ A, const u16* __restrict__ Bt, int K,
;                                                 f32x4 (&acc)[2][2][4][2], int wid_s, int ld) {
;     ...
;     LDB(B0, 0, 0); SCHED; LDA(At, 0, 0); STAGE(SA(1, 1), A, brow + G_HALF, t + 1);
;     WAIT_L(8); BAR; WAIT_L(0); MMA(0, 0, At, B0); BAR; SCHED;
;     LDB(B1, 0, 1); STAGE(SB(0, 0), Bt, bcol, t + 2);
;     BAR; WAIT_L(0); MMA(0, 1, At, B1); BAR;
;     LDA(At, 0, 1); STAGE(SA(0, 0), A, brow, t + 2);
;     BAR; WAIT_L(0); MMA(1, 0, At, B0); BAR; SCHED;
;     STAGE(SB(0, 1), Bt, bcol + G_HALF, t + 2);
;     WAIT_V(6); BAR; MMA(1, 1, At, B1); BAR;
;     ...
;     f32x4 acc[2][2][4][2];
; #pragma unroll
;     for (int a = 0; a < 2; ++a)
; #pragma unroll
;       for (int b = 0; b < 2; ++b)
; #pragma unroll
;         for (int c = 0; c < 4; ++c)
; #pragma unroll
;           for (int d = 0; d < 2; ++d) acc[a][b][c][d] = f32x4{0.f, 0.f, 0.f, 0.f};
	v_mov_b32_e32 v68, v2
	v_mov_b32_e32 v69, v2
	v_mov_b32_e32 v70, v2
	v_mov_b32_e32 v71, v2
	s_waitcnt vmcnt(16)
	v_mov_b32_e32 v72, v2
	v_mov_b32_e32 v73, v2
	v_mov_b32_e32 v74, v2
	v_mov_b32_e32 v75, v2
	s_waitcnt vmcnt(15)
	v_mov_b32_e32 v76, v2
	v_mov_b32_e32 v77, v2
	v_mov_b32_e32 v78, v2
	v_mov_b32_e32 v79, v2
	s_waitcnt vmcnt(14)
	v_mov_b32_e32 v80, v2
	v_mov_b32_e32 v81, v2
	v_mov_b32_e32 v82, v2
	v_mov_b32_e32 v83, v2
	v_mov_b32_e32 v84, v2
	v_mov_b32_e32 v85, v2
	v_mov_b32_e32 v86, v2
	v_mov_b32_e32 v87, v2
	v_mov_b32_e32 v88, v2
	v_mov_b32_e32 v89, v2
	v_mov_b32_e32 v90, v2
	v_mov_b32_e32 v91, v2
	v_mov_b32_e32 v92, v2
	v_mov_b32_e32 v93, v2
	v_mov_b32_e32 v94, v2
	v_mov_b32_e32 v95, v2
	v_mov_b32_e32 v96, v2
	v_mov_b32_e32 v97, v2
	v_mov_b32_e32 v98, v2
	v_mov_b32_e32 v99, v2
	v_mov_b32_e32 v100, v2
	v_mov_b32_e32 v101, v2
	v_mov_b32_e32 v102, v2
	v_mov_b32_e32 v103, v2
	v_mov_b32_e32 v104, v2
	v_mov_b32_e32 v105, v2
	v_mov_b32_e32 v106, v2
	v_mov_b32_e32 v107, v2
	v_mov_b32_e32 v108, v2
	v_mov_b32_e32 v109, v2
	v_mov_b32_e32 v110, v2
	v_mov_b32_e32 v111, v2
	v_mov_b32_e32 v112, v2
	v_mov_b32_e32 v113, v2
	v_mov_b32_e32 v114, v2
	v_mov_b32_e32 v115, v2
	v_mov_b32_e32 v116, v2
	v_mov_b32_e32 v117, v2
	v_mov_b32_e32 v118, v2
	v_mov_b32_e32 v119, v2
	v_mov_b32_e32 v120, v2
	v_mov_b32_e32 v121, v2
	v_mov_b32_e32 v122, v2
	v_mov_b32_e32 v123, v2
	v_mov_b32_e32 v124, v2
	v_mov_b32_e32 v125, v2
	v_mov_b32_e32 v126, v2
	v_mov_b32_e32 v127, v2
	v_mov_b32_e32 v128, v2
	v_mov_b32_e32 v129, v2
	s_barrier
	s_mov_b32 s7, s91
.LBB0_58:
	ds_read_b128 v[156:159], v155
	ds_read_b128 v[160:163], v155 offset:1024
	ds_read_b128 v[164:167], v155 offset:2048
	ds_read_b128 v[168:171], v155 offset:3072
	s_add_i32 s6, s1, 0xffffff00
	s_add_i32 m0, s100, 0xc000
	ds_read_b128 v[172:175], v133
	ds_read_b128 v[176:179], v133 offset:1024
	ds_read_b128 v[180:183], v132
	ds_read_b128 v[184:187], v132 offset:1024
	ds_read_b128 v[188:191], v131
	ds_read_b128 v[192:195], v131 offset:1024
	ds_read_b128 v[196:199], v130
	buffer_load_dwordx4 v137, s[88:91], s6 offen lds
	s_add_i32 m0, s100, 0xe000
	ds_read_b128 v[200:203], v130 offset:1024
	buffer_load_dwordx4 v136, s[88:91], s6 offen lds
	s_waitcnt lgkmcnt(8)
	s_barrier
	s_waitcnt lgkmcnt(0)
	v_mfma_f32_16x16x32_bf16 v[126:129], v[172:175], v[156:159], v[126:129]
	v_mfma_f32_16x16x32_bf16 v[122:125], v[172:175], v[164:167], v[122:125]
	v_mfma_f32_16x16x32_bf16 v[118:121], v[180:183], v[156:159], v[118:121]
	v_mfma_f32_16x16x32_bf16 v[114:117], v[180:183], v[164:167], v[114:117]
	v_mfma_f32_16x16x32_bf16 v[110:113], v[188:191], v[156:159], v[110:113]
	v_mfma_f32_16x16x32_bf16 v[106:109], v[188:191], v[164:167], v[106:109]
	v_mfma_f32_16x16x32_bf16 v[102:105], v[196:199], v[156:159], v[102:105]
	v_mfma_f32_16x16x32_bf16 v[98:101], v[196:199], v[164:167], v[98:101]
	v_mfma_f32_16x16x32_bf16 v[126:129], v[176:179], v[160:163], v[126:129]
	v_mfma_f32_16x16x32_bf16 v[122:125], v[176:179], v[168:171], v[122:125]
	v_mfma_f32_16x16x32_bf16 v[118:121], v[184:187], v[160:163], v[118:121]
	v_mfma_f32_16x16x32_bf16 v[114:117], v[184:187], v[168:171], v[114:117]
	v_mfma_f32_16x16x32_bf16 v[110:113], v[192:195], v[160:163], v[110:113]
	v_mfma_f32_16x16x32_bf16 v[106:109], v[192:195], v[168:171], v[106:109]
	v_mfma_f32_16x16x32_bf16 v[102:105], v[200:203], v[160:163], v[102:105]
	v_mfma_f32_16x16x32_bf16 v[98:101], v[200:203], v[168:171], v[98:101]
	s_barrier
	s_add_i32 s15, s1, 0xfff7ff80
	s_mov_b32 s6, s90
	s_add_i32 m0, s100, 0x10000
	ds_read_b128 v[204:207], v147
	ds_read_b128 v[208:211], v147 offset:1024
	ds_read_b128 v[212:215], v147 offset:2048
	buffer_load_dwordx4 v137, s[4:7], s15 offen lds
	s_add_i32 m0, s100, 0x12000
	ds_read_b128 v[216:219], v147 offset:3072
	buffer_load_dwordx4 v136, s[4:7], s15 offen lds
	s_barrier
	s_waitcnt lgkmcnt(0)
	v_mfma_f32_16x16x32_bf16 v[94:97], v[172:175], v[204:207], v[94:97]
	v_mfma_f32_16x16x32_bf16 v[90:93], v[172:175], v[212:215], v[90:93]
	v_mfma_f32_16x16x32_bf16 v[86:89], v[180:183], v[204:207], v[86:89]
	v_mfma_f32_16x16x32_bf16 v[82:85], v[180:183], v[212:215], v[82:85]
	v_mfma_f32_16x16x32_bf16 v[78:81], v[188:191], v[204:207], v[78:81]
	v_mfma_f32_16x16x32_bf16 v[74:77], v[188:191], v[212:215], v[74:77]
	v_mfma_f32_16x16x32_bf16 v[70:73], v[196:199], v[204:207], v[70:73]
	v_mfma_f32_16x16x32_bf16 v[66:69], v[196:199], v[212:215], v[66:69]
	v_mfma_f32_16x16x32_bf16 v[94:97], v[176:179], v[208:211], v[94:97]
	v_mfma_f32_16x16x32_bf16 v[90:93], v[176:179], v[216:219], v[90:93]
	v_mfma_f32_16x16x32_bf16 v[86:89], v[184:187], v[208:211], v[86:89]
	v_mfma_f32_16x16x32_bf16 v[82:85], v[184:187], v[216:219], v[82:85]
	v_mfma_f32_16x16x32_bf16 v[78:81], v[192:195], v[208:211], v[78:81]
	v_mfma_f32_16x16x32_bf16 v[74:77], v[192:195], v[216:219], v[74:77]
	v_mfma_f32_16x16x32_bf16 v[70:73], v[200:203], v[208:211], v[70:73]
	v_mfma_f32_16x16x32_bf16 v[66:69], v[200:203], v[216:219], v[66:69]
	s_mov_b32 m0, s100
	s_barrier
	ds_read_b128 v[172:175], v133 offset:16384
	ds_read_b128 v[176:179], v133 offset:17408
	ds_read_b128 v[180:183], v132 offset:16384
	ds_read_b128 v[184:187], v132 offset:17408
	ds_read_b128 v[188:191], v131 offset:16384
	ds_read_b128 v[192:195], v131 offset:17408
	ds_read_b128 v[196:199], v130 offset:16384
	buffer_load_dwordx4 v137, s[88:91], s15 offen lds
	s_add_i32 m0, s100, 0x2000
	ds_read_b128 v[200:203], v130 offset:17408
	buffer_load_dwordx4 v136, s[88:91], s15 offen lds
	s_barrier
; #define WAIT_V(n) asm volatile("s_waitcnt vmcnt(" #n ")" ::: "memory")
; #define WAIT_L(n) asm volatile("s_waitcnt lgkmcnt(" #n ")" ::: "memory")
; #define BAR __builtin_amdgcn_s_barrier()
; #define SCHED __builtin_amdgcn_sched_barrier(0)
; __device__ __forceinline__ void mainloop_8phase(const u16* __restrict__ A, const u16* __restrict__ Bt, int K,
;                                                 f32x4 (&acc)[2][2][4][2], int wid_s, int ld) {
;     ...
;     WAIT_V(6); BAR; MMA(1, 1, At, B1); BAR;
;     LDB(B0, 1, 0); SCHED; LDA(At, 1, 0); STAGE(SA(0, 1), A, brow + G_HALF, t + 2);
;     WAIT_L(8); BAR; WAIT_L(0); MMA(0, 0, At, B0); BAR; SCHED;
;     LDB(B1, 1, 1); STAGE(SB(1, 0), Bt, bcol, t + 3);
;     BAR; WAIT_L(0); MMA(0, 1, At, B1); BAR;
;     LDA(At, 1, 1); STAGE(SA(1, 0), A, brow, t + 3);
;     BAR; WAIT_L(0); MMA(1, 0, At, B0); BAR; SCHED;
	s_waitcnt lgkmcnt(0)
	v_mfma_f32_16x16x32_bf16 v[62:65], v[172:175], v[156:159], v[62:65]
	v_mfma_f32_16x16x32_bf16 v[58:61], v[172:175], v[164:167], v[58:61]
	v_mfma_f32_16x16x32_bf16 v[54:57], v[180:183], v[156:159], v[54:57]
	v_mfma_f32_16x16x32_bf16 v[50:53], v[180:183], v[164:167], v[50:53]
	v_mfma_f32_16x16x32_bf16 v[46:49], v[188:191], v[156:159], v[46:49]
	v_mfma_f32_16x16x32_bf16 v[42:45], v[188:191], v[164:167], v[42:45]
	v_mfma_f32_16x16x32_bf16 v[38:41], v[196:199], v[156:159], v[38:41]
	v_mfma_f32_16x16x32_bf16 v[34:37], v[196:199], v[164:167], v[34:37]
	v_mfma_f32_16x16x32_bf16 v[62:65], v[176:179], v[160:163], v[62:65]
	v_mfma_f32_16x16x32_bf16 v[58:61], v[176:179], v[168:171], v[58:61]
	v_mfma_f32_16x16x32_bf16 v[54:57], v[184:187], v[160:163], v[54:57]
	v_mfma_f32_16x16x32_bf16 v[50:53], v[184:187], v[168:171], v[50:53]
	v_mfma_f32_16x16x32_bf16 v[46:49], v[192:195], v[160:163], v[46:49]
	v_mfma_f32_16x16x32_bf16 v[42:45], v[192:195], v[168:171], v[42:45]
	v_mfma_f32_16x16x32_bf16 v[38:41], v[200:203], v[160:163], v[38:41]
	v_mfma_f32_16x16x32_bf16 v[34:37], v[200:203], v[168:171], v[34:37]
	s_barrier
	s_add_i32 s15, s1, 0xffffff80
	s_add_i32 m0, s100, 0x14000
	buffer_load_dwordx4 v137, s[4:7], s15 offen lds
	s_add_i32 m0, s100, 0x16000
	s_nop 0
	buffer_load_dwordx4 v136, s[4:7], s15 offen lds
	s_waitcnt vmcnt(6)
	s_barrier
	v_mfma_f32_16x16x32_bf16 v[30:33], v[172:175], v[204:207], v[30:33]
	v_mfma_f32_16x16x32_bf16 v[26:29], v[172:175], v[212:215], v[26:29]
	v_mfma_f32_16x16x32_bf16 v[22:25], v[180:183], v[204:207], v[22:25]
	v_mfma_f32_16x16x32_bf16 v[18:21], v[180:183], v[212:215], v[18:21]
	v_mfma_f32_16x16x32_bf16 v[14:17], v[188:191], v[204:207], v[14:17]
	v_mfma_f32_16x16x32_bf16 v[10:13], v[188:191], v[212:215], v[10:13]
	v_mfma_f32_16x16x32_bf16 v[6:9], v[196:199], v[204:207], v[6:9]
	v_mfma_f32_16x16x32_bf16 v[2:5], v[196:199], v[212:215], v[2:5]
	v_mfma_f32_16x16x32_bf16 v[30:33], v[176:179], v[208:211], v[30:33]
	v_mfma_f32_16x16x32_bf16 v[26:29], v[176:179], v[216:219], v[26:29]
	v_mfma_f32_16x16x32_bf16 v[22:25], v[184:187], v[208:211], v[22:25]
	v_mfma_f32_16x16x32_bf16 v[18:21], v[184:187], v[216:219], v[18:21]
	v_mfma_f32_16x16x32_bf16 v[14:17], v[192:195], v[208:211], v[14:17]
	v_mfma_f32_16x16x32_bf16 v[10:13], v[192:195], v[216:219], v[10:13]
	v_mfma_f32_16x16x32_bf16 v[6:9], v[200:203], v[208:211], v[6:9]
	v_mfma_f32_16x16x32_bf16 v[2:5], v[200:203], v[216:219], v[2:5]
	s_barrier
	ds_read_b128 v[156:159], v135
	ds_read_b128 v[160:163], v135 offset:1024
	ds_read_b128 v[164:167], v135 offset:2048
	ds_read_b128 v[168:171], v135 offset:3072
	s_add_i32 m0, s100, 0x4000
	ds_read_b128 v[172:175], v133 offset:32768
	ds_read_b128 v[176:179], v133 offset:33792
	ds_read_b128 v[180:183], v132 offset:32768
	ds_read_b128 v[184:187], v132 offset:33792
	ds_read_b128 v[188:191], v131 offset:32768
	ds_read_b128 v[192:195], v131 offset:33792
	ds_read_b128 v[196:199], v130 offset:32768
	buffer_load_dwordx4 v137, s[88:91], s15 offen lds
	s_add_i32 m0, s100, 0x6000
	ds_read_b128 v[200:203], v130 offset:33792
	buffer_load_dwordx4 v136, s[88:91], s15 offen lds
	s_waitcnt lgkmcnt(8)
	s_barrier
	s_waitcnt lgkmcnt(0)
	v_mfma_f32_16x16x32_bf16 v[126:129], v[172:175], v[156:159], v[126:129]
	v_mfma_f32_16x16x32_bf16 v[122:125], v[172:175], v[164:167], v[122:125]
	v_mfma_f32_16x16x32_bf16 v[118:121], v[180:183], v[156:159], v[118:121]
	v_mfma_f32_16x16x32_bf16 v[114:117], v[180:183], v[164:167], v[114:117]
	v_mfma_f32_16x16x32_bf16 v[110:113], v[188:191], v[156:159], v[110:113]
	v_mfma_f32_16x16x32_bf16 v[106:109], v[188:191], v[164:167], v[106:109]
	v_mfma_f32_16x16x32_bf16 v[102:105], v[196:199], v[156:159], v[102:105]
	v_mfma_f32_16x16x32_bf16 v[98:101], v[196:199], v[164:167], v[98:101]
	v_mfma_f32_16x16x32_bf16 v[126:129], v[176:179], v[160:163], v[126:129]
	v_mfma_f32_16x16x32_bf16 v[122:125], v[176:179], v[168:171], v[122:125]
	v_mfma_f32_16x16x32_bf16 v[118:121], v[184:187], v[160:163], v[118:121]
	v_mfma_f32_16x16x32_bf16 v[114:117], v[184:187], v[168:171], v[114:117]
	v_mfma_f32_16x16x32_bf16 v[110:113], v[192:195], v[160:163], v[110:113]
	v_mfma_f32_16x16x32_bf16 v[106:109], v[192:195], v[168:171], v[106:109]
	v_mfma_f32_16x16x32_bf16 v[102:105], v[200:203], v[160:163], v[102:105]
	v_mfma_f32_16x16x32_bf16 v[98:101], v[200:203], v[168:171], v[98:101]
	s_barrier
	s_add_i32 s15, s1, 0xfff80000
	s_add_i32 m0, s100, 0x18000
	ds_read_b128 v[204:207], v134
	ds_read_b128 v[208:211], v134 offset:1024
	ds_read_b128 v[212:215], v134 offset:2048
	buffer_load_dwordx4 v137, s[4:7], s15 offen lds
	s_add_i32 m0, s100, 0x1a000
	ds_read_b128 v[216:219], v134 offset:3072
	buffer_load_dwordx4 v136, s[4:7], s15 offen lds
	s_barrier
	s_waitcnt lgkmcnt(0)
	v_mfma_f32_16x16x32_bf16 v[94:97], v[172:175], v[204:207], v[94:97]
	v_mfma_f32_16x16x32_bf16 v[90:93], v[172:175], v[212:215], v[90:93]
	v_mfma_f32_16x16x32_bf16 v[86:89], v[180:183], v[204:207], v[86:89]
	v_mfma_f32_16x16x32_bf16 v[82:85], v[180:183], v[212:215], v[82:85]
	v_mfma_f32_16x16x32_bf16 v[78:81], v[188:191], v[204:207], v[78:81]
	v_mfma_f32_16x16x32_bf16 v[74:77], v[188:191], v[212:215], v[74:77]
	v_mfma_f32_16x16x32_bf16 v[70:73], v[196:199], v[204:207], v[70:73]
	v_mfma_f32_16x16x32_bf16 v[66:69], v[196:199], v[212:215], v[66:69]
	v_mfma_f32_16x16x32_bf16 v[94:97], v[176:179], v[208:211], v[94:97]
	v_mfma_f32_16x16x32_bf16 v[90:93], v[176:179], v[216:219], v[90:93]
	v_mfma_f32_16x16x32_bf16 v[86:89], v[184:187], v[208:211], v[86:89]
	v_mfma_f32_16x16x32_bf16 v[82:85], v[184:187], v[216:219], v[82:85]
	v_mfma_f32_16x16x32_bf16 v[78:81], v[192:195], v[208:211], v[78:81]
	v_mfma_f32_16x16x32_bf16 v[74:77], v[192:195], v[216:219], v[74:77]
	v_mfma_f32_16x16x32_bf16 v[70:73], v[200:203], v[208:211], v[70:73]
	v_mfma_f32_16x16x32_bf16 v[66:69], v[200:203], v[216:219], v[66:69]
	s_add_i32 m0, s100, 0x8000
	s_barrier
; #define WAIT_V(n) asm volatile("s_waitcnt vmcnt(" #n ")" ::: "memory")
; #define WAIT_L(n) asm volatile("s_waitcnt lgkmcnt(" #n ")" ::: "memory")
; #define BAR __builtin_amdgcn_s_barrier()
; #define SCHED __builtin_amdgcn_sched_barrier(0)
; __device__ __forceinline__ void mainloop_8phase(const u16* __restrict__ A, const u16* __restrict__ Bt, int K,
;                                                 f32x4 (&acc)[2][2][4][2], int wid_s, int ld) {
;     ...
;     BAR; WAIT_L(0); MMA(1, 0, At, B0); BAR; SCHED;
;     STAGE(SB(1, 1), Bt, bcol + G_HALF, t + 3);
;     WAIT_V(6); BAR; MMA(1, 1, At, B1); BAR;
;   }
;   { LDB(B0, 0, 0); LDA(At, 0, 0); STAGE(SA(1, 1), A, brow + G_HALF, nt - 1);
;     BAR; WAIT_L(0); MMA(0, 0, At, B0); BAR;
;     LDB(B1, 0, 1); BAR; WAIT_L(0); MMA(0, 1, At, B1); BAR;
	ds_read_b128 v[172:175], v133 offset:49152
	ds_read_b128 v[176:179], v133 offset:50176
	ds_read_b128 v[180:183], v132 offset:49152
	ds_read_b128 v[184:187], v132 offset:50176
	ds_read_b128 v[188:191], v131 offset:49152
	ds_read_b128 v[192:195], v131 offset:50176
	ds_read_b128 v[196:199], v130 offset:49152
	buffer_load_dwordx4 v137, s[88:91], s15 offen lds
	s_add_i32 m0, s100, 0xa000
	ds_read_b128 v[200:203], v130 offset:50176
	buffer_load_dwordx4 v136, s[88:91], s15 offen lds
	s_barrier
	s_waitcnt lgkmcnt(0)
	v_mfma_f32_16x16x32_bf16 v[62:65], v[172:175], v[156:159], v[62:65]
	v_mfma_f32_16x16x32_bf16 v[58:61], v[172:175], v[164:167], v[58:61]
	v_mfma_f32_16x16x32_bf16 v[54:57], v[180:183], v[156:159], v[54:57]
	v_mfma_f32_16x16x32_bf16 v[50:53], v[180:183], v[164:167], v[50:53]
	v_mfma_f32_16x16x32_bf16 v[46:49], v[188:191], v[156:159], v[46:49]
	v_mfma_f32_16x16x32_bf16 v[42:45], v[188:191], v[164:167], v[42:45]
	v_mfma_f32_16x16x32_bf16 v[38:41], v[196:199], v[156:159], v[38:41]
	v_mfma_f32_16x16x32_bf16 v[34:37], v[196:199], v[164:167], v[34:37]
	v_mfma_f32_16x16x32_bf16 v[62:65], v[176:179], v[160:163], v[62:65]
	v_mfma_f32_16x16x32_bf16 v[58:61], v[176:179], v[168:171], v[58:61]
	v_mfma_f32_16x16x32_bf16 v[54:57], v[184:187], v[160:163], v[54:57]
	v_mfma_f32_16x16x32_bf16 v[50:53], v[184:187], v[168:171], v[50:53]
	v_mfma_f32_16x16x32_bf16 v[46:49], v[192:195], v[160:163], v[46:49]
	v_mfma_f32_16x16x32_bf16 v[42:45], v[192:195], v[168:171], v[42:45]
	v_mfma_f32_16x16x32_bf16 v[38:41], v[200:203], v[160:163], v[38:41]
	v_mfma_f32_16x16x32_bf16 v[34:37], v[200:203], v[168:171], v[34:37]
	s_barrier
	s_add_i32 m0, s100, 0x1c000
	buffer_load_dwordx4 v137, s[4:7], s1 offen lds
	s_add_i32 m0, s100, 0x1e000
	s_nop 0
	buffer_load_dwordx4 v136, s[4:7], s1 offen lds
	s_waitcnt vmcnt(6)
	s_barrier
	v_mfma_f32_16x16x32_bf16 v[30:33], v[172:175], v[204:207], v[30:33]
	v_mfma_f32_16x16x32_bf16 v[26:29], v[172:175], v[212:215], v[26:29]
	v_mfma_f32_16x16x32_bf16 v[22:25], v[180:183], v[204:207], v[22:25]
	v_mfma_f32_16x16x32_bf16 v[18:21], v[180:183], v[212:215], v[18:21]
	v_mfma_f32_16x16x32_bf16 v[14:17], v[188:191], v[204:207], v[14:17]
	v_mfma_f32_16x16x32_bf16 v[10:13], v[188:191], v[212:215], v[10:13]
	v_mfma_f32_16x16x32_bf16 v[6:9], v[196:199], v[204:207], v[6:9]
	v_mfma_f32_16x16x32_bf16 v[2:5], v[196:199], v[212:215], v[2:5]
	v_mfma_f32_16x16x32_bf16 v[30:33], v[176:179], v[208:211], v[30:33]
	v_mfma_f32_16x16x32_bf16 v[26:29], v[176:179], v[216:219], v[26:29]
	v_mfma_f32_16x16x32_bf16 v[22:25], v[184:187], v[208:211], v[22:25]
	v_mfma_f32_16x16x32_bf16 v[18:21], v[184:187], v[216:219], v[18:21]
	v_mfma_f32_16x16x32_bf16 v[14:17], v[192:195], v[208:211], v[14:17]
	v_mfma_f32_16x16x32_bf16 v[10:13], v[192:195], v[216:219], v[10:13]
	v_mfma_f32_16x16x32_bf16 v[6:9], v[200:203], v[208:211], v[6:9]
	v_mfma_f32_16x16x32_bf16 v[2:5], v[200:203], v[216:219], v[2:5]
	s_add_i32 s0, s0, 2
	s_addk_i32 s1, 0x100
	s_cmp_lt_u32 s0, 28
	s_barrier
	s_cbranch_scc1 .LBB0_58
	v_readfirstlane_b32 s0, v145
	s_mov_b32 m0, s0
	s_mov_b32 s1, 0x80f80
	v_readfirstlane_b32 s0, v144
	ds_read_b128 v[138:141], v155
	ds_read_b128 v[148:151], v155 offset:1024
	ds_read_b128 v[156:159], v155 offset:2048
	ds_read_b128 v[152:155], v155 offset:3072
	ds_read_b128 v[160:163], v133
	ds_read_b128 v[164:167], v133 offset:1024
	ds_read_b128 v[168:171], v132
	ds_read_b128 v[172:175], v132 offset:1024
	ds_read_b128 v[176:179], v131
	ds_read_b128 v[180:183], v131 offset:1024
	ds_read_b128 v[184:187], v130
	ds_read_b128 v[188:191], v130 offset:1024
	buffer_load_dwordx4 v137, s[88:91], s1 offen lds
	s_mov_b32 m0, s0
	s_nop 0
	buffer_load_dwordx4 v136, s[88:91], s1 offen lds
	s_barrier
	s_waitcnt lgkmcnt(0)
	v_mfma_f32_16x16x32_bf16 v[126:129], v[160:163], v[138:141], v[126:129]
	v_mfma_f32_16x16x32_bf16 v[122:125], v[160:163], v[156:159], v[122:125]
	v_mfma_f32_16x16x32_bf16 v[118:121], v[168:171], v[138:141], v[118:121]
	v_mfma_f32_16x16x32_bf16 v[114:117], v[168:171], v[156:159], v[114:117]
	v_mfma_f32_16x16x32_bf16 v[102:105], v[184:187], v[138:141], v[102:105]
	v_mfma_f32_16x16x32_bf16 v[98:101], v[184:187], v[156:159], v[98:101]
	v_mfma_f32_16x16x32_bf16 v[126:129], v[164:167], v[148:151], v[126:129]
	v_mfma_f32_16x16x32_bf16 v[122:125], v[164:167], v[152:155], v[122:125]
	v_mfma_f32_16x16x32_bf16 v[118:121], v[172:175], v[148:151], v[118:121]
	v_mfma_f32_16x16x32_bf16 v[114:117], v[172:175], v[152:155], v[114:117]
	v_mfma_f32_16x16x32_bf16 v[110:113], v[176:179], v[138:141], v[110:113]
	v_mfma_f32_16x16x32_bf16 v[106:109], v[176:179], v[156:159], v[106:109]
	v_mfma_f32_16x16x32_bf16 v[102:105], v[188:191], v[148:151], v[102:105]
	v_mfma_f32_16x16x32_bf16 v[98:101], v[188:191], v[152:155], v[98:101]
	v_mfma_f32_16x16x32_bf16 v[142:145], v[180:183], v[148:151], v[110:113]
	v_mfma_f32_16x16x32_bf16 v[192:195], v[180:183], v[152:155], v[106:109]
	s_barrier
	s_nop 0
	ds_read_b128 v[106:109], v147
	ds_read_b128 v[110:113], v147 offset:1024
	ds_read_b128 v[196:199], v147 offset:2048
	ds_read_b128 v[200:203], v147 offset:3072
	s_barrier
; #define WAIT_V(n) asm volatile("s_waitcnt vmcnt(" #n ")" ::: "memory")
; #define WAIT_L(n) asm volatile("s_waitcnt lgkmcnt(" #n ")" ::: "memory")
; #define BAR __builtin_amdgcn_s_barrier()
; __device__ __forceinline__ void mainloop_8phase(const u16* __restrict__ A, const u16* __restrict__ Bt, int K,
;                                                 f32x4 (&acc)[2][2][4][2], int wid_s, int ld) {
;     ...
;     LDB(B1, 0, 1); BAR; WAIT_L(0); MMA(0, 1, At, B1); BAR;
;     LDA(At, 0, 1); WAIT_V(4); BAR; WAIT_L(0); MMA(1, 0, At, B0); MMA(1, 1, At, B1); BAR; }
;   { LDB(B0, 1, 0); LDA(At, 1, 0); WAIT_V(2); BAR; WAIT_L(0); MMA(0, 0, At, B0); BAR;
	s_waitcnt lgkmcnt(0)
	v_mfma_f32_16x16x32_bf16 v[86:89], v[168:171], v[106:109], v[86:89]
	v_mfma_f32_16x16x32_bf16 v[82:85], v[168:171], v[196:199], v[82:85]
	v_mfma_f32_16x16x32_bf16 v[70:73], v[184:187], v[106:109], v[70:73]
	v_mfma_f32_16x16x32_bf16 v[66:69], v[184:187], v[196:199], v[66:69]
	v_mfma_f32_16x16x32_bf16 v[94:97], v[160:163], v[106:109], v[94:97]
	v_mfma_f32_16x16x32_bf16 v[90:93], v[160:163], v[196:199], v[90:93]
	v_mfma_f32_16x16x32_bf16 v[86:89], v[172:175], v[110:113], v[86:89]
	v_mfma_f32_16x16x32_bf16 v[82:85], v[172:175], v[200:203], v[82:85]
	v_mfma_f32_16x16x32_bf16 v[78:81], v[176:179], v[106:109], v[78:81]
	v_mfma_f32_16x16x32_bf16 v[74:77], v[176:179], v[196:199], v[74:77]
	v_mfma_f32_16x16x32_bf16 v[70:73], v[188:191], v[110:113], v[70:73]
	v_mfma_f32_16x16x32_bf16 v[66:69], v[188:191], v[200:203], v[66:69]
	v_mfma_f32_16x16x32_bf16 v[204:207], v[164:167], v[110:113], v[94:97]
	v_mfma_f32_16x16x32_bf16 v[160:163], v[164:167], v[200:203], v[90:93]
	v_mfma_f32_16x16x32_bf16 v[164:167], v[180:183], v[110:113], v[78:81]
	v_mfma_f32_16x16x32_bf16 v[168:171], v[180:183], v[200:203], v[74:77]
	s_barrier
	s_nop 0
	ds_read_b128 v[74:77], v133 offset:16384
	ds_read_b128 v[78:81], v133 offset:17408
	ds_read_b128 v[90:93], v132 offset:16384
	ds_read_b128 v[94:97], v132 offset:17408
	ds_read_b128 v[172:175], v131 offset:16384
	ds_read_b128 v[176:179], v131 offset:17408
	ds_read_b128 v[180:183], v130 offset:16384
	ds_read_b128 v[184:187], v130 offset:17408
	s_waitcnt vmcnt(4)
	s_barrier
	s_waitcnt lgkmcnt(0)
	v_mfma_f32_16x16x32_bf16 v[62:65], v[74:77], v[138:141], v[62:65]
	v_mfma_f32_16x16x32_bf16 v[58:61], v[74:77], v[156:159], v[58:61]
	v_mfma_f32_16x16x32_bf16 v[54:57], v[90:93], v[138:141], v[54:57]
	v_mfma_f32_16x16x32_bf16 v[50:53], v[90:93], v[156:159], v[50:53]
	v_mfma_f32_16x16x32_bf16 v[38:41], v[180:183], v[138:141], v[38:41]
	v_mfma_f32_16x16x32_bf16 v[34:37], v[180:183], v[156:159], v[34:37]
	v_mfma_f32_16x16x32_bf16 v[62:65], v[78:81], v[148:151], v[62:65]
	v_mfma_f32_16x16x32_bf16 v[58:61], v[78:81], v[152:155], v[58:61]
	v_mfma_f32_16x16x32_bf16 v[54:57], v[94:97], v[148:151], v[54:57]
	v_mfma_f32_16x16x32_bf16 v[50:53], v[94:97], v[152:155], v[50:53]
	v_mfma_f32_16x16x32_bf16 v[46:49], v[172:175], v[138:141], v[46:49]
	v_mfma_f32_16x16x32_bf16 v[42:45], v[172:175], v[156:159], v[42:45]
	v_mfma_f32_16x16x32_bf16 v[38:41], v[184:187], v[148:151], v[38:41]
	v_mfma_f32_16x16x32_bf16 v[34:37], v[184:187], v[152:155], v[34:37]
	v_mfma_f32_16x16x32_bf16 v[188:191], v[176:179], v[148:151], v[46:49]
	v_mfma_f32_16x16x32_bf16 v[208:211], v[176:179], v[152:155], v[42:45]
	v_mfma_f32_16x16x32_bf16 v[22:25], v[90:93], v[106:109], v[22:25]
	v_mfma_f32_16x16x32_bf16 v[18:21], v[90:93], v[196:199], v[18:21]
	v_mfma_f32_16x16x32_bf16 v[6:9], v[180:183], v[106:109], v[6:9]
	v_mfma_f32_16x16x32_bf16 v[2:5], v[180:183], v[196:199], v[2:5]
	v_mfma_f32_16x16x32_bf16 v[30:33], v[74:77], v[106:109], v[30:33]
	v_mfma_f32_16x16x32_bf16 v[26:29], v[74:77], v[196:199], v[26:29]
	v_mfma_f32_16x16x32_bf16 v[22:25], v[94:97], v[110:113], v[22:25]
	v_mfma_f32_16x16x32_bf16 v[18:21], v[94:97], v[200:203], v[18:21]
	v_mfma_f32_16x16x32_bf16 v[14:17], v[172:175], v[106:109], v[14:17]
	v_mfma_f32_16x16x32_bf16 v[10:13], v[172:175], v[196:199], v[10:13]
	v_mfma_f32_16x16x32_bf16 v[6:9], v[184:187], v[110:113], v[6:9]
	v_mfma_f32_16x16x32_bf16 v[2:5], v[184:187], v[200:203], v[2:5]
	v_mfma_f32_16x16x32_bf16 v[136:139], v[78:81], v[110:113], v[30:33]
	v_mfma_f32_16x16x32_bf16 v[146:149], v[78:81], v[200:203], v[26:29]
	v_mfma_f32_16x16x32_bf16 v[150:153], v[176:179], v[110:113], v[14:17]
	v_mfma_f32_16x16x32_bf16 v[154:157], v[176:179], v[200:203], v[10:13]
	s_barrier
	s_nop 0
	ds_read_b128 v[10:13], v135
	ds_read_b128 v[14:17], v135 offset:1024
	ds_read_b128 v[172:175], v135 offset:2048
	ds_read_b128 v[176:179], v135 offset:3072
	ds_read_b128 v[26:29], v133 offset:32768
	ds_read_b128 v[30:33], v133 offset:33792
	ds_read_b128 v[42:45], v132 offset:32768
	ds_read_b128 v[46:49], v132 offset:33792
	ds_read_b128 v[180:183], v131 offset:32768
	ds_read_b128 v[184:187], v131 offset:33792
	ds_read_b128 v[196:199], v130 offset:32768
	ds_read_b128 v[200:203], v130 offset:33792
	s_waitcnt vmcnt(2)
	s_barrier
; #define WAIT_V(n) asm volatile("s_waitcnt vmcnt(" #n ")" ::: "memory")
; #define WAIT_L(n) asm volatile("s_waitcnt lgkmcnt(" #n ")" ::: "memory")
; #define BAR __builtin_amdgcn_s_barrier()
; __device__ __forceinline__ void mainloop_8phase(const u16* __restrict__ A, const u16* __restrict__ Bt, int K,
;                                                 f32x4 (&acc)[2][2][4][2], int wid_s, int ld) {
;     ...
;   { LDB(B0, 1, 0); LDA(At, 1, 0); WAIT_V(2); BAR; WAIT_L(0); MMA(0, 0, At, B0); BAR;
;     LDB(B1, 1, 1); WAIT_V(0); BAR; WAIT_L(0); MMA(0, 1, At, B1); BAR;
;     LDA(At, 1, 1); BAR; WAIT_L(0); MMA(1, 0, At, B0); MMA(1, 1, At, B1); BAR; }
;   if (wr == 0) BAR;
	s_waitcnt lgkmcnt(0)
	v_mfma_f32_16x16x32_bf16 v[74:77], v[26:29], v[10:13], v[126:129]
	v_mfma_f32_16x16x32_bf16 v[126:129], v[30:33], v[14:17], v[74:77]
	v_mfma_f32_16x16x32_bf16 v[74:77], v[26:29], v[172:175], v[122:125]
	v_mfma_f32_16x16x32_bf16 v[122:125], v[30:33], v[176:179], v[74:77]
	v_mfma_f32_16x16x32_bf16 v[74:77], v[42:45], v[10:13], v[118:121]
	v_mfma_f32_16x16x32_bf16 v[110:113], v[46:49], v[14:17], v[74:77]
	v_mfma_f32_16x16x32_bf16 v[74:77], v[42:45], v[172:175], v[114:117]
	v_mfma_f32_16x16x32_bf16 v[106:109], v[46:49], v[176:179], v[74:77]
	v_mfma_f32_16x16x32_bf16 v[74:77], v[180:183], v[10:13], v[142:145]
	v_mfma_f32_16x16x32_bf16 v[94:97], v[184:187], v[14:17], v[74:77]
	v_mfma_f32_16x16x32_bf16 v[74:77], v[180:183], v[172:175], v[192:195]
	v_mfma_f32_16x16x32_bf16 v[90:93], v[184:187], v[176:179], v[74:77]
	v_mfma_f32_16x16x32_bf16 v[74:77], v[196:199], v[10:13], v[102:105]
	v_mfma_f32_16x16x32_bf16 v[78:81], v[200:203], v[14:17], v[74:77]
	v_mfma_f32_16x16x32_bf16 v[74:77], v[196:199], v[172:175], v[98:101]
	v_mfma_f32_16x16x32_bf16 v[74:77], v[200:203], v[176:179], v[74:77]
	s_barrier
	ds_read_b128 v[140:143], v134
	ds_read_b128 v[192:195], v134 offset:1024
	ds_read_b128 v[212:215], v134 offset:2048
	ds_read_b128 v[216:219], v134 offset:3072
	s_waitcnt vmcnt(0)
	s_barrier
	s_waitcnt lgkmcnt(0)
	v_mfma_f32_16x16x32_bf16 v[98:101], v[26:29], v[140:143], v[204:207]
	v_mfma_f32_16x16x32_bf16 v[26:29], v[26:29], v[212:215], v[160:163]
	v_mfma_f32_16x16x32_bf16 v[114:117], v[30:33], v[216:219], v[26:29]
	v_mfma_f32_16x16x32_bf16 v[26:29], v[42:45], v[140:143], v[86:89]
	v_mfma_f32_16x16x32_bf16 v[102:105], v[46:49], v[192:195], v[26:29]
	v_mfma_f32_16x16x32_bf16 v[26:29], v[42:45], v[212:215], v[82:85]
	v_mfma_f32_16x16x32_bf16 v[118:121], v[30:33], v[192:195], v[98:101]
	v_mfma_f32_16x16x32_bf16 v[98:101], v[46:49], v[216:219], v[26:29]
	v_mfma_f32_16x16x32_bf16 v[26:29], v[180:183], v[140:143], v[164:167]
	v_mfma_f32_16x16x32_bf16 v[86:89], v[184:187], v[192:195], v[26:29]
	v_mfma_f32_16x16x32_bf16 v[26:29], v[180:183], v[212:215], v[168:171]
	v_mfma_f32_16x16x32_bf16 v[82:85], v[184:187], v[216:219], v[26:29]
	v_mfma_f32_16x16x32_bf16 v[26:29], v[196:199], v[140:143], v[70:73]
	v_mfma_f32_16x16x32_bf16 v[70:73], v[200:203], v[192:195], v[26:29]
	v_mfma_f32_16x16x32_bf16 v[26:29], v[196:199], v[212:215], v[66:69]
	v_mfma_f32_16x16x32_bf16 v[66:69], v[200:203], v[216:219], v[26:29]
	s_barrier
	ds_read_b128 v[158:161], v133 offset:49152
	ds_read_b128 v[162:165], v133 offset:50176
	ds_read_b128 v[166:169], v132 offset:49152
	ds_read_b128 v[132:135], v132 offset:50176
	ds_read_b128 v[180:183], v131 offset:49152
	ds_read_b128 v[184:187], v131 offset:50176
	ds_read_b128 v[196:199], v130 offset:49152
	ds_read_b128 v[200:203], v130 offset:50176
	s_barrier
	s_waitcnt lgkmcnt(0)
	v_mfma_f32_16x16x32_bf16 v[26:29], v[158:161], v[10:13], v[62:65]
	v_mfma_f32_16x16x32_bf16 v[62:65], v[162:165], v[14:17], v[26:29]
	v_mfma_f32_16x16x32_bf16 v[26:29], v[158:161], v[172:175], v[58:61]
	v_mfma_f32_16x16x32_bf16 v[58:61], v[162:165], v[176:179], v[26:29]
	v_mfma_f32_16x16x32_bf16 v[26:29], v[166:169], v[10:13], v[54:57]
	v_mfma_f32_16x16x32_bf16 v[46:49], v[132:135], v[14:17], v[26:29]
	v_mfma_f32_16x16x32_bf16 v[26:29], v[166:169], v[172:175], v[50:53]
	v_mfma_f32_16x16x32_bf16 v[42:45], v[132:135], v[176:179], v[26:29]
	v_mfma_f32_16x16x32_bf16 v[26:29], v[180:183], v[10:13], v[188:191]
	v_mfma_f32_16x16x32_bf16 v[10:13], v[196:199], v[10:13], v[38:41]
	v_mfma_f32_16x16x32_bf16 v[30:33], v[184:187], v[14:17], v[26:29]
	v_mfma_f32_16x16x32_bf16 v[26:29], v[180:183], v[172:175], v[208:211]
	v_mfma_f32_16x16x32_bf16 v[14:17], v[200:203], v[14:17], v[10:13]
	v_mfma_f32_16x16x32_bf16 v[10:13], v[196:199], v[172:175], v[34:37]
	v_mfma_f32_16x16x32_bf16 v[26:29], v[184:187], v[176:179], v[26:29]
	v_mfma_f32_16x16x32_bf16 v[10:13], v[200:203], v[176:179], v[10:13]
	v_mfma_f32_16x16x32_bf16 v[34:37], v[158:161], v[140:143], v[136:139]
	v_mfma_f32_16x16x32_bf16 v[54:57], v[162:165], v[192:195], v[34:37]
	v_mfma_f32_16x16x32_bf16 v[34:37], v[158:161], v[212:215], v[146:149]
	v_mfma_f32_16x16x32_bf16 v[18:21], v[166:169], v[212:215], v[18:21]
	v_mfma_f32_16x16x32_bf16 v[50:53], v[162:165], v[216:219], v[34:37]
	v_mfma_f32_16x16x32_bf16 v[22:25], v[166:169], v[140:143], v[22:25]
	v_mfma_f32_16x16x32_bf16 v[34:37], v[132:135], v[216:219], v[18:21]
	v_mfma_f32_16x16x32_bf16 v[18:21], v[180:183], v[140:143], v[150:153]
	v_mfma_f32_16x16x32_bf16 v[38:41], v[132:135], v[192:195], v[22:25]
	v_mfma_f32_16x16x32_bf16 v[22:25], v[184:187], v[192:195], v[18:21]
	v_mfma_f32_16x16x32_bf16 v[18:21], v[180:183], v[212:215], v[154:157]
	v_mfma_f32_16x16x32_bf16 v[6:9], v[196:199], v[140:143], v[6:9]
	v_mfma_f32_16x16x32_bf16 v[2:5], v[196:199], v[212:215], v[2:5]
	v_mfma_f32_16x16x32_bf16 v[18:21], v[184:187], v[216:219], v[18:21]
	v_mfma_f32_16x16x32_bf16 v[6:9], v[200:203], v[192:195], v[6:9]
	v_mfma_f32_16x16x32_bf16 v[2:5], v[200:203], v[216:219], v[2:5]
	s_movk_i32 s0, 0x100
	v_cmp_gt_u32_e32 vcc, s0, v0
	s_barrier
	s_and_saveexec_b64 s[0:1], vcc
	s_cbranch_execz .LBB0_61
	s_barrier

; #define WAIT_V(n) asm volatile("s_waitcnt vmcnt(" #n ")" ::: "memory")
; #define BAR __builtin_amdgcn_s_barrier()
; __device__ __forceinline__ void mainloop_8phase(const u16* __restrict__ A, const u16* __restrict__ Bt, int K,
;                                                 f32x4 (&acc)[2][2][4][2], int wid_s, int ld) {
;     ...
;   int tid = get_tid(wid_s), wid = tid >> 6, lane = tid & 63, wr = wid >> 2, wc = wid & 3, fr = lane & 15, fq = lane >> 4;
;   unsigned goff0, goff1;
;   {
;     int r0, c0, r1, c1;
;     stage_rc(tid * 16, r0, c0);
;     stage_rc(tid * 16 + 8192, r1, c1);
;     goff0 = (unsigned)(r0 * ld + c0) * 2u;
;     goff1 = (unsigned)(r1 * ld + c1) * 2u;
;   }
;   __amdgpu_buffer_rsrc_t rs_A, rs_Bt;
;   {
;     unsigned long ua = (unsigned long)A, ub = (unsigned long)Bt;
;     unsigned alo = __builtin_amdgcn_readfirstlane((unsigned)ua), ahi = __builtin_amdgcn_readfirstlane((unsigned)(ua >> 32));
;     unsigned blo = __builtin_amdgcn_readfirstlane((unsigned)ub), bhi = __builtin_amdgcn_readfirstlane((unsigned)(ub >> 32));
;     rs_A = __builtin_amdgcn_make_buffer_rsrc((void*)(((unsigned long)ahi << 32) | alo), (short)0, 0x7ffffff0, 0x00020000);
;     rs_Bt = __builtin_amdgcn_make_buffer_rsrc((void*)(((unsigned long)bhi << 32) | blo), (short)0, 0x7ffffff0, 0x00020000);
;   }
;   bf16x8 At[4][2], B0[2][2], B1[2][2];
;   const int brow = 0, bcol = 0;
;   int nt = K / G_BK;
;   if (wr == 1) BAR;
;   WAIT_V(0); BAR;
;   STAGE(SB(1, 0), Bt, bcol, 1); STAGE(SA(1, 0), A, brow, 1); STAGE(SB(1, 1), Bt, bcol + G_HALF, 1);
;   WAIT_V(6); BAR;
.LBB0_161:
	s_or_b64 exec, exec, s[2:3]
	v_bfe_i32 v8, v0, 27, 1
	v_lshlrev_b32_e32 v6, 4, v0
	v_lshrrev_b32_e32 v8, 22, v8
	v_add_u32_e32 v8, v6, v8
	v_and_b32_e32 v8, 0xfffffc00, v8
	v_sub_u32_e32 v8, v6, v8
	v_lshrrev_b32_e32 v9, 4, v8
	v_ashrrev_i32_e32 v7, 31, v0
	v_bitop3_b32 v8, v9, v8, 32 bitop3:0x6c
	v_lshrrev_b32_e32 v7, 26, v7
	v_ashrrev_i32_e32 v10, 31, v8
	v_add_u32_e32 v7, v0, v7
	v_lshrrev_b32_e32 v10, 26, v10
	v_ashrrev_i32_e32 v7, 6, v7
	v_add_u32_e32 v10, v8, v10
	v_lshlrev_b32_e32 v9, 3, v7
	v_lshrrev_b32_e32 v11, 6, v10
	v_and_b32_e32 v10, 0xc0, v10
	v_and_b32_e32 v9, 0xffff0, v9
	v_sub_u32_e32 v8, v8, v10
	v_add_u32_e32 v10, 0x2000, v6
	v_add_u32_e32 v9, v11, v9
	v_ashrrev_i32_e32 v11, 31, v10
	v_lshrrev_b32_e32 v11, 22, v11
	v_add_u32_e32 v11, v10, v11
	v_ashrrev_i32_e32 v11, 10, v11
	v_mul_i32_i24_e32 v12, 0x400, v11
	v_sub_u32_e32 v10, v10, v12
	v_lshrrev_b32_e32 v12, 4, v10
	v_bitop3_b32 v10, v12, v10, 32 bitop3:0x6c
	v_ashrrev_i32_e32 v13, 31, v10
	v_lshrrev_b32_e32 v13, 26, v13
	v_add_u32_e32 v13, v10, v13
	v_lshlrev_b32_e32 v7, 5, v7
	v_lshlrev_b32_e32 v12, 3, v11
	v_lshrrev_b32_e32 v14, 6, v13
	v_and_b32_e32 v13, 0xc0, v13
	v_readlane_b32 s6, v254, 43
	v_and_b32_e32 v7, 32, v7
	v_ashrrev_i16_sdwa v8, v244, sext(v8) dst_sel:DWORD dst_unused:UNUSED_PAD src0_sel:DWORD src1_sel:BYTE_0
	v_and_b32_e32 v12, 0xffff0, v12
	v_lshlrev_b32_e32 v11, 5, v11
	v_sub_u32_e32 v10, v10, v13
	s_waitcnt vmcnt(7)
	v_add_u32_e32 v138, s6, v6
	v_bfe_i32 v8, v8, 0, 16
	v_add_u32_e32 v12, v14, v12
	v_and_b32_e32 v11, 32, v11
	v_ashrrev_i16_sdwa v10, v244, sext(v10) dst_sel:DWORD dst_unused:UNUSED_PAD src0_sel:DWORD src1_sel:BYTE_0
	v_lshl_or_b32 v7, v9, 11, v7
	s_and_b32 s5, s13, 0xffff
	v_readfirstlane_b32 s2, v138
	v_add_u32_e32 v139, 0x2000, v138
	v_add_u32_e32 v140, 16, v6
	v_bfe_i32 v10, v10, 0, 16
	v_add_lshl_u32 v137, v7, v8, 1
	v_lshl_or_b32 v7, v12, 11, v11
	s_mov_b32 s24, s12
	s_mov_b32 s25, s5
	s_mov_b32 s26, s90
	s_mov_b32 s27, s91
	s_mov_b32 m0, s2
	s_movk_i32 s3, 0x80
	v_readfirstlane_b32 s2, v139
	v_add_u32_e32 v141, 0x8000, v140
	v_add_lshl_u32 v136, v7, v10, 1
	s_and_b32 s89, s1, 0xffff
	s_waitcnt vmcnt(0)
	s_barrier
	buffer_load_dwordx4 v137, s[24:27], s3 offen lds
	s_mov_b32 m0, s2
	v_readfirstlane_b32 s2, v141
	v_add_u32_e32 v142, 0xa000, v140
	v_readlane_b32 s7, v254, 44
	s_mov_b32 s16, s0
	s_mov_b32 s17, s89
	s_mov_b32 s18, s90
	s_mov_b32 s19, s91
	buffer_load_dwordx4 v136, s[24:27], s3 offen lds
	s_mov_b32 m0, s2
	v_readfirstlane_b32 s2, v142
	v_add_u32_e32 v143, s7, v6
	buffer_load_dwordx4 v137, s[16:19], s3 offen lds
	s_mov_b32 m0, s2
	v_readfirstlane_b32 s2, v143
	v_add_u32_e32 v144, 0x2000, v143
	buffer_load_dwordx4 v136, s[16:19], s3 offen lds
	s_mov_b32 m0, s2
	s_mov_b32 s3, 0x80080
	v_readfirstlane_b32 s2, v144
	buffer_load_dwordx4 v137, s[24:27], s3 offen lds
	s_mov_b32 m0, s2
	v_and_b32_e32 v4, 15, v2
	buffer_load_dwordx4 v136, s[24:27], s3 offen lds
	v_lshlrev_b32_e32 v7, 2, v2
	v_and_b32_e32 v5, 48, v2
	v_lshlrev_b32_e32 v4, 6, v4
	v_and_b32_e32 v7, 32, v7
	v_bitop3_b32 v4, v4, v7, v5 bitop3:0x36
	v_readlane_b32 s2, v254, 41
	v_lshlrev_b32_e32 v2, 6, v2
	s_waitcnt vmcnt(6)
	v_readlane_b32 s3, v254, 42
	v_add_u32_e32 v8, s2, v4
	v_add_u32_e32 v146, s2, v6
	s_movk_i32 s2, 0x3c0
	v_lshlrev_b32_e32 v11, 6, v0
	v_lshlrev_b32_e32 v3, 13, v3
	v_and_or_b32 v2, v2, s2, v5
	v_add_u32_e32 v9, s3, v4
	v_add_u32_e32 v147, s3, v6
	v_add_u32_e32 v6, s6, v4
	v_add_u32_e32 v10, s7, v4
	v_and_b32_e32 v11, 0x3000, v11
	v_add_u32_e32 v4, 16, v4
	v_xad_u32 v5, v2, v7, 16
	v_or_b32_e32 v7, 0x800, v3
	v_or_b32_e32 v12, 0x1000, v3
	v_or_b32_e32 v13, 0x1800, v3
	v_mov_b32_e32 v2, 0
	s_mov_b32 s88, s0
	s_mov_b32 s4, s12
	s_mov_b32 s2, -2
	s_mov_b32 s3, 0x80180
	v_add_u32_e32 v148, v8, v11
	s_waitcnt lgkmcnt(0)
	v_add_u32_e32 v133, v4, v3
	v_add_u32_e32 v132, v5, v7
	v_add_u32_e32 v131, v5, v12
	v_add_u32_e32 v130, v5, v13
	v_add_u32_e32 v145, v9, v11
	v_add_u32_e32 v135, v6, v11
	v_add_u32_e32 v134, v10, v11
	v_mov_b32_e32 v3, v2
	v_mov_b32_e32 v4, v2
	v_mov_b32_e32 v5, v2
	v_mov_b32_e32 v6, v2
	v_mov_b32_e32 v7, v2
	v_mov_b32_e32 v8, v2
	v_mov_b32_e32 v9, v2
	v_mov_b32_e32 v10, v2
	v_mov_b32_e32 v11, v2
	v_mov_b32_e32 v12, v2
	v_mov_b32_e32 v13, v2
	v_mov_b32_e32 v14, v2
	v_mov_b32_e32 v15, v2
	v_mov_b32_e32 v16, v2
	v_mov_b32_e32 v17, v2
	v_mov_b32_e32 v18, v2
	v_mov_b32_e32 v19, v2
	v_mov_b32_e32 v20, v2
	v_mov_b32_e32 v21, v2
	v_mov_b32_e32 v22, v2
	v_mov_b32_e32 v23, v2
	v_mov_b32_e32 v24, v2
	v_mov_b32_e32 v25, v2
	v_mov_b32_e32 v26, v2
	v_mov_b32_e32 v27, v2
	v_mov_b32_e32 v28, v2
	v_mov_b32_e32 v29, v2
	v_mov_b32_e32 v30, v2
	v_mov_b32_e32 v31, v2
	v_mov_b32_e32 v32, v2
	v_mov_b32_e32 v33, v2
	v_mov_b32_e32 v34, v2
	v_mov_b32_e32 v35, v2
	v_mov_b32_e32 v36, v2
	v_mov_b32_e32 v37, v2
	v_mov_b32_e32 v38, v2
	v_mov_b32_e32 v39, v2
	v_mov_b32_e32 v40, v2
	v_mov_b32_e32 v41, v2
	v_mov_b32_e32 v42, v2
	v_mov_b32_e32 v43, v2
	v_mov_b32_e32 v44, v2
	v_mov_b32_e32 v45, v2
	v_mov_b32_e32 v46, v2
	v_mov_b32_e32 v47, v2
	v_mov_b32_e32 v48, v2
	v_mov_b32_e32 v49, v2
	v_mov_b32_e32 v50, v2
	v_mov_b32_e32 v51, v2
	v_mov_b32_e32 v52, v2
	v_mov_b32_e32 v53, v2
	v_mov_b32_e32 v54, v2
	v_mov_b32_e32 v55, v2
	v_mov_b32_e32 v56, v2
	v_mov_b32_e32 v57, v2
	v_mov_b32_e32 v58, v2
	v_mov_b32_e32 v59, v2
	v_mov_b32_e32 v60, v2
	v_mov_b32_e32 v61, v2
	v_mov_b32_e32 v62, v2
	v_mov_b32_e32 v63, v2
	v_mov_b32_e32 v64, v2
	v_mov_b32_e32 v65, v2
	v_mov_b32_e32 v66, v2
	v_mov_b32_e32 v67, v2
	s_waitcnt vmcnt(9)
	v_mov_b32_e32 v68, v2
	v_mov_b32_e32 v69, v2
	v_mov_b32_e32 v70, v2
	v_mov_b32_e32 v71, v2
	s_waitcnt vmcnt(8)
; #define WAIT_L(n) asm volatile("s_waitcnt lgkmcnt(" #n ")" ::: "memory")
; #define BAR __builtin_amdgcn_s_barrier()
; #define SCHED __builtin_amdgcn_sched_barrier(0)
; __device__ __forceinline__ void mainloop_8phase(const u16* __restrict__ A, const u16* __restrict__ Bt, int K,
;                                                 f32x4 (&acc)[2][2][4][2], int wid_s, int ld) {
;     ...
;   for (int t = 0; t < nt - 2; t += 2) {
;     LDB(B0, 0, 0); SCHED; LDA(At, 0, 0); STAGE(SA(1, 1), A, brow + G_HALF, t + 1);
;     WAIT_L(8); BAR; WAIT_L(0); MMA(0, 0, At, B0); BAR; SCHED;
;     LDB(B1, 0, 1); STAGE(SB(0, 0), Bt, bcol, t + 2);
;     BAR; WAIT_L(0); MMA(0, 1, At, B1); BAR;
;     LDA(At, 0, 1); STAGE(SA(0, 0), A, brow, t + 2);
;     BAR; WAIT_L(0); MMA(1, 0, At, B0); BAR; SCHED;
	v_mov_b32_e32 v72, v2
	v_mov_b32_e32 v73, v2
	v_mov_b32_e32 v74, v2
	v_mov_b32_e32 v75, v2
	s_waitcnt vmcnt(7)
	v_mov_b32_e32 v76, v2
	v_mov_b32_e32 v77, v2
	v_mov_b32_e32 v78, v2
	v_mov_b32_e32 v79, v2
	s_waitcnt vmcnt(6)
	v_mov_b32_e32 v80, v2
	v_mov_b32_e32 v81, v2
	v_mov_b32_e32 v82, v2
	v_mov_b32_e32 v83, v2
	v_mov_b32_e32 v84, v2
	v_mov_b32_e32 v85, v2
	v_mov_b32_e32 v86, v2
	v_mov_b32_e32 v87, v2
	v_mov_b32_e32 v88, v2
	v_mov_b32_e32 v89, v2
	v_mov_b32_e32 v90, v2
	v_mov_b32_e32 v91, v2
	v_mov_b32_e32 v92, v2
	v_mov_b32_e32 v93, v2
	v_mov_b32_e32 v94, v2
	v_mov_b32_e32 v95, v2
	v_mov_b32_e32 v96, v2
	v_mov_b32_e32 v97, v2
	v_mov_b32_e32 v98, v2
	v_mov_b32_e32 v99, v2
	v_mov_b32_e32 v100, v2
	v_mov_b32_e32 v101, v2
	v_mov_b32_e32 v102, v2
	v_mov_b32_e32 v103, v2
	v_mov_b32_e32 v104, v2
	v_mov_b32_e32 v105, v2
	v_mov_b32_e32 v106, v2
	v_mov_b32_e32 v107, v2
	v_mov_b32_e32 v108, v2
	v_mov_b32_e32 v109, v2
	v_mov_b32_e32 v110, v2
	v_mov_b32_e32 v111, v2
	v_mov_b32_e32 v112, v2
	v_mov_b32_e32 v113, v2
	v_mov_b32_e32 v114, v2
	v_mov_b32_e32 v115, v2
	v_mov_b32_e32 v116, v2
	v_mov_b32_e32 v117, v2
	v_mov_b32_e32 v118, v2
	v_mov_b32_e32 v119, v2
	v_mov_b32_e32 v120, v2
	v_mov_b32_e32 v121, v2
	v_mov_b32_e32 v122, v2
	v_mov_b32_e32 v123, v2
	v_mov_b32_e32 v124, v2
	v_mov_b32_e32 v125, v2
	v_mov_b32_e32 v126, v2
	v_mov_b32_e32 v127, v2
	v_mov_b32_e32 v128, v2
	v_mov_b32_e32 v129, v2
	v_add_u32_e32 v150, 0xc000, v140
	v_add_u32_e32 v149, 0xe000, v140
	v_add_u32_e32 v151, 0x2000, v146
	v_add_u32_e32 v152, 0x2000, v140
	v_add_u32_e32 v153, 0x2000, v147
	v_add_u32_e32 v154, 0x4000, v140
	v_add_u32_e32 v155, 0x6000, v140
	s_barrier
	s_mov_b32 s7, s91
.LBB0_162:
	ds_read_b128 v[156:159], v148
	ds_read_b128 v[160:163], v148 offset:1024
	ds_read_b128 v[164:167], v148 offset:2048
	ds_read_b128 v[168:171], v148 offset:3072
	s_add_i32 s6, s3, 0xffffff00
	s_add_i32 m0, s100, 0xc000
	ds_read_b128 v[172:175], v133
	ds_read_b128 v[176:179], v133 offset:1024
	ds_read_b128 v[180:183], v132
	ds_read_b128 v[184:187], v132 offset:1024
	ds_read_b128 v[188:191], v131
	ds_read_b128 v[192:195], v131 offset:1024
	ds_read_b128 v[196:199], v130
	buffer_load_dwordx4 v137, s[88:91], s6 offen lds
	s_add_i32 m0, s100, 0xe000
	ds_read_b128 v[200:203], v130 offset:1024
	buffer_load_dwordx4 v136, s[88:91], s6 offen lds
	s_waitcnt lgkmcnt(8)
	s_barrier
	s_waitcnt lgkmcnt(0)
	v_mfma_f32_16x16x32_bf16 v[126:129], v[172:175], v[156:159], v[126:129]
	v_mfma_f32_16x16x32_bf16 v[122:125], v[172:175], v[164:167], v[122:125]
	v_mfma_f32_16x16x32_bf16 v[118:121], v[180:183], v[156:159], v[118:121]
	v_mfma_f32_16x16x32_bf16 v[114:117], v[180:183], v[164:167], v[114:117]
	v_mfma_f32_16x16x32_bf16 v[110:113], v[188:191], v[156:159], v[110:113]
	v_mfma_f32_16x16x32_bf16 v[106:109], v[188:191], v[164:167], v[106:109]
	v_mfma_f32_16x16x32_bf16 v[102:105], v[196:199], v[156:159], v[102:105]
	v_mfma_f32_16x16x32_bf16 v[98:101], v[196:199], v[164:167], v[98:101]
	v_mfma_f32_16x16x32_bf16 v[126:129], v[176:179], v[160:163], v[126:129]
	v_mfma_f32_16x16x32_bf16 v[122:125], v[176:179], v[168:171], v[122:125]
	v_mfma_f32_16x16x32_bf16 v[118:121], v[184:187], v[160:163], v[118:121]
	v_mfma_f32_16x16x32_bf16 v[114:117], v[184:187], v[168:171], v[114:117]
	v_mfma_f32_16x16x32_bf16 v[110:113], v[192:195], v[160:163], v[110:113]
	v_mfma_f32_16x16x32_bf16 v[106:109], v[192:195], v[168:171], v[106:109]
	v_mfma_f32_16x16x32_bf16 v[102:105], v[200:203], v[160:163], v[102:105]
	v_mfma_f32_16x16x32_bf16 v[98:101], v[200:203], v[168:171], v[98:101]
	s_barrier
	s_add_i32 s15, s3, 0xfff7ff80
	s_mov_b32 s6, s90
	s_add_i32 m0, s100, 0x10000
	ds_read_b128 v[204:207], v145
	ds_read_b128 v[208:211], v145 offset:1024
	ds_read_b128 v[212:215], v145 offset:2048
	buffer_load_dwordx4 v137, s[4:7], s15 offen lds
	s_add_i32 m0, s100, 0x12000
	ds_read_b128 v[216:219], v145 offset:3072
	buffer_load_dwordx4 v136, s[4:7], s15 offen lds
	s_barrier
	s_waitcnt lgkmcnt(0)
	v_mfma_f32_16x16x32_bf16 v[94:97], v[172:175], v[204:207], v[94:97]
	v_mfma_f32_16x16x32_bf16 v[90:93], v[172:175], v[212:215], v[90:93]
	v_mfma_f32_16x16x32_bf16 v[86:89], v[180:183], v[204:207], v[86:89]
	v_mfma_f32_16x16x32_bf16 v[82:85], v[180:183], v[212:215], v[82:85]
	v_mfma_f32_16x16x32_bf16 v[78:81], v[188:191], v[204:207], v[78:81]
	v_mfma_f32_16x16x32_bf16 v[74:77], v[188:191], v[212:215], v[74:77]
	v_mfma_f32_16x16x32_bf16 v[70:73], v[196:199], v[204:207], v[70:73]
	v_mfma_f32_16x16x32_bf16 v[66:69], v[196:199], v[212:215], v[66:69]
	v_mfma_f32_16x16x32_bf16 v[94:97], v[176:179], v[208:211], v[94:97]
	v_mfma_f32_16x16x32_bf16 v[90:93], v[176:179], v[216:219], v[90:93]
	v_mfma_f32_16x16x32_bf16 v[86:89], v[184:187], v[208:211], v[86:89]
	v_mfma_f32_16x16x32_bf16 v[82:85], v[184:187], v[216:219], v[82:85]
	v_mfma_f32_16x16x32_bf16 v[78:81], v[192:195], v[208:211], v[78:81]
	v_mfma_f32_16x16x32_bf16 v[74:77], v[192:195], v[216:219], v[74:77]
	v_mfma_f32_16x16x32_bf16 v[70:73], v[200:203], v[208:211], v[70:73]
	v_mfma_f32_16x16x32_bf16 v[66:69], v[200:203], v[216:219], v[66:69]
	s_mov_b32 m0, s100
	s_barrier
	ds_read_b128 v[172:175], v133 offset:16384
	ds_read_b128 v[176:179], v133 offset:17408
	ds_read_b128 v[180:183], v132 offset:16384
	ds_read_b128 v[184:187], v132 offset:17408
	ds_read_b128 v[188:191], v131 offset:16384
	ds_read_b128 v[192:195], v131 offset:17408
	ds_read_b128 v[196:199], v130 offset:16384
	buffer_load_dwordx4 v137, s[88:91], s15 offen lds
	s_add_i32 m0, s100, 0x2000
	ds_read_b128 v[200:203], v130 offset:17408
	buffer_load_dwordx4 v136, s[88:91], s15 offen lds
	s_barrier
; #define WAIT_V(n) asm volatile("s_waitcnt vmcnt(" #n ")" ::: "memory")
; #define WAIT_L(n) asm volatile("s_waitcnt lgkmcnt(" #n ")" ::: "memory")
; #define BAR __builtin_amdgcn_s_barrier()
; #define SCHED __builtin_amdgcn_sched_barrier(0)
; __device__ __forceinline__ void mainloop_8phase(const u16* __restrict__ A, const u16* __restrict__ Bt, int K,
;                                                 f32x4 (&acc)[2][2][4][2], int wid_s, int ld) {
;     ...
;     BAR; WAIT_L(0); MMA(1, 0, At, B0); BAR; SCHED;
;     STAGE(SB(0, 1), Bt, bcol + G_HALF, t + 2);
;     WAIT_V(6); BAR; MMA(1, 1, At, B1); BAR;
;     LDB(B0, 1, 0); SCHED; LDA(At, 1, 0); STAGE(SA(0, 1), A, brow + G_HALF, t + 2);
;     WAIT_L(8); BAR; WAIT_L(0); MMA(0, 0, At, B0); BAR; SCHED;
;     LDB(B1, 1, 1); STAGE(SB(1, 0), Bt, bcol, t + 3);
;     BAR; WAIT_L(0); MMA(0, 1, At, B1); BAR;
;     LDA(At, 1, 1); STAGE(SA(1, 0), A, brow, t + 3);
	s_waitcnt lgkmcnt(0)
	v_mfma_f32_16x16x32_bf16 v[62:65], v[172:175], v[156:159], v[62:65]
	v_mfma_f32_16x16x32_bf16 v[58:61], v[172:175], v[164:167], v[58:61]
	v_mfma_f32_16x16x32_bf16 v[54:57], v[180:183], v[156:159], v[54:57]
	v_mfma_f32_16x16x32_bf16 v[50:53], v[180:183], v[164:167], v[50:53]
	v_mfma_f32_16x16x32_bf16 v[46:49], v[188:191], v[156:159], v[46:49]
	v_mfma_f32_16x16x32_bf16 v[42:45], v[188:191], v[164:167], v[42:45]
	v_mfma_f32_16x16x32_bf16 v[38:41], v[196:199], v[156:159], v[38:41]
	v_mfma_f32_16x16x32_bf16 v[34:37], v[196:199], v[164:167], v[34:37]
	v_mfma_f32_16x16x32_bf16 v[62:65], v[176:179], v[160:163], v[62:65]
	v_mfma_f32_16x16x32_bf16 v[58:61], v[176:179], v[168:171], v[58:61]
	v_mfma_f32_16x16x32_bf16 v[54:57], v[184:187], v[160:163], v[54:57]
	v_mfma_f32_16x16x32_bf16 v[50:53], v[184:187], v[168:171], v[50:53]
	v_mfma_f32_16x16x32_bf16 v[46:49], v[192:195], v[160:163], v[46:49]
	v_mfma_f32_16x16x32_bf16 v[42:45], v[192:195], v[168:171], v[42:45]
	v_mfma_f32_16x16x32_bf16 v[38:41], v[200:203], v[160:163], v[38:41]
	v_mfma_f32_16x16x32_bf16 v[34:37], v[200:203], v[168:171], v[34:37]
	s_barrier
	s_add_i32 s15, s3, 0xffffff80
	s_add_i32 m0, s100, 0x14000
	buffer_load_dwordx4 v137, s[4:7], s15 offen lds
	s_add_i32 m0, s100, 0x16000
	s_nop 0
	buffer_load_dwordx4 v136, s[4:7], s15 offen lds
	s_waitcnt vmcnt(6)
	s_barrier
	v_mfma_f32_16x16x32_bf16 v[30:33], v[172:175], v[204:207], v[30:33]
	v_mfma_f32_16x16x32_bf16 v[26:29], v[172:175], v[212:215], v[26:29]
	v_mfma_f32_16x16x32_bf16 v[22:25], v[180:183], v[204:207], v[22:25]
	v_mfma_f32_16x16x32_bf16 v[18:21], v[180:183], v[212:215], v[18:21]
	v_mfma_f32_16x16x32_bf16 v[14:17], v[188:191], v[204:207], v[14:17]
	v_mfma_f32_16x16x32_bf16 v[10:13], v[188:191], v[212:215], v[10:13]
	v_mfma_f32_16x16x32_bf16 v[6:9], v[196:199], v[204:207], v[6:9]
	v_mfma_f32_16x16x32_bf16 v[2:5], v[196:199], v[212:215], v[2:5]
	v_mfma_f32_16x16x32_bf16 v[30:33], v[176:179], v[208:211], v[30:33]
	v_mfma_f32_16x16x32_bf16 v[26:29], v[176:179], v[216:219], v[26:29]
	v_mfma_f32_16x16x32_bf16 v[22:25], v[184:187], v[208:211], v[22:25]
	v_mfma_f32_16x16x32_bf16 v[18:21], v[184:187], v[216:219], v[18:21]
	v_mfma_f32_16x16x32_bf16 v[14:17], v[192:195], v[208:211], v[14:17]
	v_mfma_f32_16x16x32_bf16 v[10:13], v[192:195], v[216:219], v[10:13]
	v_mfma_f32_16x16x32_bf16 v[6:9], v[200:203], v[208:211], v[6:9]
	v_mfma_f32_16x16x32_bf16 v[2:5], v[200:203], v[216:219], v[2:5]
	s_barrier
	ds_read_b128 v[156:159], v135
	ds_read_b128 v[160:163], v135 offset:1024
	ds_read_b128 v[164:167], v135 offset:2048
	ds_read_b128 v[168:171], v135 offset:3072
	s_add_i32 m0, s100, 0x4000
	ds_read_b128 v[172:175], v133 offset:32768
	ds_read_b128 v[176:179], v133 offset:33792
	ds_read_b128 v[180:183], v132 offset:32768
	ds_read_b128 v[184:187], v132 offset:33792
	ds_read_b128 v[188:191], v131 offset:32768
	ds_read_b128 v[192:195], v131 offset:33792
	ds_read_b128 v[196:199], v130 offset:32768
	buffer_load_dwordx4 v137, s[88:91], s15 offen lds
	s_add_i32 m0, s100, 0x6000
	ds_read_b128 v[200:203], v130 offset:33792
	buffer_load_dwordx4 v136, s[88:91], s15 offen lds
	s_waitcnt lgkmcnt(8)
	s_barrier
	s_waitcnt lgkmcnt(0)
	v_mfma_f32_16x16x32_bf16 v[126:129], v[172:175], v[156:159], v[126:129]
	v_mfma_f32_16x16x32_bf16 v[122:125], v[172:175], v[164:167], v[122:125]
	v_mfma_f32_16x16x32_bf16 v[118:121], v[180:183], v[156:159], v[118:121]
	v_mfma_f32_16x16x32_bf16 v[114:117], v[180:183], v[164:167], v[114:117]
	v_mfma_f32_16x16x32_bf16 v[110:113], v[188:191], v[156:159], v[110:113]
	v_mfma_f32_16x16x32_bf16 v[106:109], v[188:191], v[164:167], v[106:109]
	v_mfma_f32_16x16x32_bf16 v[102:105], v[196:199], v[156:159], v[102:105]
	v_mfma_f32_16x16x32_bf16 v[98:101], v[196:199], v[164:167], v[98:101]
	v_mfma_f32_16x16x32_bf16 v[126:129], v[176:179], v[160:163], v[126:129]
	v_mfma_f32_16x16x32_bf16 v[122:125], v[176:179], v[168:171], v[122:125]
	v_mfma_f32_16x16x32_bf16 v[118:121], v[184:187], v[160:163], v[118:121]
	v_mfma_f32_16x16x32_bf16 v[114:117], v[184:187], v[168:171], v[114:117]
	v_mfma_f32_16x16x32_bf16 v[110:113], v[192:195], v[160:163], v[110:113]
	v_mfma_f32_16x16x32_bf16 v[106:109], v[192:195], v[168:171], v[106:109]
	v_mfma_f32_16x16x32_bf16 v[102:105], v[200:203], v[160:163], v[102:105]
	v_mfma_f32_16x16x32_bf16 v[98:101], v[200:203], v[168:171], v[98:101]
	s_barrier
	s_add_i32 s15, s3, 0xfff80000
	s_add_i32 m0, s100, 0x18000
	ds_read_b128 v[204:207], v134
	ds_read_b128 v[208:211], v134 offset:1024
	ds_read_b128 v[212:215], v134 offset:2048
	buffer_load_dwordx4 v137, s[4:7], s15 offen lds
	s_add_i32 m0, s100, 0x1a000
	ds_read_b128 v[216:219], v134 offset:3072
	buffer_load_dwordx4 v136, s[4:7], s15 offen lds
	s_barrier
	s_waitcnt lgkmcnt(0)
	v_mfma_f32_16x16x32_bf16 v[94:97], v[172:175], v[204:207], v[94:97]
	v_mfma_f32_16x16x32_bf16 v[90:93], v[172:175], v[212:215], v[90:93]
	v_mfma_f32_16x16x32_bf16 v[86:89], v[180:183], v[204:207], v[86:89]
	v_mfma_f32_16x16x32_bf16 v[82:85], v[180:183], v[212:215], v[82:85]
	v_mfma_f32_16x16x32_bf16 v[78:81], v[188:191], v[204:207], v[78:81]
	v_mfma_f32_16x16x32_bf16 v[74:77], v[188:191], v[212:215], v[74:77]
	v_mfma_f32_16x16x32_bf16 v[70:73], v[196:199], v[204:207], v[70:73]
	v_mfma_f32_16x16x32_bf16 v[66:69], v[196:199], v[212:215], v[66:69]
	v_mfma_f32_16x16x32_bf16 v[94:97], v[176:179], v[208:211], v[94:97]
	v_mfma_f32_16x16x32_bf16 v[90:93], v[176:179], v[216:219], v[90:93]
	v_mfma_f32_16x16x32_bf16 v[86:89], v[184:187], v[208:211], v[86:89]
	v_mfma_f32_16x16x32_bf16 v[82:85], v[184:187], v[216:219], v[82:85]
	v_mfma_f32_16x16x32_bf16 v[78:81], v[192:195], v[208:211], v[78:81]
	v_mfma_f32_16x16x32_bf16 v[74:77], v[192:195], v[216:219], v[74:77]
	v_mfma_f32_16x16x32_bf16 v[70:73], v[200:203], v[208:211], v[70:73]
	v_mfma_f32_16x16x32_bf16 v[66:69], v[200:203], v[216:219], v[66:69]
	s_add_i32 m0, s100, 0x8000
	s_barrier
; #define WAIT_V(n) asm volatile("s_waitcnt vmcnt(" #n ")" ::: "memory")
; #define WAIT_L(n) asm volatile("s_waitcnt lgkmcnt(" #n ")" ::: "memory")
; #define BAR __builtin_amdgcn_s_barrier()
; #define SCHED __builtin_amdgcn_sched_barrier(0)
; __device__ __forceinline__ void mainloop_8phase(const u16* __restrict__ A, const u16* __restrict__ Bt, int K,
;                                                 f32x4 (&acc)[2][2][4][2], int wid_s, int ld) {
;     ...
;     LDA(At, 1, 1); STAGE(SA(1, 0), A, brow, t + 3);
;     BAR; WAIT_L(0); MMA(1, 0, At, B0); BAR; SCHED;
;     STAGE(SB(1, 1), Bt, bcol + G_HALF, t + 3);
;     WAIT_V(6); BAR; MMA(1, 1, At, B1); BAR;
;   }
;   { LDB(B0, 0, 0); LDA(At, 0, 0); STAGE(SA(1, 1), A, brow + G_HALF, nt - 1);
;     BAR; WAIT_L(0); MMA(0, 0, At, B0); BAR;
;     LDB(B1, 0, 1); BAR; WAIT_L(0); MMA(0, 1, At, B1); BAR;
	ds_read_b128 v[172:175], v133 offset:49152
	ds_read_b128 v[176:179], v133 offset:50176
	ds_read_b128 v[180:183], v132 offset:49152
	ds_read_b128 v[184:187], v132 offset:50176
	ds_read_b128 v[188:191], v131 offset:49152
	ds_read_b128 v[192:195], v131 offset:50176
	ds_read_b128 v[196:199], v130 offset:49152
	buffer_load_dwordx4 v137, s[88:91], s15 offen lds
	s_add_i32 m0, s100, 0xa000
	ds_read_b128 v[200:203], v130 offset:50176
	buffer_load_dwordx4 v136, s[88:91], s15 offen lds
	s_barrier
	s_waitcnt lgkmcnt(0)
	v_mfma_f32_16x16x32_bf16 v[62:65], v[172:175], v[156:159], v[62:65]
	v_mfma_f32_16x16x32_bf16 v[58:61], v[172:175], v[164:167], v[58:61]
	v_mfma_f32_16x16x32_bf16 v[54:57], v[180:183], v[156:159], v[54:57]
	v_mfma_f32_16x16x32_bf16 v[50:53], v[180:183], v[164:167], v[50:53]
	v_mfma_f32_16x16x32_bf16 v[46:49], v[188:191], v[156:159], v[46:49]
	v_mfma_f32_16x16x32_bf16 v[42:45], v[188:191], v[164:167], v[42:45]
	v_mfma_f32_16x16x32_bf16 v[38:41], v[196:199], v[156:159], v[38:41]
	v_mfma_f32_16x16x32_bf16 v[34:37], v[196:199], v[164:167], v[34:37]
	v_mfma_f32_16x16x32_bf16 v[62:65], v[176:179], v[160:163], v[62:65]
	v_mfma_f32_16x16x32_bf16 v[58:61], v[176:179], v[168:171], v[58:61]
	v_mfma_f32_16x16x32_bf16 v[54:57], v[184:187], v[160:163], v[54:57]
	v_mfma_f32_16x16x32_bf16 v[50:53], v[184:187], v[168:171], v[50:53]
	v_mfma_f32_16x16x32_bf16 v[46:49], v[192:195], v[160:163], v[46:49]
	v_mfma_f32_16x16x32_bf16 v[42:45], v[192:195], v[168:171], v[42:45]
	v_mfma_f32_16x16x32_bf16 v[38:41], v[200:203], v[160:163], v[38:41]
	v_mfma_f32_16x16x32_bf16 v[34:37], v[200:203], v[168:171], v[34:37]
	s_barrier
	s_add_i32 m0, s100, 0x1c000
	buffer_load_dwordx4 v137, s[4:7], s3 offen lds
	s_add_i32 m0, s100, 0x1e000
	s_nop 0
	buffer_load_dwordx4 v136, s[4:7], s3 offen lds
	s_waitcnt vmcnt(6)
	s_barrier
	v_mfma_f32_16x16x32_bf16 v[30:33], v[172:175], v[204:207], v[30:33]
	v_mfma_f32_16x16x32_bf16 v[26:29], v[172:175], v[212:215], v[26:29]
	v_mfma_f32_16x16x32_bf16 v[22:25], v[180:183], v[204:207], v[22:25]
	v_mfma_f32_16x16x32_bf16 v[18:21], v[180:183], v[212:215], v[18:21]
	v_mfma_f32_16x16x32_bf16 v[14:17], v[188:191], v[204:207], v[14:17]
	v_mfma_f32_16x16x32_bf16 v[10:13], v[188:191], v[212:215], v[10:13]
	v_mfma_f32_16x16x32_bf16 v[6:9], v[196:199], v[204:207], v[6:9]
	v_mfma_f32_16x16x32_bf16 v[2:5], v[196:199], v[212:215], v[2:5]
	v_mfma_f32_16x16x32_bf16 v[30:33], v[176:179], v[208:211], v[30:33]
	v_mfma_f32_16x16x32_bf16 v[26:29], v[176:179], v[216:219], v[26:29]
	v_mfma_f32_16x16x32_bf16 v[22:25], v[184:187], v[208:211], v[22:25]
	v_mfma_f32_16x16x32_bf16 v[18:21], v[184:187], v[216:219], v[18:21]
	v_mfma_f32_16x16x32_bf16 v[14:17], v[192:195], v[208:211], v[14:17]
	v_mfma_f32_16x16x32_bf16 v[10:13], v[192:195], v[216:219], v[10:13]
	v_mfma_f32_16x16x32_bf16 v[6:9], v[200:203], v[208:211], v[6:9]
	v_mfma_f32_16x16x32_bf16 v[2:5], v[200:203], v[216:219], v[2:5]
	s_add_i32 s2, s2, 2
	s_addk_i32 s3, 0x100
	s_cmp_lt_u32 s2, 28
	s_barrier
	s_cbranch_scc1 .LBB0_162
	v_readfirstlane_b32 s2, v150
	s_mov_b32 m0, s2
	s_mov_b32 s3, 0x80f80
	v_readfirstlane_b32 s2, v149
	ds_read_b128 v[138:141], v148
	ds_read_b128 v[152:155], v148 offset:1024
	ds_read_b128 v[156:159], v148 offset:2048
	ds_read_b128 v[160:163], v148 offset:3072
	ds_read_b128 v[164:167], v133
	ds_read_b128 v[168:171], v133 offset:1024
	ds_read_b128 v[172:175], v132
	ds_read_b128 v[176:179], v132 offset:1024
	ds_read_b128 v[180:183], v131
	ds_read_b128 v[184:187], v131 offset:1024
	ds_read_b128 v[188:191], v130
	ds_read_b128 v[192:195], v130 offset:1024
	buffer_load_dwordx4 v137, s[88:91], s3 offen lds
	s_mov_b32 m0, s2
	s_nop 0
	buffer_load_dwordx4 v136, s[88:91], s3 offen lds
	s_barrier
	s_waitcnt lgkmcnt(0)
	v_mfma_f32_16x16x32_bf16 v[126:129], v[164:167], v[138:141], v[126:129]
	v_mfma_f32_16x16x32_bf16 v[118:121], v[172:175], v[138:141], v[118:121]
	v_mfma_f32_16x16x32_bf16 v[110:113], v[180:183], v[138:141], v[110:113]
	v_mfma_f32_16x16x32_bf16 v[102:105], v[188:191], v[138:141], v[102:105]
	v_mfma_f32_16x16x32_bf16 v[126:129], v[168:171], v[152:155], v[126:129]
	v_mfma_f32_16x16x32_bf16 v[122:125], v[164:167], v[156:159], v[122:125]
	v_mfma_f32_16x16x32_bf16 v[118:121], v[176:179], v[152:155], v[118:121]
	v_mfma_f32_16x16x32_bf16 v[114:117], v[172:175], v[156:159], v[114:117]
	v_mfma_f32_16x16x32_bf16 v[110:113], v[184:187], v[152:155], v[110:113]
	v_mfma_f32_16x16x32_bf16 v[106:109], v[180:183], v[156:159], v[106:109]
	v_mfma_f32_16x16x32_bf16 v[102:105], v[192:195], v[152:155], v[102:105]
	v_mfma_f32_16x16x32_bf16 v[98:101], v[188:191], v[156:159], v[98:101]
	v_mfma_f32_16x16x32_bf16 v[146:149], v[168:171], v[160:163], v[122:125]
	v_mfma_f32_16x16x32_bf16 v[196:199], v[176:179], v[160:163], v[114:117]
	v_mfma_f32_16x16x32_bf16 v[200:203], v[184:187], v[160:163], v[106:109]
	v_mfma_f32_16x16x32_bf16 v[204:207], v[192:195], v[160:163], v[98:101]
	s_barrier
	s_nop 1
	ds_read_b128 v[98:101], v145
	ds_read_b128 v[106:109], v145 offset:1024
	ds_read_b128 v[114:117], v145 offset:2048
	ds_read_b128 v[122:125], v145 offset:3072
	s_barrier
; #define WAIT_V(n) asm volatile("s_waitcnt vmcnt(" #n ")" ::: "memory")
; #define WAIT_L(n) asm volatile("s_waitcnt lgkmcnt(" #n ")" ::: "memory")
; #define BAR __builtin_amdgcn_s_barrier()
; __device__ __forceinline__ void mainloop_8phase(const u16* __restrict__ A, const u16* __restrict__ Bt, int K,
;                                                 f32x4 (&acc)[2][2][4][2], int wid_s, int ld) {
;     ...
;     LDB(B1, 0, 1); BAR; WAIT_L(0); MMA(0, 1, At, B1); BAR;
;     LDA(At, 0, 1); WAIT_V(4); BAR; WAIT_L(0); MMA(1, 0, At, B0); MMA(1, 1, At, B1); BAR; }
;   { LDB(B0, 1, 0); LDA(At, 1, 0); WAIT_V(2); BAR; WAIT_L(0); MMA(0, 0, At, B0); BAR;
	s_waitcnt lgkmcnt(0)
	v_mfma_f32_16x16x32_bf16 v[94:97], v[164:167], v[98:101], v[94:97]
	v_mfma_f32_16x16x32_bf16 v[90:93], v[164:167], v[114:117], v[90:93]
	v_mfma_f32_16x16x32_bf16 v[86:89], v[172:175], v[98:101], v[86:89]
	v_mfma_f32_16x16x32_bf16 v[82:85], v[172:175], v[114:117], v[82:85]
	v_mfma_f32_16x16x32_bf16 v[78:81], v[180:183], v[98:101], v[78:81]
	v_mfma_f32_16x16x32_bf16 v[74:77], v[180:183], v[114:117], v[74:77]
	v_mfma_f32_16x16x32_bf16 v[70:73], v[188:191], v[98:101], v[70:73]
	v_mfma_f32_16x16x32_bf16 v[66:69], v[188:191], v[114:117], v[66:69]
	v_mfma_f32_16x16x32_bf16 v[94:97], v[168:171], v[106:109], v[94:97]
	v_mfma_f32_16x16x32_bf16 v[90:93], v[168:171], v[122:125], v[90:93]
	v_mfma_f32_16x16x32_bf16 v[86:89], v[176:179], v[106:109], v[86:89]
	v_mfma_f32_16x16x32_bf16 v[82:85], v[176:179], v[122:125], v[82:85]
	v_mfma_f32_16x16x32_bf16 v[78:81], v[184:187], v[106:109], v[78:81]
	v_mfma_f32_16x16x32_bf16 v[74:77], v[184:187], v[122:125], v[74:77]
	v_mfma_f32_16x16x32_bf16 v[70:73], v[192:195], v[106:109], v[70:73]
	v_mfma_f32_16x16x32_bf16 v[66:69], v[192:195], v[122:125], v[66:69]
	s_barrier
	ds_read_b128 v[142:145], v133 offset:16384
	ds_read_b128 v[164:167], v133 offset:17408
	ds_read_b128 v[168:171], v132 offset:16384
	ds_read_b128 v[172:175], v132 offset:17408
	ds_read_b128 v[176:179], v131 offset:16384
	ds_read_b128 v[180:183], v131 offset:17408
	ds_read_b128 v[184:187], v130 offset:16384
	ds_read_b128 v[188:191], v130 offset:17408
	s_waitcnt vmcnt(4)
	s_barrier
	s_waitcnt lgkmcnt(0)
	v_mfma_f32_16x16x32_bf16 v[62:65], v[142:145], v[138:141], v[62:65]
	v_mfma_f32_16x16x32_bf16 v[58:61], v[142:145], v[156:159], v[58:61]
	v_mfma_f32_16x16x32_bf16 v[54:57], v[168:171], v[138:141], v[54:57]
	v_mfma_f32_16x16x32_bf16 v[50:53], v[168:171], v[156:159], v[50:53]
	v_mfma_f32_16x16x32_bf16 v[46:49], v[176:179], v[138:141], v[46:49]
	v_mfma_f32_16x16x32_bf16 v[42:45], v[176:179], v[156:159], v[42:45]
	v_mfma_f32_16x16x32_bf16 v[38:41], v[184:187], v[138:141], v[38:41]
	v_mfma_f32_16x16x32_bf16 v[34:37], v[184:187], v[156:159], v[34:37]
	v_mfma_f32_16x16x32_bf16 v[192:195], v[164:167], v[152:155], v[62:65]
	v_mfma_f32_16x16x32_bf16 v[208:211], v[164:167], v[160:163], v[58:61]
	v_mfma_f32_16x16x32_bf16 v[212:215], v[172:175], v[152:155], v[54:57]
	v_mfma_f32_16x16x32_bf16 v[216:219], v[172:175], v[160:163], v[50:53]
	v_mfma_f32_16x16x32_bf16 v[220:223], v[180:183], v[152:155], v[46:49]
	v_mfma_f32_16x16x32_bf16 v[224:227], v[180:183], v[160:163], v[42:45]
	v_mfma_f32_16x16x32_bf16 v[136:139], v[188:191], v[152:155], v[38:41]
	v_mfma_f32_16x16x32_bf16 v[150:153], v[188:191], v[160:163], v[34:37]
	v_mfma_f32_16x16x32_bf16 v[30:33], v[142:145], v[98:101], v[30:33]
	v_mfma_f32_16x16x32_bf16 v[22:25], v[168:171], v[98:101], v[22:25]
	v_mfma_f32_16x16x32_bf16 v[14:17], v[176:179], v[98:101], v[14:17]
	v_mfma_f32_16x16x32_bf16 v[6:9], v[184:187], v[98:101], v[6:9]
	v_mfma_f32_16x16x32_bf16 v[30:33], v[164:167], v[106:109], v[30:33]
	v_mfma_f32_16x16x32_bf16 v[26:29], v[142:145], v[114:117], v[26:29]
	v_mfma_f32_16x16x32_bf16 v[22:25], v[172:175], v[106:109], v[22:25]
	v_mfma_f32_16x16x32_bf16 v[18:21], v[168:171], v[114:117], v[18:21]
	v_mfma_f32_16x16x32_bf16 v[14:17], v[180:183], v[106:109], v[14:17]
	v_mfma_f32_16x16x32_bf16 v[10:13], v[176:179], v[114:117], v[10:13]
	v_mfma_f32_16x16x32_bf16 v[6:9], v[188:191], v[106:109], v[6:9]
	v_mfma_f32_16x16x32_bf16 v[2:5], v[184:187], v[114:117], v[2:5]
	v_mfma_f32_16x16x32_bf16 v[140:143], v[164:167], v[122:125], v[26:29]
	v_mfma_f32_16x16x32_bf16 v[154:157], v[172:175], v[122:125], v[18:21]
	v_mfma_f32_16x16x32_bf16 v[158:161], v[180:183], v[122:125], v[10:13]
	v_mfma_f32_16x16x32_bf16 v[162:165], v[188:191], v[122:125], v[2:5]
	s_barrier
	s_nop 1
	ds_read_b128 v[2:5], v135
	ds_read_b128 v[166:169], v135 offset:1024
	ds_read_b128 v[170:173], v135 offset:2048
	ds_read_b128 v[174:177], v135 offset:3072
	ds_read_b128 v[10:13], v133 offset:32768
	ds_read_b128 v[18:21], v133 offset:33792
	ds_read_b128 v[26:29], v132 offset:32768
	ds_read_b128 v[38:41], v132 offset:33792
	ds_read_b128 v[46:49], v131 offset:32768
	ds_read_b128 v[178:181], v131 offset:33792
	ds_read_b128 v[182:185], v130 offset:32768
	ds_read_b128 v[186:189], v130 offset:33792
	s_waitcnt vmcnt(2)
	s_barrier
; #define WAIT_V(n) asm volatile("s_waitcnt vmcnt(" #n ")" ::: "memory")
; #define WAIT_L(n) asm volatile("s_waitcnt lgkmcnt(" #n ")" ::: "memory")
; #define BAR __builtin_amdgcn_s_barrier()
; __device__ __forceinline__ void mainloop_8phase(const u16* __restrict__ A, const u16* __restrict__ Bt, int K,
;                                                 f32x4 (&acc)[2][2][4][2], int wid_s, int ld) {
;     ...
;   { LDB(B0, 1, 0); LDA(At, 1, 0); WAIT_V(2); BAR; WAIT_L(0); MMA(0, 0, At, B0); BAR;
;     LDB(B1, 1, 1); WAIT_V(0); BAR; WAIT_L(0); MMA(0, 1, At, B1); BAR;
;     LDA(At, 1, 1); BAR; WAIT_L(0); MMA(1, 0, At, B0); MMA(1, 1, At, B1); BAR; }
;   if (wr == 0) BAR;
	s_waitcnt lgkmcnt(0)
	v_mfma_f32_16x16x32_bf16 v[34:37], v[10:13], v[2:5], v[126:129]
	v_mfma_f32_16x16x32_bf16 v[122:125], v[18:21], v[166:169], v[34:37]
	v_mfma_f32_16x16x32_bf16 v[34:37], v[10:13], v[170:173], v[146:149]
	v_mfma_f32_16x16x32_bf16 v[58:61], v[18:21], v[174:177], v[34:37]
	v_mfma_f32_16x16x32_bf16 v[34:37], v[26:29], v[2:5], v[118:121]
	v_mfma_f32_16x16x32_bf16 v[114:117], v[38:41], v[166:169], v[34:37]
	v_mfma_f32_16x16x32_bf16 v[34:37], v[26:29], v[170:173], v[196:199]
	v_mfma_f32_16x16x32_bf16 v[50:53], v[38:41], v[174:177], v[34:37]
	v_mfma_f32_16x16x32_bf16 v[34:37], v[46:49], v[2:5], v[110:113]
	v_mfma_f32_16x16x32_bf16 v[106:109], v[178:181], v[166:169], v[34:37]
	v_mfma_f32_16x16x32_bf16 v[34:37], v[46:49], v[170:173], v[200:203]
	v_mfma_f32_16x16x32_bf16 v[42:45], v[178:181], v[174:177], v[34:37]
	v_mfma_f32_16x16x32_bf16 v[34:37], v[182:185], v[2:5], v[102:105]
	v_mfma_f32_16x16x32_bf16 v[98:101], v[186:189], v[166:169], v[34:37]
	v_mfma_f32_16x16x32_bf16 v[34:37], v[182:185], v[170:173], v[204:207]
	v_mfma_f32_16x16x32_bf16 v[34:37], v[186:189], v[174:177], v[34:37]
	s_barrier
	ds_read_b128 v[144:147], v134
	ds_read_b128 v[196:199], v134 offset:1024
	ds_read_b128 v[200:203], v134 offset:2048
	ds_read_b128 v[204:207], v134 offset:3072
	s_waitcnt vmcnt(0)
	s_barrier
	s_waitcnt lgkmcnt(0)
	v_mfma_f32_16x16x32_bf16 v[54:57], v[10:13], v[144:147], v[94:97]
	v_mfma_f32_16x16x32_bf16 v[10:13], v[10:13], v[200:203], v[90:93]
	v_mfma_f32_16x16x32_bf16 v[62:65], v[18:21], v[204:207], v[10:13]
	v_mfma_f32_16x16x32_bf16 v[10:13], v[26:29], v[144:147], v[86:89]
	v_mfma_f32_16x16x32_bf16 v[118:121], v[38:41], v[196:199], v[10:13]
	v_mfma_f32_16x16x32_bf16 v[10:13], v[26:29], v[200:203], v[82:85]
	v_mfma_f32_16x16x32_bf16 v[126:129], v[18:21], v[196:199], v[54:57]
	v_mfma_f32_16x16x32_bf16 v[54:57], v[38:41], v[204:207], v[10:13]
	v_mfma_f32_16x16x32_bf16 v[10:13], v[46:49], v[144:147], v[78:81]
	v_mfma_f32_16x16x32_bf16 v[110:113], v[178:181], v[196:199], v[10:13]
	v_mfma_f32_16x16x32_bf16 v[10:13], v[46:49], v[200:203], v[74:77]
	v_mfma_f32_16x16x32_bf16 v[46:49], v[178:181], v[204:207], v[10:13]
	v_mfma_f32_16x16x32_bf16 v[10:13], v[182:185], v[144:147], v[70:73]
	v_mfma_f32_16x16x32_bf16 v[102:105], v[186:189], v[196:199], v[10:13]
	v_mfma_f32_16x16x32_bf16 v[10:13], v[182:185], v[200:203], v[66:69]
	v_mfma_f32_16x16x32_bf16 v[38:41], v[186:189], v[204:207], v[10:13]
	s_barrier
	ds_read_b128 v[70:73], v133 offset:49152
	ds_read_b128 v[78:81], v133 offset:50176
	ds_read_b128 v[178:181], v132 offset:49152
	ds_read_b128 v[132:135], v132 offset:50176
	ds_read_b128 v[182:185], v131 offset:49152
	ds_read_b128 v[186:189], v131 offset:50176
	ds_read_b128 v[228:231], v130 offset:49152
	ds_read_b128 v[232:235], v130 offset:50176
	s_barrier
	s_waitcnt lgkmcnt(0)
	v_mfma_f32_16x16x32_bf16 v[10:13], v[70:73], v[2:5], v[192:195]
	v_mfma_f32_16x16x32_bf16 v[90:93], v[78:81], v[166:169], v[10:13]
	v_mfma_f32_16x16x32_bf16 v[10:13], v[70:73], v[170:173], v[208:211]
	v_mfma_f32_16x16x32_bf16 v[26:29], v[78:81], v[174:177], v[10:13]
	v_mfma_f32_16x16x32_bf16 v[10:13], v[178:181], v[2:5], v[212:215]
	v_mfma_f32_16x16x32_bf16 v[82:85], v[132:135], v[166:169], v[10:13]
	v_mfma_f32_16x16x32_bf16 v[10:13], v[178:181], v[170:173], v[216:219]
	v_mfma_f32_16x16x32_bf16 v[18:21], v[132:135], v[174:177], v[10:13]
	v_mfma_f32_16x16x32_bf16 v[10:13], v[182:185], v[2:5], v[220:223]
	v_mfma_f32_16x16x32_bf16 v[2:5], v[228:231], v[2:5], v[136:139]
	v_mfma_f32_16x16x32_bf16 v[74:77], v[186:189], v[166:169], v[10:13]
	v_mfma_f32_16x16x32_bf16 v[10:13], v[182:185], v[170:173], v[224:227]
	v_mfma_f32_16x16x32_bf16 v[66:69], v[232:235], v[166:169], v[2:5]
	v_mfma_f32_16x16x32_bf16 v[2:5], v[228:231], v[170:173], v[150:153]
	v_mfma_f32_16x16x32_bf16 v[10:13], v[186:189], v[174:177], v[10:13]
	v_mfma_f32_16x16x32_bf16 v[2:5], v[232:235], v[174:177], v[2:5]
	v_mfma_f32_16x16x32_bf16 v[30:33], v[70:73], v[144:147], v[30:33]
	v_mfma_f32_16x16x32_bf16 v[94:97], v[78:81], v[196:199], v[30:33]
	v_mfma_f32_16x16x32_bf16 v[30:33], v[70:73], v[200:203], v[140:143]
	v_mfma_f32_16x16x32_bf16 v[22:25], v[178:181], v[144:147], v[22:25]
	v_mfma_f32_16x16x32_bf16 v[14:17], v[182:185], v[144:147], v[14:17]
	v_mfma_f32_16x16x32_bf16 v[6:9], v[228:231], v[144:147], v[6:9]
	v_mfma_f32_16x16x32_bf16 v[30:33], v[78:81], v[204:207], v[30:33]
	v_mfma_f32_16x16x32_bf16 v[86:89], v[132:135], v[196:199], v[22:25]
	v_mfma_f32_16x16x32_bf16 v[22:25], v[178:181], v[200:203], v[154:157]
	v_mfma_f32_16x16x32_bf16 v[78:81], v[186:189], v[196:199], v[14:17]
	v_mfma_f32_16x16x32_bf16 v[14:17], v[182:185], v[200:203], v[158:161]
	v_mfma_f32_16x16x32_bf16 v[70:73], v[232:235], v[196:199], v[6:9]
	v_mfma_f32_16x16x32_bf16 v[6:9], v[228:231], v[200:203], v[162:165]
	v_mfma_f32_16x16x32_bf16 v[22:25], v[132:135], v[204:207], v[22:25]
	v_mfma_f32_16x16x32_bf16 v[14:17], v[186:189], v[204:207], v[14:17]
	v_mfma_f32_16x16x32_bf16 v[6:9], v[232:235], v[204:207], v[6:9]
	s_movk_i32 s2, 0x100
	v_cmp_gt_u32_e32 vcc, s2, v0
	s_barrier
	s_and_saveexec_b64 s[2:3], vcc
	s_cbranch_execz .LBB0_165
	s_barrier

; #define WAIT_V(n) asm volatile("s_waitcnt vmcnt(" #n ")" ::: "memory")
; #define BAR __builtin_amdgcn_s_barrier()
; __device__ __forceinline__ void mainloop_8phase(const u16* __restrict__ A, const u16* __restrict__ Bt, int K,
;                                                 f32x4 (&acc)[2][2][4][2], int wid_s, int ld) {
;     ...
;   int tid = get_tid(wid_s), wid = tid >> 6, lane = tid & 63, wr = wid >> 2, wc = wid & 3, fr = lane & 15, fq = lane >> 4;
;   unsigned goff0, goff1;
;   {
;     int r0, c0, r1, c1;
;     stage_rc(tid * 16, r0, c0);
;     stage_rc(tid * 16 + 8192, r1, c1);
;     goff0 = (unsigned)(r0 * ld + c0) * 2u;
;     goff1 = (unsigned)(r1 * ld + c1) * 2u;
;   }
;   __amdgpu_buffer_rsrc_t rs_A, rs_Bt;
;   {
;     unsigned long ua = (unsigned long)A, ub = (unsigned long)Bt;
;     unsigned alo = __builtin_amdgcn_readfirstlane((unsigned)ua), ahi = __builtin_amdgcn_readfirstlane((unsigned)(ua >> 32));
;     unsigned blo = __builtin_amdgcn_readfirstlane((unsigned)ub), bhi = __builtin_amdgcn_readfirstlane((unsigned)(ub >> 32));
;     rs_A = __builtin_amdgcn_make_buffer_rsrc((void*)(((unsigned long)ahi << 32) | alo), (short)0, 0x7ffffff0, 0x00020000);
;     rs_Bt = __builtin_amdgcn_make_buffer_rsrc((void*)(((unsigned long)bhi << 32) | blo), (short)0, 0x7ffffff0, 0x00020000);
;   }
;   bf16x8 At[4][2], B0[2][2], B1[2][2];
;   const int brow = 0, bcol = 0;
;   int nt = K / G_BK;
;   if (wr == 1) BAR;
;   WAIT_V(0); BAR;
;   STAGE(SB(1, 0), Bt, bcol, 1); STAGE(SA(1, 0), A, brow, 1); STAGE(SB(1, 1), Bt, bcol + G_HALF, 1);
;   WAIT_V(6); BAR;
.LBB0_246:
	s_or_b64 exec, exec, s[0:1]
	v_bfe_i32 v8, v0, 27, 1
	v_lshlrev_b32_e32 v6, 4, v0
	v_lshrrev_b32_e32 v8, 22, v8
	v_add_u32_e32 v8, v6, v8
	v_and_b32_e32 v8, 0xfffffc00, v8
	v_sub_u32_e32 v8, v6, v8
	v_lshrrev_b32_e32 v9, 4, v8
	v_ashrrev_i32_e32 v7, 31, v0
	v_bitop3_b32 v8, v9, v8, 32 bitop3:0x6c
	v_lshrrev_b32_e32 v7, 26, v7
	v_ashrrev_i32_e32 v10, 31, v8
	v_add_u32_e32 v7, v0, v7
	v_lshrrev_b32_e32 v10, 26, v10
	v_ashrrev_i32_e32 v7, 6, v7
	v_add_u32_e32 v10, v8, v10
	v_lshlrev_b32_e32 v9, 3, v7
	v_lshrrev_b32_e32 v11, 6, v10
	v_and_b32_e32 v10, 0xc0, v10
	v_and_b32_e32 v9, 0xffff0, v9
	v_sub_u32_e32 v8, v8, v10
	v_add_u32_e32 v10, 0x2000, v6
	v_add_u32_e32 v9, v11, v9
	v_ashrrev_i32_e32 v11, 31, v10
	v_lshrrev_b32_e32 v11, 22, v11
	v_add_u32_e32 v11, v10, v11
	v_ashrrev_i32_e32 v11, 10, v11
	v_mul_i32_i24_e32 v12, 0x400, v11
	v_sub_u32_e32 v10, v10, v12
	v_lshrrev_b32_e32 v12, 4, v10
	v_bitop3_b32 v10, v12, v10, 32 bitop3:0x6c
	v_ashrrev_i32_e32 v13, 31, v10
	v_lshrrev_b32_e32 v13, 26, v13
	v_add_u32_e32 v13, v10, v13
	v_lshlrev_b32_e32 v7, 5, v7
	v_lshlrev_b32_e32 v12, 3, v11
	v_lshrrev_b32_e32 v14, 6, v13
	v_and_b32_e32 v13, 0xc0, v13
	v_readlane_b32 s3, v254, 43
	v_and_b32_e32 v7, 32, v7
	v_ashrrev_i16_sdwa v8, v244, sext(v8) dst_sel:DWORD dst_unused:UNUSED_PAD src0_sel:DWORD src1_sel:BYTE_0
	v_and_b32_e32 v12, 0xffff0, v12
	v_lshlrev_b32_e32 v11, 5, v11
	v_sub_u32_e32 v10, v10, v13
	s_waitcnt vmcnt(7)
	v_add_u32_e32 v138, s3, v6
	v_bfe_i32 v8, v8, 0, 16
	v_add_u32_e32 v12, v14, v12
	v_and_b32_e32 v11, 32, v11
	v_ashrrev_i16_sdwa v10, v244, sext(v10) dst_sel:DWORD dst_unused:UNUSED_PAD src0_sel:DWORD src1_sel:BYTE_0
	v_lshl_or_b32 v7, v9, 11, v7
	s_and_b32 s5, s13, 0xffff
	v_readfirstlane_b32 s0, v138
	v_add_u32_e32 v139, 0x2000, v138
	v_add_u32_e32 v140, 16, v6
	v_bfe_i32 v10, v10, 0, 16
	v_add_lshl_u32 v137, v7, v8, 1
	v_lshl_or_b32 v7, v12, 11, v11
	s_mov_b32 s24, s12
	s_mov_b32 s25, s5
	s_mov_b32 s26, s90
	s_mov_b32 s27, s91
	s_mov_b32 m0, s0
	s_movk_i32 s1, 0x80
	v_readfirstlane_b32 s0, v139
	v_add_u32_e32 v141, 0x8000, v140
	v_add_lshl_u32 v136, v7, v10, 1
	s_and_b32 s89, s11, 0xffff
	s_waitcnt vmcnt(0)
	s_barrier
	buffer_load_dwordx4 v137, s[24:27], s1 offen lds
	s_mov_b32 m0, s0
	v_readfirstlane_b32 s0, v141
	v_add_u32_e32 v142, 0xa000, v140
	v_readlane_b32 s6, v254, 44
	s_mov_b32 s20, s10
	s_mov_b32 s21, s89
	s_mov_b32 s22, s90
	s_mov_b32 s23, s91
	buffer_load_dwordx4 v136, s[24:27], s1 offen lds
	s_mov_b32 m0, s0
	v_readfirstlane_b32 s0, v142
	v_add_u32_e32 v143, s6, v6
	buffer_load_dwordx4 v137, s[20:23], s1 offen lds
	s_mov_b32 m0, s0
	v_readfirstlane_b32 s0, v143
	v_add_u32_e32 v146, 0x2000, v143
	buffer_load_dwordx4 v136, s[20:23], s1 offen lds
	s_mov_b32 m0, s0
	s_mov_b32 s1, 0x80080
	v_readfirstlane_b32 s0, v146
	buffer_load_dwordx4 v137, s[24:27], s1 offen lds
	s_mov_b32 m0, s0
	v_and_b32_e32 v4, 15, v2
	buffer_load_dwordx4 v136, s[24:27], s1 offen lds
	v_lshlrev_b32_e32 v7, 2, v2
	v_and_b32_e32 v5, 48, v2
	v_lshlrev_b32_e32 v4, 6, v4
	v_and_b32_e32 v7, 32, v7
	v_bitop3_b32 v4, v4, v7, v5 bitop3:0x36
	v_readlane_b32 s0, v254, 41
	v_lshlrev_b32_e32 v2, 6, v2
	s_waitcnt vmcnt(6)
	v_readlane_b32 s1, v254, 42
	v_add_u32_e32 v8, s0, v4
	v_add_u32_e32 v148, s0, v6
	s_movk_i32 s0, 0x3c0
	v_lshlrev_b32_e32 v11, 6, v0
	v_lshlrev_b32_e32 v3, 13, v3
	v_and_or_b32 v2, v2, s0, v5
	v_add_u32_e32 v9, s1, v4
	v_add_u32_e32 v151, s1, v6
	v_add_u32_e32 v6, s3, v4
	v_add_u32_e32 v10, s6, v4
	v_and_b32_e32 v11, 0x3000, v11
	v_add_u32_e32 v4, 16, v4
	v_xad_u32 v5, v2, v7, 16
	v_or_b32_e32 v7, 0x800, v3
	v_or_b32_e32 v12, 0x1000, v3
	v_or_b32_e32 v13, 0x1800, v3
	v_mov_b32_e32 v2, 0
	s_mov_b32 s88, s10
	s_mov_b32 s4, s12
	v_add_u32_e32 v145, 0xc000, v140
	v_add_u32_e32 v144, 0xe000, v140
	v_add_u32_e32 v149, 0x2000, v148
	v_add_u32_e32 v150, 0x2000, v140
	v_add_u32_e32 v152, 0x2000, v151
	v_add_u32_e32 v153, 0x4000, v140
	v_add_u32_e32 v154, 0x6000, v140
	s_mov_b32 s0, -2
	s_mov_b32 s1, 0x80180
	v_add_u32_e32 v155, v8, v11
	s_waitcnt lgkmcnt(0)
	v_add_u32_e32 v133, v4, v3
	v_add_u32_e32 v132, v5, v7
	v_add_u32_e32 v131, v5, v12
	v_add_u32_e32 v130, v5, v13
	v_add_u32_e32 v147, v9, v11
	v_add_u32_e32 v135, v6, v11
	v_add_u32_e32 v134, v10, v11
	v_mov_b32_e32 v3, v2
	v_mov_b32_e32 v4, v2
	v_mov_b32_e32 v5, v2
	v_mov_b32_e32 v6, v2
	v_mov_b32_e32 v7, v2
	v_mov_b32_e32 v8, v2
	v_mov_b32_e32 v9, v2
	v_mov_b32_e32 v10, v2
	v_mov_b32_e32 v11, v2
	v_mov_b32_e32 v12, v2
	v_mov_b32_e32 v13, v2
	v_mov_b32_e32 v14, v2
	v_mov_b32_e32 v15, v2
	v_mov_b32_e32 v16, v2
	v_mov_b32_e32 v17, v2
	v_mov_b32_e32 v18, v2
	v_mov_b32_e32 v19, v2
	v_mov_b32_e32 v20, v2
	v_mov_b32_e32 v21, v2
	v_mov_b32_e32 v22, v2
	v_mov_b32_e32 v23, v2
	v_mov_b32_e32 v24, v2
	v_mov_b32_e32 v25, v2
	v_mov_b32_e32 v26, v2
	v_mov_b32_e32 v27, v2
	v_mov_b32_e32 v28, v2
	v_mov_b32_e32 v29, v2
	v_mov_b32_e32 v30, v2
	v_mov_b32_e32 v31, v2
	v_mov_b32_e32 v32, v2
	v_mov_b32_e32 v33, v2
	v_mov_b32_e32 v34, v2
	v_mov_b32_e32 v35, v2
	v_mov_b32_e32 v36, v2
	v_mov_b32_e32 v37, v2
	v_mov_b32_e32 v38, v2
	v_mov_b32_e32 v39, v2
	v_mov_b32_e32 v40, v2
	v_mov_b32_e32 v41, v2
	v_mov_b32_e32 v42, v2
	v_mov_b32_e32 v43, v2
	v_mov_b32_e32 v44, v2
	v_mov_b32_e32 v45, v2
	v_mov_b32_e32 v46, v2
	v_mov_b32_e32 v47, v2
	v_mov_b32_e32 v48, v2
	v_mov_b32_e32 v49, v2
	v_mov_b32_e32 v50, v2
	v_mov_b32_e32 v51, v2
	v_mov_b32_e32 v52, v2
	v_mov_b32_e32 v53, v2
	v_mov_b32_e32 v54, v2
	v_mov_b32_e32 v55, v2
	v_mov_b32_e32 v56, v2
	v_mov_b32_e32 v57, v2
	v_mov_b32_e32 v58, v2
	v_mov_b32_e32 v59, v2
	v_mov_b32_e32 v60, v2
	v_mov_b32_e32 v61, v2
	v_mov_b32_e32 v62, v2
	v_mov_b32_e32 v63, v2
	v_mov_b32_e32 v64, v2
	v_mov_b32_e32 v65, v2
	v_mov_b32_e32 v66, v2
	v_mov_b32_e32 v67, v2
	s_waitcnt vmcnt(9)
; #define WAIT_L(n) asm volatile("s_waitcnt lgkmcnt(" #n ")" ::: "memory")
; #define BAR __builtin_amdgcn_s_barrier()
; #define SCHED __builtin_amdgcn_sched_barrier(0)
; __device__ __forceinline__ void mainloop_8phase(const u16* __restrict__ A, const u16* __restrict__ Bt, int K,
;                                                 f32x4 (&acc)[2][2][4][2], int wid_s, int ld) {
;     ...
;   for (int t = 0; t < nt - 2; t += 2) {
;     LDB(B0, 0, 0); SCHED; LDA(At, 0, 0); STAGE(SA(1, 1), A, brow + G_HALF, t + 1);
;     WAIT_L(8); BAR; WAIT_L(0); MMA(0, 0, At, B0); BAR; SCHED;
;     LDB(B1, 0, 1); STAGE(SB(0, 0), Bt, bcol, t + 2);
;     BAR; WAIT_L(0); MMA(0, 1, At, B1); BAR;
;     LDA(At, 0, 1); STAGE(SA(0, 0), A, brow, t + 2);
;     BAR; WAIT_L(0); MMA(1, 0, At, B0); BAR; SCHED;
	v_mov_b32_e32 v68, v2
	v_mov_b32_e32 v69, v2
	v_mov_b32_e32 v70, v2
	v_mov_b32_e32 v71, v2
	s_waitcnt vmcnt(8)
	v_mov_b32_e32 v72, v2
	v_mov_b32_e32 v73, v2
	v_mov_b32_e32 v74, v2
	v_mov_b32_e32 v75, v2
	s_waitcnt vmcnt(7)
	v_mov_b32_e32 v76, v2
	v_mov_b32_e32 v77, v2
	v_mov_b32_e32 v78, v2
	v_mov_b32_e32 v79, v2
	s_waitcnt vmcnt(6)
	v_mov_b32_e32 v80, v2
	v_mov_b32_e32 v81, v2
	v_mov_b32_e32 v82, v2
	v_mov_b32_e32 v83, v2
	v_mov_b32_e32 v84, v2
	v_mov_b32_e32 v85, v2
	v_mov_b32_e32 v86, v2
	v_mov_b32_e32 v87, v2
	v_mov_b32_e32 v88, v2
	v_mov_b32_e32 v89, v2
	v_mov_b32_e32 v90, v2
	v_mov_b32_e32 v91, v2
	v_mov_b32_e32 v92, v2
	v_mov_b32_e32 v93, v2
	v_mov_b32_e32 v94, v2
	v_mov_b32_e32 v95, v2
	v_mov_b32_e32 v96, v2
	v_mov_b32_e32 v97, v2
	v_mov_b32_e32 v98, v2
	v_mov_b32_e32 v99, v2
	v_mov_b32_e32 v100, v2
	v_mov_b32_e32 v101, v2
	v_mov_b32_e32 v102, v2
	v_mov_b32_e32 v103, v2
	v_mov_b32_e32 v104, v2
	v_mov_b32_e32 v105, v2
	v_mov_b32_e32 v106, v2
	v_mov_b32_e32 v107, v2
	v_mov_b32_e32 v108, v2
	v_mov_b32_e32 v109, v2
	v_mov_b32_e32 v110, v2
	v_mov_b32_e32 v111, v2
	v_mov_b32_e32 v112, v2
	v_mov_b32_e32 v113, v2
	v_mov_b32_e32 v114, v2
	v_mov_b32_e32 v115, v2
	v_mov_b32_e32 v116, v2
	v_mov_b32_e32 v117, v2
	v_mov_b32_e32 v118, v2
	v_mov_b32_e32 v119, v2
	v_mov_b32_e32 v120, v2
	v_mov_b32_e32 v121, v2
	v_mov_b32_e32 v122, v2
	v_mov_b32_e32 v123, v2
	v_mov_b32_e32 v124, v2
	v_mov_b32_e32 v125, v2
	v_mov_b32_e32 v126, v2
	v_mov_b32_e32 v127, v2
	v_mov_b32_e32 v128, v2
	v_mov_b32_e32 v129, v2
	s_barrier
	s_mov_b32 s6, s90
	s_mov_b32 s7, s91
.LBB0_247:
	ds_read_b128 v[156:159], v155
	ds_read_b128 v[160:163], v155 offset:1024
	ds_read_b128 v[164:167], v155 offset:2048
	ds_read_b128 v[168:171], v155 offset:3072
	s_add_i32 s3, s1, 0xffffff00
	s_add_i32 m0, s100, 0xc000
	ds_read_b128 v[172:175], v133
	ds_read_b128 v[176:179], v133 offset:1024
	ds_read_b128 v[180:183], v132
	ds_read_b128 v[184:187], v132 offset:1024
	ds_read_b128 v[188:191], v131
	ds_read_b128 v[192:195], v131 offset:1024
	ds_read_b128 v[196:199], v130
	buffer_load_dwordx4 v137, s[88:91], s3 offen lds
	s_add_i32 m0, s100, 0xe000
	ds_read_b128 v[200:203], v130 offset:1024
	buffer_load_dwordx4 v136, s[88:91], s3 offen lds
	s_waitcnt lgkmcnt(8)
	s_barrier
	s_waitcnt lgkmcnt(0)
	v_mfma_f32_16x16x32_bf16 v[126:129], v[172:175], v[156:159], v[126:129]
	v_mfma_f32_16x16x32_bf16 v[122:125], v[172:175], v[164:167], v[122:125]
	v_mfma_f32_16x16x32_bf16 v[118:121], v[180:183], v[156:159], v[118:121]
	v_mfma_f32_16x16x32_bf16 v[114:117], v[180:183], v[164:167], v[114:117]
	v_mfma_f32_16x16x32_bf16 v[110:113], v[188:191], v[156:159], v[110:113]
	v_mfma_f32_16x16x32_bf16 v[106:109], v[188:191], v[164:167], v[106:109]
	v_mfma_f32_16x16x32_bf16 v[102:105], v[196:199], v[156:159], v[102:105]
	v_mfma_f32_16x16x32_bf16 v[98:101], v[196:199], v[164:167], v[98:101]
	v_mfma_f32_16x16x32_bf16 v[126:129], v[176:179], v[160:163], v[126:129]
	v_mfma_f32_16x16x32_bf16 v[122:125], v[176:179], v[168:171], v[122:125]
	v_mfma_f32_16x16x32_bf16 v[118:121], v[184:187], v[160:163], v[118:121]
	v_mfma_f32_16x16x32_bf16 v[114:117], v[184:187], v[168:171], v[114:117]
	v_mfma_f32_16x16x32_bf16 v[110:113], v[192:195], v[160:163], v[110:113]
	v_mfma_f32_16x16x32_bf16 v[106:109], v[192:195], v[168:171], v[106:109]
	v_mfma_f32_16x16x32_bf16 v[102:105], v[200:203], v[160:163], v[102:105]
	v_mfma_f32_16x16x32_bf16 v[98:101], v[200:203], v[168:171], v[98:101]
	s_barrier
	s_add_i32 s3, s1, 0xfff7ff80
	s_add_i32 m0, s100, 0x10000
	ds_read_b128 v[204:207], v147
	ds_read_b128 v[208:211], v147 offset:1024
	ds_read_b128 v[212:215], v147 offset:2048
	buffer_load_dwordx4 v137, s[4:7], s3 offen lds
	s_add_i32 m0, s100, 0x12000
	ds_read_b128 v[216:219], v147 offset:3072
	buffer_load_dwordx4 v136, s[4:7], s3 offen lds
	s_barrier
	s_waitcnt lgkmcnt(0)
	v_mfma_f32_16x16x32_bf16 v[94:97], v[172:175], v[204:207], v[94:97]
	v_mfma_f32_16x16x32_bf16 v[90:93], v[172:175], v[212:215], v[90:93]
	v_mfma_f32_16x16x32_bf16 v[86:89], v[180:183], v[204:207], v[86:89]
	v_mfma_f32_16x16x32_bf16 v[82:85], v[180:183], v[212:215], v[82:85]
	v_mfma_f32_16x16x32_bf16 v[78:81], v[188:191], v[204:207], v[78:81]
	v_mfma_f32_16x16x32_bf16 v[74:77], v[188:191], v[212:215], v[74:77]
	v_mfma_f32_16x16x32_bf16 v[70:73], v[196:199], v[204:207], v[70:73]
	v_mfma_f32_16x16x32_bf16 v[66:69], v[196:199], v[212:215], v[66:69]
	v_mfma_f32_16x16x32_bf16 v[94:97], v[176:179], v[208:211], v[94:97]
	v_mfma_f32_16x16x32_bf16 v[90:93], v[176:179], v[216:219], v[90:93]
	v_mfma_f32_16x16x32_bf16 v[86:89], v[184:187], v[208:211], v[86:89]
	v_mfma_f32_16x16x32_bf16 v[82:85], v[184:187], v[216:219], v[82:85]
	v_mfma_f32_16x16x32_bf16 v[78:81], v[192:195], v[208:211], v[78:81]
	v_mfma_f32_16x16x32_bf16 v[74:77], v[192:195], v[216:219], v[74:77]
	v_mfma_f32_16x16x32_bf16 v[70:73], v[200:203], v[208:211], v[70:73]
	v_mfma_f32_16x16x32_bf16 v[66:69], v[200:203], v[216:219], v[66:69]
	s_mov_b32 m0, s100
	s_barrier
	ds_read_b128 v[172:175], v133 offset:16384
	ds_read_b128 v[176:179], v133 offset:17408
	ds_read_b128 v[180:183], v132 offset:16384
	ds_read_b128 v[184:187], v132 offset:17408
	ds_read_b128 v[188:191], v131 offset:16384
	ds_read_b128 v[192:195], v131 offset:17408
	ds_read_b128 v[196:199], v130 offset:16384
	buffer_load_dwordx4 v137, s[88:91], s3 offen lds
	s_add_i32 m0, s100, 0x2000
	ds_read_b128 v[200:203], v130 offset:17408
	buffer_load_dwordx4 v136, s[88:91], s3 offen lds
	s_barrier
; #define WAIT_V(n) asm volatile("s_waitcnt vmcnt(" #n ")" ::: "memory")
; #define WAIT_L(n) asm volatile("s_waitcnt lgkmcnt(" #n ")" ::: "memory")
; #define BAR __builtin_amdgcn_s_barrier()
; #define SCHED __builtin_amdgcn_sched_barrier(0)
; __device__ __forceinline__ void mainloop_8phase(const u16* __restrict__ A, const u16* __restrict__ Bt, int K,
;                                                 f32x4 (&acc)[2][2][4][2], int wid_s, int ld) {
;     ...
;     BAR; WAIT_L(0); MMA(1, 0, At, B0); BAR; SCHED;
;     STAGE(SB(0, 1), Bt, bcol + G_HALF, t + 2);
;     WAIT_V(6); BAR; MMA(1, 1, At, B1); BAR;
;     LDB(B0, 1, 0); SCHED; LDA(At, 1, 0); STAGE(SA(0, 1), A, brow + G_HALF, t + 2);
;     WAIT_L(8); BAR; WAIT_L(0); MMA(0, 0, At, B0); BAR; SCHED;
;     LDB(B1, 1, 1); STAGE(SB(1, 0), Bt, bcol, t + 3);
;     BAR; WAIT_L(0); MMA(0, 1, At, B1); BAR;
;     LDA(At, 1, 1); STAGE(SA(1, 0), A, brow, t + 3);
	s_waitcnt lgkmcnt(0)
	v_mfma_f32_16x16x32_bf16 v[62:65], v[172:175], v[156:159], v[62:65]
	v_mfma_f32_16x16x32_bf16 v[58:61], v[172:175], v[164:167], v[58:61]
	v_mfma_f32_16x16x32_bf16 v[54:57], v[180:183], v[156:159], v[54:57]
	v_mfma_f32_16x16x32_bf16 v[50:53], v[180:183], v[164:167], v[50:53]
	v_mfma_f32_16x16x32_bf16 v[46:49], v[188:191], v[156:159], v[46:49]
	v_mfma_f32_16x16x32_bf16 v[42:45], v[188:191], v[164:167], v[42:45]
	v_mfma_f32_16x16x32_bf16 v[38:41], v[196:199], v[156:159], v[38:41]
	v_mfma_f32_16x16x32_bf16 v[34:37], v[196:199], v[164:167], v[34:37]
	v_mfma_f32_16x16x32_bf16 v[62:65], v[176:179], v[160:163], v[62:65]
	v_mfma_f32_16x16x32_bf16 v[58:61], v[176:179], v[168:171], v[58:61]
	v_mfma_f32_16x16x32_bf16 v[54:57], v[184:187], v[160:163], v[54:57]
	v_mfma_f32_16x16x32_bf16 v[50:53], v[184:187], v[168:171], v[50:53]
	v_mfma_f32_16x16x32_bf16 v[46:49], v[192:195], v[160:163], v[46:49]
	v_mfma_f32_16x16x32_bf16 v[42:45], v[192:195], v[168:171], v[42:45]
	v_mfma_f32_16x16x32_bf16 v[38:41], v[200:203], v[160:163], v[38:41]
	v_mfma_f32_16x16x32_bf16 v[34:37], v[200:203], v[168:171], v[34:37]
	s_barrier
	s_add_i32 s3, s1, 0xffffff80
	s_add_i32 m0, s100, 0x14000
	buffer_load_dwordx4 v137, s[4:7], s3 offen lds
	s_add_i32 m0, s100, 0x16000
	s_nop 0
	buffer_load_dwordx4 v136, s[4:7], s3 offen lds
	s_waitcnt vmcnt(6)
	s_barrier
	v_mfma_f32_16x16x32_bf16 v[30:33], v[172:175], v[204:207], v[30:33]
	v_mfma_f32_16x16x32_bf16 v[26:29], v[172:175], v[212:215], v[26:29]
	v_mfma_f32_16x16x32_bf16 v[22:25], v[180:183], v[204:207], v[22:25]
	v_mfma_f32_16x16x32_bf16 v[18:21], v[180:183], v[212:215], v[18:21]
	v_mfma_f32_16x16x32_bf16 v[14:17], v[188:191], v[204:207], v[14:17]
	v_mfma_f32_16x16x32_bf16 v[10:13], v[188:191], v[212:215], v[10:13]
	v_mfma_f32_16x16x32_bf16 v[6:9], v[196:199], v[204:207], v[6:9]
	v_mfma_f32_16x16x32_bf16 v[2:5], v[196:199], v[212:215], v[2:5]
	v_mfma_f32_16x16x32_bf16 v[30:33], v[176:179], v[208:211], v[30:33]
	v_mfma_f32_16x16x32_bf16 v[26:29], v[176:179], v[216:219], v[26:29]
	v_mfma_f32_16x16x32_bf16 v[22:25], v[184:187], v[208:211], v[22:25]
	v_mfma_f32_16x16x32_bf16 v[18:21], v[184:187], v[216:219], v[18:21]
	v_mfma_f32_16x16x32_bf16 v[14:17], v[192:195], v[208:211], v[14:17]
	v_mfma_f32_16x16x32_bf16 v[10:13], v[192:195], v[216:219], v[10:13]
	v_mfma_f32_16x16x32_bf16 v[6:9], v[200:203], v[208:211], v[6:9]
	v_mfma_f32_16x16x32_bf16 v[2:5], v[200:203], v[216:219], v[2:5]
	s_barrier
	ds_read_b128 v[156:159], v135
	ds_read_b128 v[160:163], v135 offset:1024
	ds_read_b128 v[164:167], v135 offset:2048
	ds_read_b128 v[168:171], v135 offset:3072
	s_add_i32 m0, s100, 0x4000
	ds_read_b128 v[172:175], v133 offset:32768
	ds_read_b128 v[176:179], v133 offset:33792
	ds_read_b128 v[180:183], v132 offset:32768
	ds_read_b128 v[184:187], v132 offset:33792
	ds_read_b128 v[188:191], v131 offset:32768
	ds_read_b128 v[192:195], v131 offset:33792
	ds_read_b128 v[196:199], v130 offset:32768
	buffer_load_dwordx4 v137, s[88:91], s3 offen lds
	s_add_i32 m0, s100, 0x6000
	ds_read_b128 v[200:203], v130 offset:33792
	buffer_load_dwordx4 v136, s[88:91], s3 offen lds
	s_waitcnt lgkmcnt(8)
	s_barrier
	s_waitcnt lgkmcnt(0)
	v_mfma_f32_16x16x32_bf16 v[126:129], v[172:175], v[156:159], v[126:129]
	v_mfma_f32_16x16x32_bf16 v[122:125], v[172:175], v[164:167], v[122:125]
	v_mfma_f32_16x16x32_bf16 v[118:121], v[180:183], v[156:159], v[118:121]
	v_mfma_f32_16x16x32_bf16 v[114:117], v[180:183], v[164:167], v[114:117]
	v_mfma_f32_16x16x32_bf16 v[110:113], v[188:191], v[156:159], v[110:113]
	v_mfma_f32_16x16x32_bf16 v[106:109], v[188:191], v[164:167], v[106:109]
	v_mfma_f32_16x16x32_bf16 v[102:105], v[196:199], v[156:159], v[102:105]
	v_mfma_f32_16x16x32_bf16 v[98:101], v[196:199], v[164:167], v[98:101]
	v_mfma_f32_16x16x32_bf16 v[126:129], v[176:179], v[160:163], v[126:129]
	v_mfma_f32_16x16x32_bf16 v[122:125], v[176:179], v[168:171], v[122:125]
	v_mfma_f32_16x16x32_bf16 v[118:121], v[184:187], v[160:163], v[118:121]
	v_mfma_f32_16x16x32_bf16 v[114:117], v[184:187], v[168:171], v[114:117]
	v_mfma_f32_16x16x32_bf16 v[110:113], v[192:195], v[160:163], v[110:113]
	v_mfma_f32_16x16x32_bf16 v[106:109], v[192:195], v[168:171], v[106:109]
	v_mfma_f32_16x16x32_bf16 v[102:105], v[200:203], v[160:163], v[102:105]
	v_mfma_f32_16x16x32_bf16 v[98:101], v[200:203], v[168:171], v[98:101]
	s_barrier
	s_add_i32 s3, s1, 0xfff80000
	s_add_i32 m0, s100, 0x18000
	ds_read_b128 v[204:207], v134
	ds_read_b128 v[208:211], v134 offset:1024
	ds_read_b128 v[212:215], v134 offset:2048
	buffer_load_dwordx4 v137, s[4:7], s3 offen lds
	s_add_i32 m0, s100, 0x1a000
	ds_read_b128 v[216:219], v134 offset:3072
	buffer_load_dwordx4 v136, s[4:7], s3 offen lds
	s_barrier
	s_waitcnt lgkmcnt(0)
	v_mfma_f32_16x16x32_bf16 v[94:97], v[172:175], v[204:207], v[94:97]
	v_mfma_f32_16x16x32_bf16 v[90:93], v[172:175], v[212:215], v[90:93]
	v_mfma_f32_16x16x32_bf16 v[86:89], v[180:183], v[204:207], v[86:89]
	v_mfma_f32_16x16x32_bf16 v[82:85], v[180:183], v[212:215], v[82:85]
	v_mfma_f32_16x16x32_bf16 v[78:81], v[188:191], v[204:207], v[78:81]
	v_mfma_f32_16x16x32_bf16 v[74:77], v[188:191], v[212:215], v[74:77]
	v_mfma_f32_16x16x32_bf16 v[70:73], v[196:199], v[204:207], v[70:73]
	v_mfma_f32_16x16x32_bf16 v[66:69], v[196:199], v[212:215], v[66:69]
	v_mfma_f32_16x16x32_bf16 v[94:97], v[176:179], v[208:211], v[94:97]
	v_mfma_f32_16x16x32_bf16 v[90:93], v[176:179], v[216:219], v[90:93]
	v_mfma_f32_16x16x32_bf16 v[86:89], v[184:187], v[208:211], v[86:89]
	v_mfma_f32_16x16x32_bf16 v[82:85], v[184:187], v[216:219], v[82:85]
	v_mfma_f32_16x16x32_bf16 v[78:81], v[192:195], v[208:211], v[78:81]
	v_mfma_f32_16x16x32_bf16 v[74:77], v[192:195], v[216:219], v[74:77]
	v_mfma_f32_16x16x32_bf16 v[70:73], v[200:203], v[208:211], v[70:73]
	v_mfma_f32_16x16x32_bf16 v[66:69], v[200:203], v[216:219], v[66:69]
	s_add_i32 m0, s100, 0x8000
	s_barrier
; #define WAIT_V(n) asm volatile("s_waitcnt vmcnt(" #n ")" ::: "memory")
; #define WAIT_L(n) asm volatile("s_waitcnt lgkmcnt(" #n ")" ::: "memory")
; #define BAR __builtin_amdgcn_s_barrier()
; #define SCHED __builtin_amdgcn_sched_barrier(0)
; __device__ __forceinline__ void mainloop_8phase(const u16* __restrict__ A, const u16* __restrict__ Bt, int K,
;                                                 f32x4 (&acc)[2][2][4][2], int wid_s, int ld) {
;     ...
;     LDA(At, 1, 1); STAGE(SA(1, 0), A, brow, t + 3);
;     BAR; WAIT_L(0); MMA(1, 0, At, B0); BAR; SCHED;
;     STAGE(SB(1, 1), Bt, bcol + G_HALF, t + 3);
;     WAIT_V(6); BAR; MMA(1, 1, At, B1); BAR;
;   }
;   { LDB(B0, 0, 0); LDA(At, 0, 0); STAGE(SA(1, 1), A, brow + G_HALF, nt - 1);
;     BAR; WAIT_L(0); MMA(0, 0, At, B0); BAR;
;     LDB(B1, 0, 1); BAR; WAIT_L(0); MMA(0, 1, At, B1); BAR;
	ds_read_b128 v[172:175], v133 offset:49152
	ds_read_b128 v[176:179], v133 offset:50176
	ds_read_b128 v[180:183], v132 offset:49152
	ds_read_b128 v[184:187], v132 offset:50176
	ds_read_b128 v[188:191], v131 offset:49152
	ds_read_b128 v[192:195], v131 offset:50176
	ds_read_b128 v[196:199], v130 offset:49152
	buffer_load_dwordx4 v137, s[88:91], s3 offen lds
	s_add_i32 m0, s100, 0xa000
	ds_read_b128 v[200:203], v130 offset:50176
	buffer_load_dwordx4 v136, s[88:91], s3 offen lds
	s_barrier
	s_waitcnt lgkmcnt(0)
	v_mfma_f32_16x16x32_bf16 v[62:65], v[172:175], v[156:159], v[62:65]
	v_mfma_f32_16x16x32_bf16 v[58:61], v[172:175], v[164:167], v[58:61]
	v_mfma_f32_16x16x32_bf16 v[54:57], v[180:183], v[156:159], v[54:57]
	v_mfma_f32_16x16x32_bf16 v[50:53], v[180:183], v[164:167], v[50:53]
	v_mfma_f32_16x16x32_bf16 v[46:49], v[188:191], v[156:159], v[46:49]
	v_mfma_f32_16x16x32_bf16 v[42:45], v[188:191], v[164:167], v[42:45]
	v_mfma_f32_16x16x32_bf16 v[38:41], v[196:199], v[156:159], v[38:41]
	v_mfma_f32_16x16x32_bf16 v[34:37], v[196:199], v[164:167], v[34:37]
	v_mfma_f32_16x16x32_bf16 v[62:65], v[176:179], v[160:163], v[62:65]
	v_mfma_f32_16x16x32_bf16 v[58:61], v[176:179], v[168:171], v[58:61]
	v_mfma_f32_16x16x32_bf16 v[54:57], v[184:187], v[160:163], v[54:57]
	v_mfma_f32_16x16x32_bf16 v[50:53], v[184:187], v[168:171], v[50:53]
	v_mfma_f32_16x16x32_bf16 v[46:49], v[192:195], v[160:163], v[46:49]
	v_mfma_f32_16x16x32_bf16 v[42:45], v[192:195], v[168:171], v[42:45]
	v_mfma_f32_16x16x32_bf16 v[38:41], v[200:203], v[160:163], v[38:41]
	v_mfma_f32_16x16x32_bf16 v[34:37], v[200:203], v[168:171], v[34:37]
	s_barrier
	s_add_i32 m0, s100, 0x1c000
	buffer_load_dwordx4 v137, s[4:7], s1 offen lds
	s_add_i32 m0, s100, 0x1e000
	s_nop 0
	buffer_load_dwordx4 v136, s[4:7], s1 offen lds
	s_waitcnt vmcnt(6)
	s_barrier
	v_mfma_f32_16x16x32_bf16 v[30:33], v[172:175], v[204:207], v[30:33]
	v_mfma_f32_16x16x32_bf16 v[26:29], v[172:175], v[212:215], v[26:29]
	v_mfma_f32_16x16x32_bf16 v[22:25], v[180:183], v[204:207], v[22:25]
	v_mfma_f32_16x16x32_bf16 v[18:21], v[180:183], v[212:215], v[18:21]
	v_mfma_f32_16x16x32_bf16 v[14:17], v[188:191], v[204:207], v[14:17]
	v_mfma_f32_16x16x32_bf16 v[10:13], v[188:191], v[212:215], v[10:13]
	v_mfma_f32_16x16x32_bf16 v[6:9], v[196:199], v[204:207], v[6:9]
	v_mfma_f32_16x16x32_bf16 v[2:5], v[196:199], v[212:215], v[2:5]
	v_mfma_f32_16x16x32_bf16 v[30:33], v[176:179], v[208:211], v[30:33]
	v_mfma_f32_16x16x32_bf16 v[26:29], v[176:179], v[216:219], v[26:29]
	v_mfma_f32_16x16x32_bf16 v[22:25], v[184:187], v[208:211], v[22:25]
	v_mfma_f32_16x16x32_bf16 v[18:21], v[184:187], v[216:219], v[18:21]
	v_mfma_f32_16x16x32_bf16 v[14:17], v[192:195], v[208:211], v[14:17]
	v_mfma_f32_16x16x32_bf16 v[10:13], v[192:195], v[216:219], v[10:13]
	v_mfma_f32_16x16x32_bf16 v[6:9], v[200:203], v[208:211], v[6:9]
	v_mfma_f32_16x16x32_bf16 v[2:5], v[200:203], v[216:219], v[2:5]
	s_add_i32 s0, s0, 2
	s_addk_i32 s1, 0x100
	s_cmp_lt_u32 s0, 28
	s_barrier
	s_cbranch_scc1 .LBB0_247
	v_readfirstlane_b32 s0, v145
	s_mov_b32 m0, s0
	s_mov_b32 s1, 0x80f80
	v_readfirstlane_b32 s0, v144
	ds_read_b128 v[138:141], v155
	ds_read_b128 v[148:151], v155 offset:1024
	ds_read_b128 v[156:159], v155 offset:2048
	ds_read_b128 v[152:155], v155 offset:3072
	ds_read_b128 v[160:163], v133
	ds_read_b128 v[164:167], v133 offset:1024
	ds_read_b128 v[168:171], v132
	ds_read_b128 v[172:175], v132 offset:1024
	ds_read_b128 v[176:179], v131
	ds_read_b128 v[180:183], v131 offset:1024
	ds_read_b128 v[184:187], v130
	ds_read_b128 v[188:191], v130 offset:1024
	buffer_load_dwordx4 v137, s[88:91], s1 offen lds
	s_mov_b32 m0, s0
	s_nop 0
	buffer_load_dwordx4 v136, s[88:91], s1 offen lds
	s_barrier
	s_waitcnt lgkmcnt(0)
	v_mfma_f32_16x16x32_bf16 v[126:129], v[160:163], v[138:141], v[126:129]
	v_mfma_f32_16x16x32_bf16 v[118:121], v[168:171], v[138:141], v[118:121]
	v_mfma_f32_16x16x32_bf16 v[110:113], v[176:179], v[138:141], v[110:113]
	v_mfma_f32_16x16x32_bf16 v[102:105], v[184:187], v[138:141], v[102:105]
	v_mfma_f32_16x16x32_bf16 v[126:129], v[164:167], v[148:151], v[126:129]
	v_mfma_f32_16x16x32_bf16 v[122:125], v[160:163], v[156:159], v[122:125]
	v_mfma_f32_16x16x32_bf16 v[118:121], v[172:175], v[148:151], v[118:121]
	v_mfma_f32_16x16x32_bf16 v[114:117], v[168:171], v[156:159], v[114:117]
	v_mfma_f32_16x16x32_bf16 v[110:113], v[180:183], v[148:151], v[110:113]
	v_mfma_f32_16x16x32_bf16 v[106:109], v[176:179], v[156:159], v[106:109]
	v_mfma_f32_16x16x32_bf16 v[102:105], v[188:191], v[148:151], v[102:105]
	v_mfma_f32_16x16x32_bf16 v[98:101], v[184:187], v[156:159], v[98:101]
	v_mfma_f32_16x16x32_bf16 v[142:145], v[164:167], v[152:155], v[122:125]
	v_mfma_f32_16x16x32_bf16 v[192:195], v[172:175], v[152:155], v[114:117]
	v_mfma_f32_16x16x32_bf16 v[196:199], v[180:183], v[152:155], v[106:109]
	v_mfma_f32_16x16x32_bf16 v[200:203], v[188:191], v[152:155], v[98:101]
	s_barrier
	s_nop 1
	ds_read_b128 v[98:101], v147
	ds_read_b128 v[106:109], v147 offset:1024
	ds_read_b128 v[114:117], v147 offset:2048
	ds_read_b128 v[122:125], v147 offset:3072
	s_barrier
; #define WAIT_V(n) asm volatile("s_waitcnt vmcnt(" #n ")" ::: "memory")
; #define WAIT_L(n) asm volatile("s_waitcnt lgkmcnt(" #n ")" ::: "memory")
; #define BAR __builtin_amdgcn_s_barrier()
; __device__ __forceinline__ void mainloop_8phase(const u16* __restrict__ A, const u16* __restrict__ Bt, int K,
;                                                 f32x4 (&acc)[2][2][4][2], int wid_s, int ld) {
;     ...
;     LDB(B1, 0, 1); BAR; WAIT_L(0); MMA(0, 1, At, B1); BAR;
;     LDA(At, 0, 1); WAIT_V(4); BAR; WAIT_L(0); MMA(1, 0, At, B0); MMA(1, 1, At, B1); BAR; }
;   { LDB(B0, 1, 0); LDA(At, 1, 0); WAIT_V(2); BAR; WAIT_L(0); MMA(0, 0, At, B0); BAR;
	s_waitcnt lgkmcnt(0)
	v_mfma_f32_16x16x32_bf16 v[94:97], v[160:163], v[98:101], v[94:97]
	v_mfma_f32_16x16x32_bf16 v[90:93], v[160:163], v[114:117], v[90:93]
	v_mfma_f32_16x16x32_bf16 v[86:89], v[168:171], v[98:101], v[86:89]
	v_mfma_f32_16x16x32_bf16 v[82:85], v[168:171], v[114:117], v[82:85]
	v_mfma_f32_16x16x32_bf16 v[78:81], v[176:179], v[98:101], v[78:81]
	v_mfma_f32_16x16x32_bf16 v[74:77], v[176:179], v[114:117], v[74:77]
	v_mfma_f32_16x16x32_bf16 v[70:73], v[184:187], v[98:101], v[70:73]
	v_mfma_f32_16x16x32_bf16 v[66:69], v[184:187], v[114:117], v[66:69]
	v_mfma_f32_16x16x32_bf16 v[94:97], v[164:167], v[106:109], v[94:97]
	v_mfma_f32_16x16x32_bf16 v[90:93], v[164:167], v[122:125], v[90:93]
	v_mfma_f32_16x16x32_bf16 v[86:89], v[172:175], v[106:109], v[86:89]
	v_mfma_f32_16x16x32_bf16 v[82:85], v[172:175], v[122:125], v[82:85]
	v_mfma_f32_16x16x32_bf16 v[78:81], v[180:183], v[106:109], v[78:81]
	v_mfma_f32_16x16x32_bf16 v[74:77], v[180:183], v[122:125], v[74:77]
	v_mfma_f32_16x16x32_bf16 v[70:73], v[188:191], v[106:109], v[70:73]
	v_mfma_f32_16x16x32_bf16 v[66:69], v[188:191], v[122:125], v[66:69]
	s_barrier
	ds_read_b128 v[160:163], v133 offset:16384
	ds_read_b128 v[164:167], v133 offset:17408
	ds_read_b128 v[168:171], v132 offset:16384
	ds_read_b128 v[172:175], v132 offset:17408
	ds_read_b128 v[176:179], v131 offset:16384
	ds_read_b128 v[180:183], v131 offset:17408
	ds_read_b128 v[184:187], v130 offset:16384
	ds_read_b128 v[188:191], v130 offset:17408
	s_waitcnt vmcnt(4)
	s_barrier
	s_waitcnt lgkmcnt(0)
	v_mfma_f32_16x16x32_bf16 v[62:65], v[160:163], v[138:141], v[62:65]
	v_mfma_f32_16x16x32_bf16 v[58:61], v[160:163], v[156:159], v[58:61]
	v_mfma_f32_16x16x32_bf16 v[54:57], v[168:171], v[138:141], v[54:57]
	v_mfma_f32_16x16x32_bf16 v[50:53], v[168:171], v[156:159], v[50:53]
	v_mfma_f32_16x16x32_bf16 v[46:49], v[176:179], v[138:141], v[46:49]
	v_mfma_f32_16x16x32_bf16 v[42:45], v[176:179], v[156:159], v[42:45]
	v_mfma_f32_16x16x32_bf16 v[38:41], v[184:187], v[138:141], v[38:41]
	v_mfma_f32_16x16x32_bf16 v[34:37], v[184:187], v[156:159], v[34:37]
	v_mfma_f32_16x16x32_bf16 v[204:207], v[164:167], v[148:151], v[62:65]
	v_mfma_f32_16x16x32_bf16 v[208:211], v[164:167], v[152:155], v[58:61]
	v_mfma_f32_16x16x32_bf16 v[212:215], v[172:175], v[148:151], v[54:57]
	v_mfma_f32_16x16x32_bf16 v[216:219], v[172:175], v[152:155], v[50:53]
	v_mfma_f32_16x16x32_bf16 v[220:223], v[180:183], v[148:151], v[46:49]
	v_mfma_f32_16x16x32_bf16 v[224:227], v[180:183], v[152:155], v[42:45]
	v_mfma_f32_16x16x32_bf16 v[136:139], v[188:191], v[148:151], v[38:41]
	v_mfma_f32_16x16x32_bf16 v[146:149], v[188:191], v[152:155], v[34:37]
	v_mfma_f32_16x16x32_bf16 v[30:33], v[160:163], v[98:101], v[30:33]
	v_mfma_f32_16x16x32_bf16 v[22:25], v[168:171], v[98:101], v[22:25]
	v_mfma_f32_16x16x32_bf16 v[14:17], v[176:179], v[98:101], v[14:17]
	v_mfma_f32_16x16x32_bf16 v[6:9], v[184:187], v[98:101], v[6:9]
	v_mfma_f32_16x16x32_bf16 v[30:33], v[164:167], v[106:109], v[30:33]
	v_mfma_f32_16x16x32_bf16 v[26:29], v[160:163], v[114:117], v[26:29]
	v_mfma_f32_16x16x32_bf16 v[22:25], v[172:175], v[106:109], v[22:25]
	v_mfma_f32_16x16x32_bf16 v[18:21], v[168:171], v[114:117], v[18:21]
	v_mfma_f32_16x16x32_bf16 v[14:17], v[180:183], v[106:109], v[14:17]
	v_mfma_f32_16x16x32_bf16 v[10:13], v[176:179], v[114:117], v[10:13]
	v_mfma_f32_16x16x32_bf16 v[6:9], v[188:191], v[106:109], v[6:9]
	v_mfma_f32_16x16x32_bf16 v[2:5], v[184:187], v[114:117], v[2:5]
	v_mfma_f32_16x16x32_bf16 v[150:153], v[164:167], v[122:125], v[26:29]
	v_mfma_f32_16x16x32_bf16 v[154:157], v[172:175], v[122:125], v[18:21]
	v_mfma_f32_16x16x32_bf16 v[158:161], v[180:183], v[122:125], v[10:13]
	v_mfma_f32_16x16x32_bf16 v[162:165], v[188:191], v[122:125], v[2:5]
	s_barrier
	s_nop 1
	ds_read_b128 v[2:5], v135
	ds_read_b128 v[10:13], v135 offset:1024
	ds_read_b128 v[18:21], v135 offset:2048
	ds_read_b128 v[26:29], v135 offset:3072
	ds_read_b128 v[34:37], v133 offset:32768
	ds_read_b128 v[38:41], v133 offset:33792
	ds_read_b128 v[42:45], v132 offset:32768
	ds_read_b128 v[46:49], v132 offset:33792
	ds_read_b128 v[166:169], v131 offset:32768
	ds_read_b128 v[170:173], v131 offset:33792
	ds_read_b128 v[174:177], v130 offset:32768
	ds_read_b128 v[178:181], v130 offset:33792
	s_waitcnt vmcnt(2)
	s_barrier
; #define WAIT_V(n) asm volatile("s_waitcnt vmcnt(" #n ")" ::: "memory")
; #define WAIT_L(n) asm volatile("s_waitcnt lgkmcnt(" #n ")" ::: "memory")
; #define BAR __builtin_amdgcn_s_barrier()
; __device__ __forceinline__ void mainloop_8phase(const u16* __restrict__ A, const u16* __restrict__ Bt, int K,
;                                                 f32x4 (&acc)[2][2][4][2], int wid_s, int ld) {
;     ...
;   { LDB(B0, 1, 0); LDA(At, 1, 0); WAIT_V(2); BAR; WAIT_L(0); MMA(0, 0, At, B0); BAR;
;     LDB(B1, 1, 1); WAIT_V(0); BAR; WAIT_L(0); MMA(0, 1, At, B1); BAR;
;     LDA(At, 1, 1); BAR; WAIT_L(0); MMA(1, 0, At, B0); MMA(1, 1, At, B1); BAR; }
;   if (wr == 0) BAR;
	s_waitcnt lgkmcnt(0)
	v_mfma_f32_16x16x32_bf16 v[50:53], v[34:37], v[2:5], v[126:129]
	v_mfma_f32_16x16x32_bf16 v[122:125], v[38:41], v[10:13], v[50:53]
	v_mfma_f32_16x16x32_bf16 v[50:53], v[34:37], v[18:21], v[142:145]
	v_mfma_f32_16x16x32_bf16 v[126:129], v[38:41], v[26:29], v[50:53]
	v_mfma_f32_16x16x32_bf16 v[50:53], v[42:45], v[2:5], v[118:121]
	v_mfma_f32_16x16x32_bf16 v[114:117], v[46:49], v[10:13], v[50:53]
	v_mfma_f32_16x16x32_bf16 v[50:53], v[42:45], v[18:21], v[192:195]
	v_mfma_f32_16x16x32_bf16 v[118:121], v[46:49], v[26:29], v[50:53]
	v_mfma_f32_16x16x32_bf16 v[50:53], v[166:169], v[2:5], v[110:113]
	v_mfma_f32_16x16x32_bf16 v[106:109], v[170:173], v[10:13], v[50:53]
	v_mfma_f32_16x16x32_bf16 v[50:53], v[166:169], v[18:21], v[196:199]
	v_mfma_f32_16x16x32_bf16 v[110:113], v[170:173], v[26:29], v[50:53]
	v_mfma_f32_16x16x32_bf16 v[50:53], v[174:177], v[2:5], v[102:105]
	v_mfma_f32_16x16x32_bf16 v[98:101], v[178:181], v[10:13], v[50:53]
	v_mfma_f32_16x16x32_bf16 v[50:53], v[174:177], v[18:21], v[200:203]
	v_mfma_f32_16x16x32_bf16 v[102:105], v[178:181], v[26:29], v[50:53]
	s_barrier
	ds_read_b128 v[140:143], v134
	ds_read_b128 v[182:185], v134 offset:1024
	ds_read_b128 v[186:189], v134 offset:2048
	ds_read_b128 v[190:193], v134 offset:3072
	s_waitcnt vmcnt(0)
	s_barrier
	s_waitcnt lgkmcnt(0)
	v_mfma_f32_16x16x32_bf16 v[50:53], v[34:37], v[140:143], v[94:97]
	v_mfma_f32_16x16x32_bf16 v[34:37], v[34:37], v[186:189], v[90:93]
	v_mfma_f32_16x16x32_bf16 v[62:65], v[38:41], v[190:193], v[34:37]
	v_mfma_f32_16x16x32_bf16 v[34:37], v[42:45], v[140:143], v[86:89]
	v_mfma_f32_16x16x32_bf16 v[58:61], v[38:41], v[182:185], v[50:53]
	v_mfma_f32_16x16x32_bf16 v[50:53], v[46:49], v[182:185], v[34:37]
	v_mfma_f32_16x16x32_bf16 v[34:37], v[42:45], v[186:189], v[82:85]
	v_mfma_f32_16x16x32_bf16 v[54:57], v[46:49], v[190:193], v[34:37]
	v_mfma_f32_16x16x32_bf16 v[34:37], v[166:169], v[140:143], v[78:81]
	v_mfma_f32_16x16x32_bf16 v[42:45], v[170:173], v[182:185], v[34:37]
	v_mfma_f32_16x16x32_bf16 v[34:37], v[166:169], v[186:189], v[74:77]
	v_mfma_f32_16x16x32_bf16 v[46:49], v[170:173], v[190:193], v[34:37]
	v_mfma_f32_16x16x32_bf16 v[34:37], v[174:177], v[140:143], v[70:73]
	v_mfma_f32_16x16x32_bf16 v[38:41], v[174:177], v[186:189], v[66:69]
	v_mfma_f32_16x16x32_bf16 v[34:37], v[178:181], v[182:185], v[34:37]
	v_mfma_f32_16x16x32_bf16 v[38:41], v[178:181], v[190:193], v[38:41]
	s_barrier
	ds_read_b128 v[166:169], v133 offset:49152
	ds_read_b128 v[170:173], v133 offset:50176
	ds_read_b128 v[174:177], v132 offset:49152
	ds_read_b128 v[132:135], v132 offset:50176
	ds_read_b128 v[178:181], v131 offset:49152
	ds_read_b128 v[194:197], v131 offset:50176
	ds_read_b128 v[198:201], v130 offset:49152
	ds_read_b128 v[228:231], v130 offset:50176
	s_barrier
	s_waitcnt lgkmcnt(0)
	v_mfma_f32_16x16x32_bf16 v[66:69], v[166:169], v[2:5], v[204:207]
	v_mfma_f32_16x16x32_bf16 v[90:93], v[170:173], v[10:13], v[66:69]
	v_mfma_f32_16x16x32_bf16 v[66:69], v[166:169], v[18:21], v[208:211]
	v_mfma_f32_16x16x32_bf16 v[94:97], v[170:173], v[26:29], v[66:69]
	v_mfma_f32_16x16x32_bf16 v[66:69], v[174:177], v[2:5], v[212:215]
	v_mfma_f32_16x16x32_bf16 v[82:85], v[132:135], v[10:13], v[66:69]
	v_mfma_f32_16x16x32_bf16 v[66:69], v[174:177], v[18:21], v[216:219]
	v_mfma_f32_16x16x32_bf16 v[86:89], v[132:135], v[26:29], v[66:69]
	v_mfma_f32_16x16x32_bf16 v[66:69], v[178:181], v[2:5], v[220:223]
	v_mfma_f32_16x16x32_bf16 v[74:77], v[194:197], v[10:13], v[66:69]
	v_mfma_f32_16x16x32_bf16 v[66:69], v[178:181], v[18:21], v[224:227]
	v_mfma_f32_16x16x32_bf16 v[2:5], v[198:201], v[2:5], v[136:139]
	v_mfma_f32_16x16x32_bf16 v[78:81], v[194:197], v[26:29], v[66:69]
	v_mfma_f32_16x16x32_bf16 v[66:69], v[228:231], v[10:13], v[2:5]
	v_mfma_f32_16x16x32_bf16 v[2:5], v[198:201], v[18:21], v[146:149]
	v_mfma_f32_16x16x32_bf16 v[70:73], v[228:231], v[26:29], v[2:5]
	v_mfma_f32_16x16x32_bf16 v[2:5], v[166:169], v[140:143], v[30:33]
	v_mfma_f32_16x16x32_bf16 v[26:29], v[170:173], v[182:185], v[2:5]
	v_mfma_f32_16x16x32_bf16 v[2:5], v[166:169], v[186:189], v[150:153]
	v_mfma_f32_16x16x32_bf16 v[30:33], v[170:173], v[190:193], v[2:5]
	v_mfma_f32_16x16x32_bf16 v[2:5], v[174:177], v[140:143], v[22:25]
	v_mfma_f32_16x16x32_bf16 v[18:21], v[132:135], v[182:185], v[2:5]
	v_mfma_f32_16x16x32_bf16 v[2:5], v[174:177], v[186:189], v[154:157]
	v_mfma_f32_16x16x32_bf16 v[22:25], v[132:135], v[190:193], v[2:5]
	v_mfma_f32_16x16x32_bf16 v[2:5], v[178:181], v[140:143], v[14:17]
	v_mfma_f32_16x16x32_bf16 v[10:13], v[194:197], v[182:185], v[2:5]
	v_mfma_f32_16x16x32_bf16 v[2:5], v[178:181], v[186:189], v[158:161]
	v_mfma_f32_16x16x32_bf16 v[14:17], v[194:197], v[190:193], v[2:5]
	v_mfma_f32_16x16x32_bf16 v[2:5], v[198:201], v[140:143], v[6:9]
	v_mfma_f32_16x16x32_bf16 v[6:9], v[198:201], v[186:189], v[162:165]
	v_mfma_f32_16x16x32_bf16 v[2:5], v[228:231], v[182:185], v[2:5]
	v_mfma_f32_16x16x32_bf16 v[6:9], v[228:231], v[190:193], v[6:9]
	s_movk_i32 s0, 0x100
	v_cmp_gt_u32_e32 vcc, s0, v0
	s_barrier
	s_and_saveexec_b64 s[0:1], vcc
	s_cbranch_execz .LBB0_250
	s_barrier

; #define WAIT_V(n) asm volatile("s_waitcnt vmcnt(" #n ")" ::: "memory")
; #define BAR __builtin_amdgcn_s_barrier()
; __device__ __forceinline__ void mainloop_8phase(const u16* __restrict__ A, const u16* __restrict__ Bt, int K,
;                                                 f32x4 (&acc)[2][2][4][2], int wid_s, int ld) {
;     ...
;   int tid = get_tid(wid_s), wid = tid >> 6, lane = tid & 63, wr = wid >> 2, wc = wid & 3, fr = lane & 15, fq = lane >> 4;
;   unsigned goff0, goff1;
;   {
;     int r0, c0, r1, c1;
;     stage_rc(tid * 16, r0, c0);
;     stage_rc(tid * 16 + 8192, r1, c1);
;     goff0 = (unsigned)(r0 * ld + c0) * 2u;
;     goff1 = (unsigned)(r1 * ld + c1) * 2u;
;   }
;   __amdgpu_buffer_rsrc_t rs_A, rs_Bt;
;   {
;     unsigned long ua = (unsigned long)A, ub = (unsigned long)Bt;
;     unsigned alo = __builtin_amdgcn_readfirstlane((unsigned)ua), ahi = __builtin_amdgcn_readfirstlane((unsigned)(ua >> 32));
;     unsigned blo = __builtin_amdgcn_readfirstlane((unsigned)ub), bhi = __builtin_amdgcn_readfirstlane((unsigned)(ub >> 32));
;     rs_A = __builtin_amdgcn_make_buffer_rsrc((void*)(((unsigned long)ahi << 32) | alo), (short)0, 0x7ffffff0, 0x00020000);
;     rs_Bt = __builtin_amdgcn_make_buffer_rsrc((void*)(((unsigned long)bhi << 32) | blo), (short)0, 0x7ffffff0, 0x00020000);
;   }
;   bf16x8 At[4][2], B0[2][2], B1[2][2];
;   const int brow = 0, bcol = 0;
;   int nt = K / G_BK;
;   if (wr == 1) BAR;
;   WAIT_V(0); BAR;
;   STAGE(SB(1, 0), Bt, bcol, 1); STAGE(SA(1, 0), A, brow, 1); STAGE(SB(1, 1), Bt, bcol + G_HALF, 1);
;   WAIT_V(6); BAR;
.LBB0_341:
	s_or_b64 exec, exec, s[2:3]
	v_bfe_i32 v8, v0, 27, 1
	v_lshlrev_b32_e32 v6, 4, v0
	v_lshrrev_b32_e32 v8, 22, v8
	v_add_u32_e32 v8, v6, v8
	v_and_b32_e32 v8, 0xfffffc00, v8
	v_sub_u32_e32 v8, v6, v8
	v_lshrrev_b32_e32 v9, 4, v8
	v_ashrrev_i32_e32 v7, 31, v0
	v_bitop3_b32 v8, v9, v8, 32 bitop3:0x6c
	v_lshrrev_b32_e32 v7, 26, v7
	v_ashrrev_i32_e32 v10, 31, v8
	v_add_u32_e32 v7, v0, v7
	v_lshrrev_b32_e32 v10, 26, v10
	v_ashrrev_i32_e32 v7, 6, v7
	v_add_u32_e32 v10, v8, v10
	v_lshlrev_b32_e32 v9, 3, v7
	v_lshrrev_b32_e32 v11, 6, v10
	v_and_b32_e32 v10, 0xc0, v10
	v_and_b32_e32 v9, 0xffff0, v9
	v_sub_u32_e32 v8, v8, v10
	v_add_u32_e32 v10, 0x2000, v6
	v_add_u32_e32 v9, v11, v9
	v_ashrrev_i32_e32 v11, 31, v10
	v_lshrrev_b32_e32 v11, 22, v11
	v_add_u32_e32 v11, v10, v11
	v_ashrrev_i32_e32 v11, 10, v11
	v_mul_i32_i24_e32 v12, 0x400, v11
	v_sub_u32_e32 v10, v10, v12
	v_lshrrev_b32_e32 v12, 4, v10
	v_bitop3_b32 v10, v12, v10, 32 bitop3:0x6c
	v_readlane_b32 s2, v254, 62
	v_ashrrev_i32_e32 v13, 31, v10
	v_readlane_b32 s3, v254, 63
	v_lshrrev_b32_e32 v13, 26, v13
	s_and_b32 s89, s3, 0xffff
	s_mov_b32 s88, s2
	s_mov_b32 s12, s2
	v_readlane_b32 s2, v255, 0
	v_add_u32_e32 v13, v10, v13
	v_readlane_b32 s3, v255, 1
	v_lshlrev_b32_e32 v7, 5, v7
	v_lshlrev_b32_e32 v12, 3, v11
	v_lshrrev_b32_e32 v14, 6, v13
	v_and_b32_e32 v13, 0xc0, v13
	s_and_b32 s5, s3, 0xffff
	v_readlane_b32 s3, v254, 43
	v_and_b32_e32 v7, 32, v7
	v_ashrrev_i16_sdwa v8, v244, sext(v8) dst_sel:DWORD dst_unused:UNUSED_PAD src0_sel:DWORD src1_sel:BYTE_0
	v_and_b32_e32 v12, 0xffff0, v12
	v_lshlrev_b32_e32 v11, 5, v11
	v_sub_u32_e32 v10, v10, v13
	s_waitcnt vmcnt(7)
	v_add_u32_e32 v138, s3, v6
	v_bfe_i32 v8, v8, 0, 16
	v_add_u32_e32 v12, v14, v12
	v_and_b32_e32 v11, 32, v11
	v_ashrrev_i16_sdwa v10, v244, sext(v10) dst_sel:DWORD dst_unused:UNUSED_PAD src0_sel:DWORD src1_sel:BYTE_0
	v_lshl_or_b32 v7, v9, 11, v7
	v_readfirstlane_b32 s1, v138
	v_add_u32_e32 v139, 0x2000, v138
	v_add_u32_e32 v140, 16, v6
	v_bfe_i32 v10, v10, 0, 16
	v_add_lshl_u32 v136, v7, v8, 1
	v_lshl_or_b32 v7, v12, 11, v11
	s_mov_b32 s4, s2
	s_mov_b32 s16, s2
	s_mov_b32 s17, s5
	s_mov_b32 s18, s90
	s_mov_b32 s19, s91
	s_mov_b32 m0, s1
	s_movk_i32 s2, 0x80
	v_readfirstlane_b32 s1, v139
	v_add_u32_e32 v141, 0x8000, v140
	v_add_lshl_u32 v135, v7, v10, 1
	s_waitcnt vmcnt(0)
	s_barrier
	buffer_load_dwordx4 v136, s[16:19], s2 offen lds
	s_mov_b32 m0, s1
	v_readfirstlane_b32 s1, v141
	v_add_u32_e32 v142, 0xa000, v140
	v_readlane_b32 s6, v254, 44
	s_mov_b32 s13, s89
	s_mov_b32 s14, s90
	s_mov_b32 s15, s91
	buffer_load_dwordx4 v135, s[16:19], s2 offen lds
	s_mov_b32 m0, s1
	v_readfirstlane_b32 s1, v142
	v_add_u32_e32 v143, s6, v6
	buffer_load_dwordx4 v136, s[12:15], s2 offen lds
	s_mov_b32 m0, s1
	v_readfirstlane_b32 s1, v143
	v_add_u32_e32 v146, 0x2000, v143
	buffer_load_dwordx4 v135, s[12:15], s2 offen lds
	s_mov_b32 m0, s1
	s_mov_b32 s2, 0x80080
	v_readfirstlane_b32 s1, v146
	buffer_load_dwordx4 v136, s[16:19], s2 offen lds
	s_mov_b32 m0, s1
	v_and_b32_e32 v4, 15, v2
	buffer_load_dwordx4 v135, s[16:19], s2 offen lds
	v_lshlrev_b32_e32 v7, 2, v2
	v_and_b32_e32 v5, 48, v2
	v_lshlrev_b32_e32 v4, 6, v4
	v_and_b32_e32 v7, 32, v7
	v_bitop3_b32 v4, v4, v7, v5 bitop3:0x36
	v_readlane_b32 s1, v254, 41
	v_lshlrev_b32_e32 v2, 6, v2
	s_waitcnt vmcnt(6)
	v_readlane_b32 s2, v254, 42
	v_add_u32_e32 v8, s1, v4
	v_add_u32_e32 v148, s1, v6
	s_movk_i32 s1, 0x3c0
	v_lshlrev_b32_e32 v11, 6, v0
	v_lshlrev_b32_e32 v3, 13, v3
	v_and_or_b32 v2, v2, s1, v5
	v_add_u32_e32 v9, s2, v4
	v_add_u32_e32 v151, s2, v6
	v_add_u32_e32 v6, s3, v4
	v_add_u32_e32 v10, s6, v4
	v_and_b32_e32 v11, 0x3000, v11
	v_add_u32_e32 v4, 16, v4
	v_xad_u32 v5, v2, v7, 16
	v_or_b32_e32 v7, 0x800, v3
	v_or_b32_e32 v12, 0x1000, v3
	v_or_b32_e32 v13, 0x1800, v3
	v_mov_b32_e32 v2, 0
	v_add_u32_e32 v145, 0xc000, v140
	v_add_u32_e32 v144, 0xe000, v140
	v_add_u32_e32 v149, 0x2000, v148
	v_add_u32_e32 v150, 0x2000, v140
	v_add_u32_e32 v152, 0x2000, v151
	v_add_u32_e32 v153, 0x4000, v140
	v_add_u32_e32 v154, 0x6000, v140
	s_mov_b32 s1, -2
	s_mov_b32 s2, 0x80180
	v_add_u32_e32 v155, v8, v11
	s_waitcnt lgkmcnt(0)
	v_add_u32_e32 v133, v4, v3
	v_add_u32_e32 v132, v5, v7
	v_add_u32_e32 v131, v5, v12
	v_add_u32_e32 v130, v5, v13
	v_add_u32_e32 v147, v9, v11
	v_add_u32_e32 v137, v6, v11
	v_add_u32_e32 v134, v10, v11
	v_mov_b32_e32 v3, v2
	v_mov_b32_e32 v4, v2
	v_mov_b32_e32 v5, v2
	v_mov_b32_e32 v6, v2
	v_mov_b32_e32 v7, v2
	v_mov_b32_e32 v8, v2
	v_mov_b32_e32 v9, v2
	v_mov_b32_e32 v10, v2
	v_mov_b32_e32 v11, v2
	v_mov_b32_e32 v12, v2
	v_mov_b32_e32 v13, v2
	v_mov_b32_e32 v14, v2
	v_mov_b32_e32 v15, v2
	v_mov_b32_e32 v16, v2
	v_mov_b32_e32 v17, v2
	v_mov_b32_e32 v18, v2
	v_mov_b32_e32 v19, v2
	v_mov_b32_e32 v20, v2
	v_mov_b32_e32 v21, v2
	v_mov_b32_e32 v22, v2
	v_mov_b32_e32 v23, v2
	v_mov_b32_e32 v24, v2
	v_mov_b32_e32 v25, v2
	v_mov_b32_e32 v26, v2
	v_mov_b32_e32 v27, v2
	v_mov_b32_e32 v28, v2
	v_mov_b32_e32 v29, v2
	v_mov_b32_e32 v30, v2
	v_mov_b32_e32 v31, v2
	v_mov_b32_e32 v32, v2
	v_mov_b32_e32 v33, v2
	v_mov_b32_e32 v34, v2
	v_mov_b32_e32 v35, v2
	v_mov_b32_e32 v36, v2
	v_mov_b32_e32 v37, v2
	v_mov_b32_e32 v38, v2
	v_mov_b32_e32 v39, v2
	v_mov_b32_e32 v40, v2
	v_mov_b32_e32 v41, v2
	v_mov_b32_e32 v42, v2
	v_mov_b32_e32 v43, v2
	v_mov_b32_e32 v44, v2
	v_mov_b32_e32 v45, v2
	v_mov_b32_e32 v46, v2
	v_mov_b32_e32 v47, v2
	v_mov_b32_e32 v48, v2
	v_mov_b32_e32 v49, v2
	v_mov_b32_e32 v50, v2
	v_mov_b32_e32 v51, v2
	v_mov_b32_e32 v52, v2
	v_mov_b32_e32 v53, v2
	v_mov_b32_e32 v54, v2
	v_mov_b32_e32 v55, v2
	v_mov_b32_e32 v56, v2
	v_mov_b32_e32 v57, v2
	v_mov_b32_e32 v58, v2
	v_mov_b32_e32 v59, v2
	v_mov_b32_e32 v60, v2
	v_mov_b32_e32 v61, v2
	v_mov_b32_e32 v62, v2
	v_mov_b32_e32 v63, v2
	v_mov_b32_e32 v64, v2
	v_mov_b32_e32 v65, v2
	v_mov_b32_e32 v66, v2
	v_mov_b32_e32 v67, v2
	s_waitcnt vmcnt(9)
; #define WAIT_L(n) asm volatile("s_waitcnt lgkmcnt(" #n ")" ::: "memory")
; #define BAR __builtin_amdgcn_s_barrier()
; #define SCHED __builtin_amdgcn_sched_barrier(0)
; __device__ __forceinline__ void mainloop_8phase(const u16* __restrict__ A, const u16* __restrict__ Bt, int K,
;                                                 f32x4 (&acc)[2][2][4][2], int wid_s, int ld) {
;     ...
;   for (int t = 0; t < nt - 2; t += 2) {
;     LDB(B0, 0, 0); SCHED; LDA(At, 0, 0); STAGE(SA(1, 1), A, brow + G_HALF, t + 1);
;     WAIT_L(8); BAR; WAIT_L(0); MMA(0, 0, At, B0); BAR; SCHED;
;     LDB(B1, 0, 1); STAGE(SB(0, 0), Bt, bcol, t + 2);
;     BAR; WAIT_L(0); MMA(0, 1, At, B1); BAR;
;     LDA(At, 0, 1); STAGE(SA(0, 0), A, brow, t + 2);
;     BAR; WAIT_L(0); MMA(1, 0, At, B0); BAR; SCHED;
	v_mov_b32_e32 v68, v2
	v_mov_b32_e32 v69, v2
	v_mov_b32_e32 v70, v2
	v_mov_b32_e32 v71, v2
	s_waitcnt vmcnt(8)
	v_mov_b32_e32 v72, v2
	v_mov_b32_e32 v73, v2
	v_mov_b32_e32 v74, v2
	v_mov_b32_e32 v75, v2
	s_waitcnt vmcnt(7)
	v_mov_b32_e32 v76, v2
	v_mov_b32_e32 v77, v2
	v_mov_b32_e32 v78, v2
	v_mov_b32_e32 v79, v2
	s_waitcnt vmcnt(6)
	v_mov_b32_e32 v80, v2
	v_mov_b32_e32 v81, v2
	v_mov_b32_e32 v82, v2
	v_mov_b32_e32 v83, v2
	v_mov_b32_e32 v84, v2
	v_mov_b32_e32 v85, v2
	v_mov_b32_e32 v86, v2
	v_mov_b32_e32 v87, v2
	v_mov_b32_e32 v88, v2
	v_mov_b32_e32 v89, v2
	v_mov_b32_e32 v90, v2
	v_mov_b32_e32 v91, v2
	v_mov_b32_e32 v92, v2
	v_mov_b32_e32 v93, v2
	v_mov_b32_e32 v94, v2
	v_mov_b32_e32 v95, v2
	v_mov_b32_e32 v96, v2
	v_mov_b32_e32 v97, v2
	v_mov_b32_e32 v98, v2
	v_mov_b32_e32 v99, v2
	v_mov_b32_e32 v100, v2
	v_mov_b32_e32 v101, v2
	v_mov_b32_e32 v102, v2
	v_mov_b32_e32 v103, v2
	v_mov_b32_e32 v104, v2
	v_mov_b32_e32 v105, v2
	v_mov_b32_e32 v106, v2
	v_mov_b32_e32 v107, v2
	v_mov_b32_e32 v108, v2
	v_mov_b32_e32 v109, v2
	v_mov_b32_e32 v110, v2
	v_mov_b32_e32 v111, v2
	v_mov_b32_e32 v112, v2
	v_mov_b32_e32 v113, v2
	v_mov_b32_e32 v114, v2
	v_mov_b32_e32 v115, v2
	v_mov_b32_e32 v116, v2
	v_mov_b32_e32 v117, v2
	v_mov_b32_e32 v118, v2
	v_mov_b32_e32 v119, v2
	v_mov_b32_e32 v120, v2
	v_mov_b32_e32 v121, v2
	v_mov_b32_e32 v122, v2
	v_mov_b32_e32 v123, v2
	v_mov_b32_e32 v124, v2
	v_mov_b32_e32 v125, v2
	v_mov_b32_e32 v126, v2
	v_mov_b32_e32 v127, v2
	v_mov_b32_e32 v128, v2
	v_mov_b32_e32 v129, v2
	s_barrier
	s_mov_b32 s6, s90
	s_mov_b32 s7, s91
.LBB0_342:
	ds_read_b128 v[156:159], v155
	ds_read_b128 v[160:163], v155 offset:1024
	ds_read_b128 v[164:167], v155 offset:2048
	ds_read_b128 v[168:171], v155 offset:3072
	s_add_i32 s3, s2, 0xffffff00
	s_add_i32 m0, s100, 0xc000
	ds_read_b128 v[172:175], v133
	ds_read_b128 v[176:179], v133 offset:1024
	ds_read_b128 v[180:183], v132
	ds_read_b128 v[184:187], v132 offset:1024
	ds_read_b128 v[188:191], v131
	ds_read_b128 v[192:195], v131 offset:1024
	ds_read_b128 v[196:199], v130
	buffer_load_dwordx4 v136, s[88:91], s3 offen lds
	s_add_i32 m0, s100, 0xe000
	ds_read_b128 v[200:203], v130 offset:1024
	buffer_load_dwordx4 v135, s[88:91], s3 offen lds
	s_waitcnt lgkmcnt(8)
	s_barrier
	s_waitcnt lgkmcnt(0)
	v_mfma_f32_16x16x32_bf16 v[126:129], v[172:175], v[156:159], v[126:129]
	v_mfma_f32_16x16x32_bf16 v[122:125], v[172:175], v[164:167], v[122:125]
	v_mfma_f32_16x16x32_bf16 v[118:121], v[180:183], v[156:159], v[118:121]
	v_mfma_f32_16x16x32_bf16 v[114:117], v[180:183], v[164:167], v[114:117]
	v_mfma_f32_16x16x32_bf16 v[110:113], v[188:191], v[156:159], v[110:113]
	v_mfma_f32_16x16x32_bf16 v[106:109], v[188:191], v[164:167], v[106:109]
	v_mfma_f32_16x16x32_bf16 v[102:105], v[196:199], v[156:159], v[102:105]
	v_mfma_f32_16x16x32_bf16 v[98:101], v[196:199], v[164:167], v[98:101]
	v_mfma_f32_16x16x32_bf16 v[126:129], v[176:179], v[160:163], v[126:129]
	v_mfma_f32_16x16x32_bf16 v[122:125], v[176:179], v[168:171], v[122:125]
	v_mfma_f32_16x16x32_bf16 v[118:121], v[184:187], v[160:163], v[118:121]
	v_mfma_f32_16x16x32_bf16 v[114:117], v[184:187], v[168:171], v[114:117]
	v_mfma_f32_16x16x32_bf16 v[110:113], v[192:195], v[160:163], v[110:113]
	v_mfma_f32_16x16x32_bf16 v[106:109], v[192:195], v[168:171], v[106:109]
	v_mfma_f32_16x16x32_bf16 v[102:105], v[200:203], v[160:163], v[102:105]
	v_mfma_f32_16x16x32_bf16 v[98:101], v[200:203], v[168:171], v[98:101]
	s_barrier
	s_add_i32 s3, s2, 0xfff7ff80
	s_add_i32 m0, s100, 0x10000
	ds_read_b128 v[204:207], v147
	ds_read_b128 v[208:211], v147 offset:1024
	ds_read_b128 v[212:215], v147 offset:2048
	buffer_load_dwordx4 v136, s[4:7], s3 offen lds
	s_add_i32 m0, s100, 0x12000
	ds_read_b128 v[216:219], v147 offset:3072
	buffer_load_dwordx4 v135, s[4:7], s3 offen lds
	s_barrier
	s_waitcnt lgkmcnt(0)
	v_mfma_f32_16x16x32_bf16 v[94:97], v[172:175], v[204:207], v[94:97]
	v_mfma_f32_16x16x32_bf16 v[90:93], v[172:175], v[212:215], v[90:93]
	v_mfma_f32_16x16x32_bf16 v[86:89], v[180:183], v[204:207], v[86:89]
	v_mfma_f32_16x16x32_bf16 v[82:85], v[180:183], v[212:215], v[82:85]
	v_mfma_f32_16x16x32_bf16 v[78:81], v[188:191], v[204:207], v[78:81]
	v_mfma_f32_16x16x32_bf16 v[74:77], v[188:191], v[212:215], v[74:77]
	v_mfma_f32_16x16x32_bf16 v[70:73], v[196:199], v[204:207], v[70:73]
	v_mfma_f32_16x16x32_bf16 v[66:69], v[196:199], v[212:215], v[66:69]
	v_mfma_f32_16x16x32_bf16 v[94:97], v[176:179], v[208:211], v[94:97]
	v_mfma_f32_16x16x32_bf16 v[90:93], v[176:179], v[216:219], v[90:93]
	v_mfma_f32_16x16x32_bf16 v[86:89], v[184:187], v[208:211], v[86:89]
	v_mfma_f32_16x16x32_bf16 v[82:85], v[184:187], v[216:219], v[82:85]
	v_mfma_f32_16x16x32_bf16 v[78:81], v[192:195], v[208:211], v[78:81]
	v_mfma_f32_16x16x32_bf16 v[74:77], v[192:195], v[216:219], v[74:77]
	v_mfma_f32_16x16x32_bf16 v[70:73], v[200:203], v[208:211], v[70:73]
	v_mfma_f32_16x16x32_bf16 v[66:69], v[200:203], v[216:219], v[66:69]
	s_mov_b32 m0, s100
	s_barrier
	ds_read_b128 v[172:175], v133 offset:16384
	ds_read_b128 v[176:179], v133 offset:17408
	ds_read_b128 v[180:183], v132 offset:16384
	ds_read_b128 v[184:187], v132 offset:17408
	ds_read_b128 v[188:191], v131 offset:16384
	ds_read_b128 v[192:195], v131 offset:17408
	ds_read_b128 v[196:199], v130 offset:16384
	buffer_load_dwordx4 v136, s[88:91], s3 offen lds
	s_add_i32 m0, s100, 0x2000
	ds_read_b128 v[200:203], v130 offset:17408
	buffer_load_dwordx4 v135, s[88:91], s3 offen lds
	s_barrier
; #define WAIT_V(n) asm volatile("s_waitcnt vmcnt(" #n ")" ::: "memory")
; #define WAIT_L(n) asm volatile("s_waitcnt lgkmcnt(" #n ")" ::: "memory")
; #define BAR __builtin_amdgcn_s_barrier()
; #define SCHED __builtin_amdgcn_sched_barrier(0)
; __device__ __forceinline__ void mainloop_8phase(const u16* __restrict__ A, const u16* __restrict__ Bt, int K,
;                                                 f32x4 (&acc)[2][2][4][2], int wid_s, int ld) {
;     ...
;     BAR; WAIT_L(0); MMA(1, 0, At, B0); BAR; SCHED;
;     STAGE(SB(0, 1), Bt, bcol + G_HALF, t + 2);
;     WAIT_V(6); BAR; MMA(1, 1, At, B1); BAR;
;     LDB(B0, 1, 0); SCHED; LDA(At, 1, 0); STAGE(SA(0, 1), A, brow + G_HALF, t + 2);
;     WAIT_L(8); BAR; WAIT_L(0); MMA(0, 0, At, B0); BAR; SCHED;
;     LDB(B1, 1, 1); STAGE(SB(1, 0), Bt, bcol, t + 3);
;     BAR; WAIT_L(0); MMA(0, 1, At, B1); BAR;
;     LDA(At, 1, 1); STAGE(SA(1, 0), A, brow, t + 3);
	s_waitcnt lgkmcnt(0)
	v_mfma_f32_16x16x32_bf16 v[62:65], v[172:175], v[156:159], v[62:65]
	v_mfma_f32_16x16x32_bf16 v[58:61], v[172:175], v[164:167], v[58:61]
	v_mfma_f32_16x16x32_bf16 v[54:57], v[180:183], v[156:159], v[54:57]
	v_mfma_f32_16x16x32_bf16 v[50:53], v[180:183], v[164:167], v[50:53]
	v_mfma_f32_16x16x32_bf16 v[46:49], v[188:191], v[156:159], v[46:49]
	v_mfma_f32_16x16x32_bf16 v[42:45], v[188:191], v[164:167], v[42:45]
	v_mfma_f32_16x16x32_bf16 v[38:41], v[196:199], v[156:159], v[38:41]
	v_mfma_f32_16x16x32_bf16 v[34:37], v[196:199], v[164:167], v[34:37]
	v_mfma_f32_16x16x32_bf16 v[62:65], v[176:179], v[160:163], v[62:65]
	v_mfma_f32_16x16x32_bf16 v[58:61], v[176:179], v[168:171], v[58:61]
	v_mfma_f32_16x16x32_bf16 v[54:57], v[184:187], v[160:163], v[54:57]
	v_mfma_f32_16x16x32_bf16 v[50:53], v[184:187], v[168:171], v[50:53]
	v_mfma_f32_16x16x32_bf16 v[46:49], v[192:195], v[160:163], v[46:49]
	v_mfma_f32_16x16x32_bf16 v[42:45], v[192:195], v[168:171], v[42:45]
	v_mfma_f32_16x16x32_bf16 v[38:41], v[200:203], v[160:163], v[38:41]
	v_mfma_f32_16x16x32_bf16 v[34:37], v[200:203], v[168:171], v[34:37]
	s_barrier
	s_add_i32 s3, s2, 0xffffff80
	s_add_i32 m0, s100, 0x14000
	buffer_load_dwordx4 v136, s[4:7], s3 offen lds
	s_add_i32 m0, s100, 0x16000
	s_nop 0
	buffer_load_dwordx4 v135, s[4:7], s3 offen lds
	s_waitcnt vmcnt(6)
	s_barrier
	v_mfma_f32_16x16x32_bf16 v[30:33], v[172:175], v[204:207], v[30:33]
	v_mfma_f32_16x16x32_bf16 v[26:29], v[172:175], v[212:215], v[26:29]
	v_mfma_f32_16x16x32_bf16 v[22:25], v[180:183], v[204:207], v[22:25]
	v_mfma_f32_16x16x32_bf16 v[18:21], v[180:183], v[212:215], v[18:21]
	v_mfma_f32_16x16x32_bf16 v[14:17], v[188:191], v[204:207], v[14:17]
	v_mfma_f32_16x16x32_bf16 v[10:13], v[188:191], v[212:215], v[10:13]
	v_mfma_f32_16x16x32_bf16 v[6:9], v[196:199], v[204:207], v[6:9]
	v_mfma_f32_16x16x32_bf16 v[2:5], v[196:199], v[212:215], v[2:5]
	v_mfma_f32_16x16x32_bf16 v[30:33], v[176:179], v[208:211], v[30:33]
	v_mfma_f32_16x16x32_bf16 v[26:29], v[176:179], v[216:219], v[26:29]
	v_mfma_f32_16x16x32_bf16 v[22:25], v[184:187], v[208:211], v[22:25]
	v_mfma_f32_16x16x32_bf16 v[18:21], v[184:187], v[216:219], v[18:21]
	v_mfma_f32_16x16x32_bf16 v[14:17], v[192:195], v[208:211], v[14:17]
	v_mfma_f32_16x16x32_bf16 v[10:13], v[192:195], v[216:219], v[10:13]
	v_mfma_f32_16x16x32_bf16 v[6:9], v[200:203], v[208:211], v[6:9]
	v_mfma_f32_16x16x32_bf16 v[2:5], v[200:203], v[216:219], v[2:5]
	s_barrier
	ds_read_b128 v[156:159], v137
	ds_read_b128 v[160:163], v137 offset:1024
	ds_read_b128 v[164:167], v137 offset:2048
	ds_read_b128 v[168:171], v137 offset:3072
	s_add_i32 m0, s100, 0x4000
	ds_read_b128 v[172:175], v133 offset:32768
	ds_read_b128 v[176:179], v133 offset:33792
	ds_read_b128 v[180:183], v132 offset:32768
	ds_read_b128 v[184:187], v132 offset:33792
	ds_read_b128 v[188:191], v131 offset:32768
	ds_read_b128 v[192:195], v131 offset:33792
	ds_read_b128 v[196:199], v130 offset:32768
	buffer_load_dwordx4 v136, s[88:91], s3 offen lds
	s_add_i32 m0, s100, 0x6000
	ds_read_b128 v[200:203], v130 offset:33792
	buffer_load_dwordx4 v135, s[88:91], s3 offen lds
	s_waitcnt lgkmcnt(8)
	s_barrier
	s_waitcnt lgkmcnt(0)
	v_mfma_f32_16x16x32_bf16 v[126:129], v[172:175], v[156:159], v[126:129]
	v_mfma_f32_16x16x32_bf16 v[122:125], v[172:175], v[164:167], v[122:125]
	v_mfma_f32_16x16x32_bf16 v[118:121], v[180:183], v[156:159], v[118:121]
	v_mfma_f32_16x16x32_bf16 v[114:117], v[180:183], v[164:167], v[114:117]
	v_mfma_f32_16x16x32_bf16 v[110:113], v[188:191], v[156:159], v[110:113]
	v_mfma_f32_16x16x32_bf16 v[106:109], v[188:191], v[164:167], v[106:109]
	v_mfma_f32_16x16x32_bf16 v[102:105], v[196:199], v[156:159], v[102:105]
	v_mfma_f32_16x16x32_bf16 v[98:101], v[196:199], v[164:167], v[98:101]
	v_mfma_f32_16x16x32_bf16 v[126:129], v[176:179], v[160:163], v[126:129]
	v_mfma_f32_16x16x32_bf16 v[122:125], v[176:179], v[168:171], v[122:125]
	v_mfma_f32_16x16x32_bf16 v[118:121], v[184:187], v[160:163], v[118:121]
	v_mfma_f32_16x16x32_bf16 v[114:117], v[184:187], v[168:171], v[114:117]
	v_mfma_f32_16x16x32_bf16 v[110:113], v[192:195], v[160:163], v[110:113]
	v_mfma_f32_16x16x32_bf16 v[106:109], v[192:195], v[168:171], v[106:109]
	v_mfma_f32_16x16x32_bf16 v[102:105], v[200:203], v[160:163], v[102:105]
	v_mfma_f32_16x16x32_bf16 v[98:101], v[200:203], v[168:171], v[98:101]
	s_barrier
	s_add_i32 s3, s2, 0xfff80000
	s_add_i32 m0, s100, 0x18000
	ds_read_b128 v[204:207], v134
	ds_read_b128 v[208:211], v134 offset:1024
	ds_read_b128 v[212:215], v134 offset:2048
	buffer_load_dwordx4 v136, s[4:7], s3 offen lds
	s_add_i32 m0, s100, 0x1a000
	ds_read_b128 v[216:219], v134 offset:3072
	buffer_load_dwordx4 v135, s[4:7], s3 offen lds
	s_barrier
	s_waitcnt lgkmcnt(0)
	v_mfma_f32_16x16x32_bf16 v[94:97], v[172:175], v[204:207], v[94:97]
	v_mfma_f32_16x16x32_bf16 v[90:93], v[172:175], v[212:215], v[90:93]
	v_mfma_f32_16x16x32_bf16 v[86:89], v[180:183], v[204:207], v[86:89]
	v_mfma_f32_16x16x32_bf16 v[82:85], v[180:183], v[212:215], v[82:85]
	v_mfma_f32_16x16x32_bf16 v[78:81], v[188:191], v[204:207], v[78:81]
	v_mfma_f32_16x16x32_bf16 v[74:77], v[188:191], v[212:215], v[74:77]
	v_mfma_f32_16x16x32_bf16 v[70:73], v[196:199], v[204:207], v[70:73]
	v_mfma_f32_16x16x32_bf16 v[66:69], v[196:199], v[212:215], v[66:69]
	v_mfma_f32_16x16x32_bf16 v[94:97], v[176:179], v[208:211], v[94:97]
	v_mfma_f32_16x16x32_bf16 v[90:93], v[176:179], v[216:219], v[90:93]
	v_mfma_f32_16x16x32_bf16 v[86:89], v[184:187], v[208:211], v[86:89]
	v_mfma_f32_16x16x32_bf16 v[82:85], v[184:187], v[216:219], v[82:85]
	v_mfma_f32_16x16x32_bf16 v[78:81], v[192:195], v[208:211], v[78:81]
	v_mfma_f32_16x16x32_bf16 v[74:77], v[192:195], v[216:219], v[74:77]
	v_mfma_f32_16x16x32_bf16 v[70:73], v[200:203], v[208:211], v[70:73]
	v_mfma_f32_16x16x32_bf16 v[66:69], v[200:203], v[216:219], v[66:69]
	s_add_i32 m0, s100, 0x8000
	s_barrier
; #define WAIT_V(n) asm volatile("s_waitcnt vmcnt(" #n ")" ::: "memory")
; #define WAIT_L(n) asm volatile("s_waitcnt lgkmcnt(" #n ")" ::: "memory")
; #define BAR __builtin_amdgcn_s_barrier()
; #define SCHED __builtin_amdgcn_sched_barrier(0)
; __device__ __forceinline__ void mainloop_8phase(const u16* __restrict__ A, const u16* __restrict__ Bt, int K,
;                                                 f32x4 (&acc)[2][2][4][2], int wid_s, int ld) {
;     ...
;     LDA(At, 1, 1); STAGE(SA(1, 0), A, brow, t + 3);
;     BAR; WAIT_L(0); MMA(1, 0, At, B0); BAR; SCHED;
;     STAGE(SB(1, 1), Bt, bcol + G_HALF, t + 3);
;     WAIT_V(6); BAR; MMA(1, 1, At, B1); BAR;
;   }
;   { LDB(B0, 0, 0); LDA(At, 0, 0); STAGE(SA(1, 1), A, brow + G_HALF, nt - 1);
;     BAR; WAIT_L(0); MMA(0, 0, At, B0); BAR;
;     LDB(B1, 0, 1); BAR; WAIT_L(0); MMA(0, 1, At, B1); BAR;
	ds_read_b128 v[172:175], v133 offset:49152
	ds_read_b128 v[176:179], v133 offset:50176
	ds_read_b128 v[180:183], v132 offset:49152
	ds_read_b128 v[184:187], v132 offset:50176
	ds_read_b128 v[188:191], v131 offset:49152
	ds_read_b128 v[192:195], v131 offset:50176
	ds_read_b128 v[196:199], v130 offset:49152
	buffer_load_dwordx4 v136, s[88:91], s3 offen lds
	s_add_i32 m0, s100, 0xa000
	ds_read_b128 v[200:203], v130 offset:50176
	buffer_load_dwordx4 v135, s[88:91], s3 offen lds
	s_barrier
	s_waitcnt lgkmcnt(0)
	v_mfma_f32_16x16x32_bf16 v[62:65], v[172:175], v[156:159], v[62:65]
	v_mfma_f32_16x16x32_bf16 v[58:61], v[172:175], v[164:167], v[58:61]
	v_mfma_f32_16x16x32_bf16 v[54:57], v[180:183], v[156:159], v[54:57]
	v_mfma_f32_16x16x32_bf16 v[50:53], v[180:183], v[164:167], v[50:53]
	v_mfma_f32_16x16x32_bf16 v[46:49], v[188:191], v[156:159], v[46:49]
	v_mfma_f32_16x16x32_bf16 v[42:45], v[188:191], v[164:167], v[42:45]
	v_mfma_f32_16x16x32_bf16 v[38:41], v[196:199], v[156:159], v[38:41]
	v_mfma_f32_16x16x32_bf16 v[34:37], v[196:199], v[164:167], v[34:37]
	v_mfma_f32_16x16x32_bf16 v[62:65], v[176:179], v[160:163], v[62:65]
	v_mfma_f32_16x16x32_bf16 v[58:61], v[176:179], v[168:171], v[58:61]
	v_mfma_f32_16x16x32_bf16 v[54:57], v[184:187], v[160:163], v[54:57]
	v_mfma_f32_16x16x32_bf16 v[50:53], v[184:187], v[168:171], v[50:53]
	v_mfma_f32_16x16x32_bf16 v[46:49], v[192:195], v[160:163], v[46:49]
	v_mfma_f32_16x16x32_bf16 v[42:45], v[192:195], v[168:171], v[42:45]
	v_mfma_f32_16x16x32_bf16 v[38:41], v[200:203], v[160:163], v[38:41]
	v_mfma_f32_16x16x32_bf16 v[34:37], v[200:203], v[168:171], v[34:37]
	s_barrier
	s_add_i32 m0, s100, 0x1c000
	buffer_load_dwordx4 v136, s[4:7], s2 offen lds
	s_add_i32 m0, s100, 0x1e000
	s_nop 0
	buffer_load_dwordx4 v135, s[4:7], s2 offen lds
	s_waitcnt vmcnt(6)
	s_barrier
	v_mfma_f32_16x16x32_bf16 v[30:33], v[172:175], v[204:207], v[30:33]
	v_mfma_f32_16x16x32_bf16 v[26:29], v[172:175], v[212:215], v[26:29]
	v_mfma_f32_16x16x32_bf16 v[22:25], v[180:183], v[204:207], v[22:25]
	v_mfma_f32_16x16x32_bf16 v[18:21], v[180:183], v[212:215], v[18:21]
	v_mfma_f32_16x16x32_bf16 v[14:17], v[188:191], v[204:207], v[14:17]
	v_mfma_f32_16x16x32_bf16 v[10:13], v[188:191], v[212:215], v[10:13]
	v_mfma_f32_16x16x32_bf16 v[6:9], v[196:199], v[204:207], v[6:9]
	v_mfma_f32_16x16x32_bf16 v[2:5], v[196:199], v[212:215], v[2:5]
	v_mfma_f32_16x16x32_bf16 v[30:33], v[176:179], v[208:211], v[30:33]
	v_mfma_f32_16x16x32_bf16 v[26:29], v[176:179], v[216:219], v[26:29]
	v_mfma_f32_16x16x32_bf16 v[22:25], v[184:187], v[208:211], v[22:25]
	v_mfma_f32_16x16x32_bf16 v[18:21], v[184:187], v[216:219], v[18:21]
	v_mfma_f32_16x16x32_bf16 v[14:17], v[192:195], v[208:211], v[14:17]
	v_mfma_f32_16x16x32_bf16 v[10:13], v[192:195], v[216:219], v[10:13]
	v_mfma_f32_16x16x32_bf16 v[6:9], v[200:203], v[208:211], v[6:9]
	v_mfma_f32_16x16x32_bf16 v[2:5], v[200:203], v[216:219], v[2:5]
	s_add_i32 s1, s1, 2
	s_addk_i32 s2, 0x100
	s_cmp_lt_u32 s1, 28
	s_barrier
	s_cbranch_scc1 .LBB0_342
	v_readfirstlane_b32 s1, v145
	s_mov_b32 m0, s1
	s_mov_b32 s2, 0x80f80
	v_readfirstlane_b32 s1, v144
	ds_read_b128 v[138:141], v155
	ds_read_b128 v[148:151], v155 offset:1024
	ds_read_b128 v[156:159], v155 offset:2048
	ds_read_b128 v[152:155], v155 offset:3072
	ds_read_b128 v[160:163], v133
	ds_read_b128 v[164:167], v133 offset:1024
	ds_read_b128 v[168:171], v132
	ds_read_b128 v[172:175], v132 offset:1024
	ds_read_b128 v[176:179], v131
	ds_read_b128 v[180:183], v131 offset:1024
	ds_read_b128 v[184:187], v130
	ds_read_b128 v[188:191], v130 offset:1024
	buffer_load_dwordx4 v136, s[88:91], s2 offen lds
	s_mov_b32 m0, s1
	s_nop 0
	buffer_load_dwordx4 v135, s[88:91], s2 offen lds
	s_barrier
	s_waitcnt lgkmcnt(0)
	v_mfma_f32_16x16x32_bf16 v[126:129], v[160:163], v[138:141], v[126:129]
	v_mfma_f32_16x16x32_bf16 v[118:121], v[168:171], v[138:141], v[118:121]
	v_mfma_f32_16x16x32_bf16 v[110:113], v[176:179], v[138:141], v[110:113]
	v_mfma_f32_16x16x32_bf16 v[102:105], v[184:187], v[138:141], v[102:105]
	v_mfma_f32_16x16x32_bf16 v[126:129], v[164:167], v[148:151], v[126:129]
	v_mfma_f32_16x16x32_bf16 v[122:125], v[160:163], v[156:159], v[122:125]
	v_mfma_f32_16x16x32_bf16 v[118:121], v[172:175], v[148:151], v[118:121]
	v_mfma_f32_16x16x32_bf16 v[114:117], v[168:171], v[156:159], v[114:117]
	v_mfma_f32_16x16x32_bf16 v[110:113], v[180:183], v[148:151], v[110:113]
	v_mfma_f32_16x16x32_bf16 v[106:109], v[176:179], v[156:159], v[106:109]
	v_mfma_f32_16x16x32_bf16 v[102:105], v[188:191], v[148:151], v[102:105]
	v_mfma_f32_16x16x32_bf16 v[98:101], v[184:187], v[156:159], v[98:101]
	v_mfma_f32_16x16x32_bf16 v[142:145], v[164:167], v[152:155], v[122:125]
	v_mfma_f32_16x16x32_bf16 v[192:195], v[172:175], v[152:155], v[114:117]
	v_mfma_f32_16x16x32_bf16 v[196:199], v[180:183], v[152:155], v[106:109]
	v_mfma_f32_16x16x32_bf16 v[200:203], v[188:191], v[152:155], v[98:101]
	s_barrier
	s_nop 1
	ds_read_b128 v[98:101], v147
	ds_read_b128 v[106:109], v147 offset:1024
	ds_read_b128 v[114:117], v147 offset:2048
	ds_read_b128 v[122:125], v147 offset:3072
	s_barrier
; #define WAIT_V(n) asm volatile("s_waitcnt vmcnt(" #n ")" ::: "memory")
; #define WAIT_L(n) asm volatile("s_waitcnt lgkmcnt(" #n ")" ::: "memory")
; #define BAR __builtin_amdgcn_s_barrier()
; __device__ __forceinline__ void mainloop_8phase(const u16* __restrict__ A, const u16* __restrict__ Bt, int K,
;                                                 f32x4 (&acc)[2][2][4][2], int wid_s, int ld) {
;     ...
;     LDB(B1, 0, 1); BAR; WAIT_L(0); MMA(0, 1, At, B1); BAR;
;     LDA(At, 0, 1); WAIT_V(4); BAR; WAIT_L(0); MMA(1, 0, At, B0); MMA(1, 1, At, B1); BAR; }
;   { LDB(B0, 1, 0); LDA(At, 1, 0); WAIT_V(2); BAR; WAIT_L(0); MMA(0, 0, At, B0); BAR;
	s_waitcnt lgkmcnt(0)
	v_mfma_f32_16x16x32_bf16 v[94:97], v[160:163], v[98:101], v[94:97]
	v_mfma_f32_16x16x32_bf16 v[90:93], v[160:163], v[114:117], v[90:93]
	v_mfma_f32_16x16x32_bf16 v[86:89], v[168:171], v[98:101], v[86:89]
	v_mfma_f32_16x16x32_bf16 v[82:85], v[168:171], v[114:117], v[82:85]
	v_mfma_f32_16x16x32_bf16 v[78:81], v[176:179], v[98:101], v[78:81]
	v_mfma_f32_16x16x32_bf16 v[74:77], v[176:179], v[114:117], v[74:77]
	v_mfma_f32_16x16x32_bf16 v[70:73], v[184:187], v[98:101], v[70:73]
	v_mfma_f32_16x16x32_bf16 v[66:69], v[184:187], v[114:117], v[66:69]
	v_mfma_f32_16x16x32_bf16 v[94:97], v[164:167], v[106:109], v[94:97]
	v_mfma_f32_16x16x32_bf16 v[90:93], v[164:167], v[122:125], v[90:93]
	v_mfma_f32_16x16x32_bf16 v[86:89], v[172:175], v[106:109], v[86:89]
	v_mfma_f32_16x16x32_bf16 v[82:85], v[172:175], v[122:125], v[82:85]
	v_mfma_f32_16x16x32_bf16 v[78:81], v[180:183], v[106:109], v[78:81]
	v_mfma_f32_16x16x32_bf16 v[74:77], v[180:183], v[122:125], v[74:77]
	v_mfma_f32_16x16x32_bf16 v[70:73], v[188:191], v[106:109], v[70:73]
	v_mfma_f32_16x16x32_bf16 v[66:69], v[188:191], v[122:125], v[66:69]
	s_barrier
	ds_read_b128 v[160:163], v133 offset:16384
	ds_read_b128 v[164:167], v133 offset:17408
	ds_read_b128 v[168:171], v132 offset:16384
	ds_read_b128 v[172:175], v132 offset:17408
	ds_read_b128 v[176:179], v131 offset:16384
	ds_read_b128 v[180:183], v131 offset:17408
	ds_read_b128 v[184:187], v130 offset:16384
	ds_read_b128 v[188:191], v130 offset:17408
	s_waitcnt vmcnt(4)
	s_barrier
	s_waitcnt lgkmcnt(0)
	v_mfma_f32_16x16x32_bf16 v[62:65], v[160:163], v[138:141], v[62:65]
	v_mfma_f32_16x16x32_bf16 v[58:61], v[160:163], v[156:159], v[58:61]
	v_mfma_f32_16x16x32_bf16 v[54:57], v[168:171], v[138:141], v[54:57]
	v_mfma_f32_16x16x32_bf16 v[50:53], v[168:171], v[156:159], v[50:53]
	v_mfma_f32_16x16x32_bf16 v[46:49], v[176:179], v[138:141], v[46:49]
	v_mfma_f32_16x16x32_bf16 v[42:45], v[176:179], v[156:159], v[42:45]
	v_mfma_f32_16x16x32_bf16 v[38:41], v[184:187], v[138:141], v[38:41]
	v_mfma_f32_16x16x32_bf16 v[34:37], v[184:187], v[156:159], v[34:37]
	v_mfma_f32_16x16x32_bf16 v[204:207], v[164:167], v[148:151], v[62:65]
	v_mfma_f32_16x16x32_bf16 v[208:211], v[164:167], v[152:155], v[58:61]
	v_mfma_f32_16x16x32_bf16 v[212:215], v[172:175], v[148:151], v[54:57]
	v_mfma_f32_16x16x32_bf16 v[216:219], v[172:175], v[152:155], v[50:53]
	v_mfma_f32_16x16x32_bf16 v[220:223], v[180:183], v[148:151], v[46:49]
	v_mfma_f32_16x16x32_bf16 v[224:227], v[180:183], v[152:155], v[42:45]
	v_mfma_f32_16x16x32_bf16 v[138:141], v[188:191], v[148:151], v[38:41]
	v_mfma_f32_16x16x32_bf16 v[146:149], v[188:191], v[152:155], v[34:37]
	v_mfma_f32_16x16x32_bf16 v[30:33], v[160:163], v[98:101], v[30:33]
	v_mfma_f32_16x16x32_bf16 v[22:25], v[168:171], v[98:101], v[22:25]
	v_mfma_f32_16x16x32_bf16 v[14:17], v[176:179], v[98:101], v[14:17]
	v_mfma_f32_16x16x32_bf16 v[6:9], v[184:187], v[98:101], v[6:9]
	v_mfma_f32_16x16x32_bf16 v[30:33], v[164:167], v[106:109], v[30:33]
	v_mfma_f32_16x16x32_bf16 v[26:29], v[160:163], v[114:117], v[26:29]
	v_mfma_f32_16x16x32_bf16 v[22:25], v[172:175], v[106:109], v[22:25]
	v_mfma_f32_16x16x32_bf16 v[18:21], v[168:171], v[114:117], v[18:21]
	v_mfma_f32_16x16x32_bf16 v[14:17], v[180:183], v[106:109], v[14:17]
	v_mfma_f32_16x16x32_bf16 v[10:13], v[176:179], v[114:117], v[10:13]
	v_mfma_f32_16x16x32_bf16 v[6:9], v[188:191], v[106:109], v[6:9]
	v_mfma_f32_16x16x32_bf16 v[2:5], v[184:187], v[114:117], v[2:5]
	v_mfma_f32_16x16x32_bf16 v[150:153], v[164:167], v[122:125], v[26:29]
	v_mfma_f32_16x16x32_bf16 v[154:157], v[172:175], v[122:125], v[18:21]
	v_mfma_f32_16x16x32_bf16 v[158:161], v[180:183], v[122:125], v[10:13]
	v_mfma_f32_16x16x32_bf16 v[162:165], v[188:191], v[122:125], v[2:5]
	s_barrier
	s_nop 1
	ds_read_b128 v[2:5], v137
	ds_read_b128 v[166:169], v137 offset:1024
	ds_read_b128 v[170:173], v137 offset:2048
	ds_read_b128 v[174:177], v137 offset:3072
	ds_read_b128 v[10:13], v133 offset:32768
	ds_read_b128 v[18:21], v133 offset:33792
	ds_read_b128 v[26:29], v132 offset:32768
	ds_read_b128 v[38:41], v132 offset:33792
	ds_read_b128 v[46:49], v131 offset:32768
	ds_read_b128 v[178:181], v131 offset:33792
	ds_read_b128 v[182:185], v130 offset:32768
	ds_read_b128 v[186:189], v130 offset:33792
	s_waitcnt vmcnt(2)
	s_barrier
; #define WAIT_V(n) asm volatile("s_waitcnt vmcnt(" #n ")" ::: "memory")
; #define WAIT_L(n) asm volatile("s_waitcnt lgkmcnt(" #n ")" ::: "memory")
; #define BAR __builtin_amdgcn_s_barrier()
; __device__ __forceinline__ void mainloop_8phase(const u16* __restrict__ A, const u16* __restrict__ Bt, int K,
;                                                 f32x4 (&acc)[2][2][4][2], int wid_s, int ld) {
;     ...
;   { LDB(B0, 1, 0); LDA(At, 1, 0); WAIT_V(2); BAR; WAIT_L(0); MMA(0, 0, At, B0); BAR;
;     LDB(B1, 1, 1); WAIT_V(0); BAR; WAIT_L(0); MMA(0, 1, At, B1); BAR;
;     LDA(At, 1, 1); BAR; WAIT_L(0); MMA(1, 0, At, B0); MMA(1, 1, At, B1); BAR; }
;   if (wr == 0) BAR;
	s_waitcnt lgkmcnt(0)
	v_mfma_f32_16x16x32_bf16 v[34:37], v[10:13], v[2:5], v[126:129]
	v_mfma_f32_16x16x32_bf16 v[122:125], v[18:21], v[166:169], v[34:37]
	v_mfma_f32_16x16x32_bf16 v[34:37], v[10:13], v[170:173], v[142:145]
	v_mfma_f32_16x16x32_bf16 v[58:61], v[18:21], v[174:177], v[34:37]
	v_mfma_f32_16x16x32_bf16 v[34:37], v[26:29], v[2:5], v[118:121]
	v_mfma_f32_16x16x32_bf16 v[114:117], v[38:41], v[166:169], v[34:37]
	v_mfma_f32_16x16x32_bf16 v[34:37], v[26:29], v[170:173], v[192:195]
	v_mfma_f32_16x16x32_bf16 v[50:53], v[38:41], v[174:177], v[34:37]
	v_mfma_f32_16x16x32_bf16 v[34:37], v[46:49], v[2:5], v[110:113]
	v_mfma_f32_16x16x32_bf16 v[106:109], v[178:181], v[166:169], v[34:37]
	v_mfma_f32_16x16x32_bf16 v[34:37], v[46:49], v[170:173], v[196:199]
	v_mfma_f32_16x16x32_bf16 v[42:45], v[178:181], v[174:177], v[34:37]
	v_mfma_f32_16x16x32_bf16 v[34:37], v[182:185], v[2:5], v[102:105]
	v_mfma_f32_16x16x32_bf16 v[98:101], v[186:189], v[166:169], v[34:37]
	v_mfma_f32_16x16x32_bf16 v[34:37], v[182:185], v[170:173], v[200:203]
	v_mfma_f32_16x16x32_bf16 v[34:37], v[186:189], v[174:177], v[34:37]
	s_barrier
	ds_read_b128 v[142:145], v134
	ds_read_b128 v[190:193], v134 offset:1024
	ds_read_b128 v[194:197], v134 offset:2048
	ds_read_b128 v[134:137], v134 offset:3072
	s_waitcnt vmcnt(0)
	s_barrier
	s_waitcnt lgkmcnt(0)
	v_mfma_f32_16x16x32_bf16 v[54:57], v[10:13], v[142:145], v[94:97]
	v_mfma_f32_16x16x32_bf16 v[10:13], v[10:13], v[194:197], v[90:93]
	v_mfma_f32_16x16x32_bf16 v[62:65], v[18:21], v[134:137], v[10:13]
	v_mfma_f32_16x16x32_bf16 v[10:13], v[26:29], v[142:145], v[86:89]
	v_mfma_f32_16x16x32_bf16 v[118:121], v[38:41], v[190:193], v[10:13]
	v_mfma_f32_16x16x32_bf16 v[10:13], v[26:29], v[194:197], v[82:85]
	v_mfma_f32_16x16x32_bf16 v[126:129], v[18:21], v[190:193], v[54:57]
	v_mfma_f32_16x16x32_bf16 v[54:57], v[38:41], v[134:137], v[10:13]
	v_mfma_f32_16x16x32_bf16 v[10:13], v[46:49], v[142:145], v[78:81]
	v_mfma_f32_16x16x32_bf16 v[110:113], v[178:181], v[190:193], v[10:13]
	v_mfma_f32_16x16x32_bf16 v[10:13], v[46:49], v[194:197], v[74:77]
	v_mfma_f32_16x16x32_bf16 v[46:49], v[178:181], v[134:137], v[10:13]
	v_mfma_f32_16x16x32_bf16 v[10:13], v[182:185], v[142:145], v[70:73]
	v_mfma_f32_16x16x32_bf16 v[102:105], v[186:189], v[190:193], v[10:13]
	v_mfma_f32_16x16x32_bf16 v[10:13], v[182:185], v[194:197], v[66:69]
	v_mfma_f32_16x16x32_bf16 v[38:41], v[186:189], v[134:137], v[10:13]
	s_barrier
	ds_read_b128 v[66:69], v133 offset:49152
	ds_read_b128 v[78:81], v133 offset:50176
	ds_read_b128 v[178:181], v132 offset:49152
	ds_read_b128 v[182:185], v132 offset:50176
	ds_read_b128 v[186:189], v131 offset:49152
	ds_read_b128 v[198:201], v131 offset:50176
	ds_read_b128 v[228:231], v130 offset:49152
	ds_read_b128 v[130:133], v130 offset:50176
	s_barrier
	s_waitcnt lgkmcnt(0)
	v_mfma_f32_16x16x32_bf16 v[10:13], v[66:69], v[2:5], v[204:207]
	v_mfma_f32_16x16x32_bf16 v[90:93], v[78:81], v[166:169], v[10:13]
	v_mfma_f32_16x16x32_bf16 v[10:13], v[66:69], v[170:173], v[208:211]
	v_mfma_f32_16x16x32_bf16 v[26:29], v[78:81], v[174:177], v[10:13]
	v_mfma_f32_16x16x32_bf16 v[10:13], v[178:181], v[2:5], v[212:215]
	v_mfma_f32_16x16x32_bf16 v[82:85], v[182:185], v[166:169], v[10:13]
	v_mfma_f32_16x16x32_bf16 v[10:13], v[178:181], v[170:173], v[216:219]
	v_mfma_f32_16x16x32_bf16 v[18:21], v[182:185], v[174:177], v[10:13]
	v_mfma_f32_16x16x32_bf16 v[10:13], v[186:189], v[2:5], v[220:223]
	v_mfma_f32_16x16x32_bf16 v[2:5], v[228:231], v[2:5], v[138:141]
	v_mfma_f32_16x16x32_bf16 v[74:77], v[198:201], v[166:169], v[10:13]
	v_mfma_f32_16x16x32_bf16 v[10:13], v[186:189], v[170:173], v[224:227]
	v_mfma_f32_16x16x32_bf16 v[70:73], v[130:133], v[166:169], v[2:5]
	v_mfma_f32_16x16x32_bf16 v[2:5], v[228:231], v[170:173], v[146:149]
	v_mfma_f32_16x16x32_bf16 v[10:13], v[198:201], v[174:177], v[10:13]
	v_mfma_f32_16x16x32_bf16 v[2:5], v[130:133], v[174:177], v[2:5]
	v_mfma_f32_16x16x32_bf16 v[30:33], v[66:69], v[142:145], v[30:33]
	v_mfma_f32_16x16x32_bf16 v[94:97], v[78:81], v[190:193], v[30:33]
	v_mfma_f32_16x16x32_bf16 v[30:33], v[66:69], v[194:197], v[150:153]
	v_mfma_f32_16x16x32_bf16 v[22:25], v[178:181], v[142:145], v[22:25]
	v_mfma_f32_16x16x32_bf16 v[14:17], v[186:189], v[142:145], v[14:17]
	v_mfma_f32_16x16x32_bf16 v[6:9], v[228:231], v[142:145], v[6:9]
	v_mfma_f32_16x16x32_bf16 v[30:33], v[78:81], v[134:137], v[30:33]
	v_mfma_f32_16x16x32_bf16 v[86:89], v[182:185], v[190:193], v[22:25]
	v_mfma_f32_16x16x32_bf16 v[22:25], v[178:181], v[194:197], v[154:157]
	v_mfma_f32_16x16x32_bf16 v[78:81], v[198:201], v[190:193], v[14:17]
	v_mfma_f32_16x16x32_bf16 v[14:17], v[186:189], v[194:197], v[158:161]
	v_mfma_f32_16x16x32_bf16 v[66:69], v[130:133], v[190:193], v[6:9]
	v_mfma_f32_16x16x32_bf16 v[6:9], v[228:231], v[194:197], v[162:165]
	v_mfma_f32_16x16x32_bf16 v[22:25], v[182:185], v[134:137], v[22:25]
	v_mfma_f32_16x16x32_bf16 v[14:17], v[198:201], v[134:137], v[14:17]
	v_mfma_f32_16x16x32_bf16 v[6:9], v[130:133], v[134:137], v[6:9]
	s_movk_i32 s1, 0x100
	v_cmp_gt_u32_e32 vcc, s1, v0
	s_barrier
	s_and_saveexec_b64 s[2:3], vcc
	s_cbranch_execz .LBB0_345
	s_barrier

; #define WAIT_V(n) asm volatile("s_waitcnt vmcnt(" #n ")" ::: "memory")
; #define WAIT_L(n) asm volatile("s_waitcnt lgkmcnt(" #n ")" ::: "memory")
; #define BAR __builtin_amdgcn_s_barrier()
; #define SCHED __builtin_amdgcn_sched_barrier(0)
; __device__ __forceinline__ void mainloop_8phase(const u16* __restrict__ A, const u16* __restrict__ Bt, int K,
;                                                 f32x4 (&acc)[2][2][4][2], int wid_s, int ld) {
;     ...
;   for (int t = 0; t < nt - 2; t += 2) {
;     LDB(B0, 0, 0); SCHED; LDA(At, 0, 0); STAGE(SA(1, 1), A, brow + G_HALF, t + 1);
;     WAIT_L(8); BAR; WAIT_L(0); MMA(0, 0, At, B0); BAR; SCHED;
;     LDB(B1, 0, 1); STAGE(SB(0, 0), Bt, bcol, t + 2);
;     BAR; WAIT_L(0); MMA(0, 1, At, B1); BAR;
;     LDA(At, 0, 1); STAGE(SA(0, 0), A, brow, t + 2);
;     BAR; WAIT_L(0); MMA(1, 0, At, B0); BAR; SCHED;
;     STAGE(SB(0, 1), Bt, bcol + G_HALF, t + 2);
;     WAIT_V(6); BAR; MMA(1, 1, At, B1); BAR;
.LBB0_565:
	ds_read_b128 v[158:161], v156
	ds_read_b128 v[162:165], v156 offset:1024
	ds_read_b128 v[166:169], v156 offset:2048
	ds_read_b128 v[170:173], v156 offset:3072
	s_add_i32 s15, s27, s3
	s_add_i32 s6, s15, 0x80
	s_add_i32 m0, s100, 0xc000
	ds_read_b128 v[174:177], v134
	ds_read_b128 v[178:181], v134 offset:1024
	ds_read_b128 v[182:185], v133
	ds_read_b128 v[186:189], v133 offset:1024
	ds_read_b128 v[190:193], v132
	ds_read_b128 v[194:197], v132 offset:1024
	ds_read_b128 v[198:201], v131
	buffer_load_dwordx4 v137, s[76:79], s6 offen lds
	s_add_i32 m0, s100, 0xe000
	ds_read_b128 v[202:205], v131 offset:1024
	buffer_load_dwordx4 v138, s[76:79], s6 offen lds
	s_waitcnt lgkmcnt(8)
	s_barrier
	s_waitcnt lgkmcnt(0)
	v_mfma_f32_16x16x32_bf16 v[126:129], v[174:177], v[158:161], v[126:129]
	v_mfma_f32_16x16x32_bf16 v[122:125], v[174:177], v[166:169], v[122:125]
	v_mfma_f32_16x16x32_bf16 v[118:121], v[182:185], v[158:161], v[118:121]
	v_mfma_f32_16x16x32_bf16 v[114:117], v[182:185], v[166:169], v[114:117]
	v_mfma_f32_16x16x32_bf16 v[110:113], v[190:193], v[158:161], v[110:113]
	v_mfma_f32_16x16x32_bf16 v[106:109], v[190:193], v[166:169], v[106:109]
	v_mfma_f32_16x16x32_bf16 v[102:105], v[198:201], v[158:161], v[102:105]
	v_mfma_f32_16x16x32_bf16 v[98:101], v[198:201], v[166:169], v[98:101]
	v_mfma_f32_16x16x32_bf16 v[126:129], v[178:181], v[162:165], v[126:129]
	v_mfma_f32_16x16x32_bf16 v[122:125], v[178:181], v[170:173], v[122:125]
	v_mfma_f32_16x16x32_bf16 v[118:121], v[186:189], v[162:165], v[118:121]
	v_mfma_f32_16x16x32_bf16 v[114:117], v[186:189], v[170:173], v[114:117]
	v_mfma_f32_16x16x32_bf16 v[110:113], v[194:197], v[162:165], v[110:113]
	v_mfma_f32_16x16x32_bf16 v[106:109], v[194:197], v[170:173], v[106:109]
	v_mfma_f32_16x16x32_bf16 v[102:105], v[202:205], v[162:165], v[102:105]
	v_mfma_f32_16x16x32_bf16 v[98:101], v[202:205], v[170:173], v[98:101]
	s_barrier
	s_add_i32 s14, s3, 0x100
	s_mov_b32 s6, s78
	s_mov_b32 s7, s79
	s_add_i32 m0, s100, 0x10000
	ds_read_b128 v[206:209], v148
	ds_read_b128 v[210:213], v148 offset:1024
	ds_read_b128 v[214:217], v148 offset:2048
	ds_read_b128 v[218:221], v148 offset:3072
	buffer_load_dwordx4 v137, s[4:7], s14 offen lds
	s_add_i32 m0, s100, 0x12000
	s_add_i32 s2, s2, 2
	buffer_load_dwordx4 v138, s[4:7], s14 offen lds
	s_barrier
	s_waitcnt lgkmcnt(0)
	v_mfma_f32_16x16x32_bf16 v[94:97], v[174:177], v[206:209], v[94:97]
	v_mfma_f32_16x16x32_bf16 v[90:93], v[174:177], v[214:217], v[90:93]
	v_mfma_f32_16x16x32_bf16 v[86:89], v[182:185], v[206:209], v[86:89]
	v_mfma_f32_16x16x32_bf16 v[82:85], v[182:185], v[214:217], v[82:85]
	v_mfma_f32_16x16x32_bf16 v[78:81], v[190:193], v[206:209], v[78:81]
	v_mfma_f32_16x16x32_bf16 v[74:77], v[190:193], v[214:217], v[74:77]
	v_mfma_f32_16x16x32_bf16 v[70:73], v[198:201], v[206:209], v[70:73]
	v_mfma_f32_16x16x32_bf16 v[66:69], v[198:201], v[214:217], v[66:69]
	v_mfma_f32_16x16x32_bf16 v[94:97], v[178:181], v[210:213], v[94:97]
	v_mfma_f32_16x16x32_bf16 v[90:93], v[178:181], v[218:221], v[90:93]
	v_mfma_f32_16x16x32_bf16 v[86:89], v[186:189], v[210:213], v[86:89]
	v_mfma_f32_16x16x32_bf16 v[82:85], v[186:189], v[218:221], v[82:85]
	v_mfma_f32_16x16x32_bf16 v[78:81], v[194:197], v[210:213], v[78:81]
	v_mfma_f32_16x16x32_bf16 v[74:77], v[194:197], v[218:221], v[74:77]
	v_mfma_f32_16x16x32_bf16 v[70:73], v[202:205], v[210:213], v[70:73]
	v_mfma_f32_16x16x32_bf16 v[66:69], v[202:205], v[218:221], v[66:69]
	s_mov_b32 m0, s100
	s_barrier
	ds_read_b128 v[174:177], v134 offset:16384
	ds_read_b128 v[178:181], v134 offset:17408
	ds_read_b128 v[182:185], v133 offset:16384
	ds_read_b128 v[186:189], v133 offset:17408
	ds_read_b128 v[190:193], v132 offset:16384
	ds_read_b128 v[194:197], v132 offset:17408
	ds_read_b128 v[198:201], v131 offset:16384
	buffer_load_dwordx4 v137, s[76:79], s14 offen lds
	s_add_i32 m0, s100, 0x2000
	ds_read_b128 v[202:205], v131 offset:17408
	buffer_load_dwordx4 v138, s[76:79], s14 offen lds
	s_barrier
	s_waitcnt lgkmcnt(0)
	v_mfma_f32_16x16x32_bf16 v[62:65], v[174:177], v[158:161], v[62:65]
	v_mfma_f32_16x16x32_bf16 v[58:61], v[174:177], v[166:169], v[58:61]
	v_mfma_f32_16x16x32_bf16 v[54:57], v[182:185], v[158:161], v[54:57]
	v_mfma_f32_16x16x32_bf16 v[50:53], v[182:185], v[166:169], v[50:53]
	v_mfma_f32_16x16x32_bf16 v[46:49], v[190:193], v[158:161], v[46:49]
	v_mfma_f32_16x16x32_bf16 v[42:45], v[190:193], v[166:169], v[42:45]
	v_mfma_f32_16x16x32_bf16 v[38:41], v[198:201], v[158:161], v[38:41]
	v_mfma_f32_16x16x32_bf16 v[34:37], v[198:201], v[166:169], v[34:37]
	v_mfma_f32_16x16x32_bf16 v[62:65], v[178:181], v[162:165], v[62:65]
	v_mfma_f32_16x16x32_bf16 v[58:61], v[178:181], v[170:173], v[58:61]
	v_mfma_f32_16x16x32_bf16 v[54:57], v[186:189], v[162:165], v[54:57]
	v_mfma_f32_16x16x32_bf16 v[50:53], v[186:189], v[170:173], v[50:53]
	v_mfma_f32_16x16x32_bf16 v[46:49], v[194:197], v[162:165], v[46:49]
	v_mfma_f32_16x16x32_bf16 v[42:45], v[194:197], v[170:173], v[42:45]
	v_mfma_f32_16x16x32_bf16 v[38:41], v[202:205], v[162:165], v[38:41]
	v_mfma_f32_16x16x32_bf16 v[34:37], v[202:205], v[170:173], v[34:37]
	s_barrier
	s_add_i32 s34, s15, 0x100
	s_add_i32 m0, s100, 0x14000
	buffer_load_dwordx4 v137, s[4:7], s34 offen lds
	s_add_i32 m0, s100, 0x16000
	s_nop 0
	buffer_load_dwordx4 v138, s[4:7], s34 offen lds
	s_waitcnt vmcnt(6)
	s_barrier
; #define WAIT_V(n) asm volatile("s_waitcnt vmcnt(" #n ")" ::: "memory")
; #define WAIT_L(n) asm volatile("s_waitcnt lgkmcnt(" #n ")" ::: "memory")
; #define BAR __builtin_amdgcn_s_barrier()
; #define SCHED __builtin_amdgcn_sched_barrier(0)
; __device__ __forceinline__ void mainloop_8phase(const u16* __restrict__ A, const u16* __restrict__ Bt, int K,
;                                                 f32x4 (&acc)[2][2][4][2], int wid_s, int ld) {
;     ...
;     WAIT_V(6); BAR; MMA(1, 1, At, B1); BAR;
;     LDB(B0, 1, 0); SCHED; LDA(At, 1, 0); STAGE(SA(0, 1), A, brow + G_HALF, t + 2);
;     WAIT_L(8); BAR; WAIT_L(0); MMA(0, 0, At, B0); BAR; SCHED;
;     LDB(B1, 1, 1); STAGE(SB(1, 0), Bt, bcol, t + 3);
;     BAR; WAIT_L(0); MMA(0, 1, At, B1); BAR;
;     LDA(At, 1, 1); STAGE(SA(1, 0), A, brow, t + 3);
;     BAR; WAIT_L(0); MMA(1, 0, At, B0); BAR; SCHED;
	v_mfma_f32_16x16x32_bf16 v[30:33], v[174:177], v[206:209], v[30:33]
	v_mfma_f32_16x16x32_bf16 v[26:29], v[174:177], v[214:217], v[26:29]
	v_mfma_f32_16x16x32_bf16 v[22:25], v[182:185], v[206:209], v[22:25]
	v_mfma_f32_16x16x32_bf16 v[18:21], v[182:185], v[214:217], v[18:21]
	v_mfma_f32_16x16x32_bf16 v[14:17], v[190:193], v[206:209], v[14:17]
	v_mfma_f32_16x16x32_bf16 v[10:13], v[190:193], v[214:217], v[10:13]
	v_mfma_f32_16x16x32_bf16 v[6:9], v[198:201], v[206:209], v[6:9]
	v_mfma_f32_16x16x32_bf16 v[2:5], v[198:201], v[214:217], v[2:5]
	v_mfma_f32_16x16x32_bf16 v[30:33], v[178:181], v[210:213], v[30:33]
	v_mfma_f32_16x16x32_bf16 v[26:29], v[178:181], v[218:221], v[26:29]
	v_mfma_f32_16x16x32_bf16 v[22:25], v[186:189], v[210:213], v[22:25]
	v_mfma_f32_16x16x32_bf16 v[18:21], v[186:189], v[218:221], v[18:21]
	v_mfma_f32_16x16x32_bf16 v[14:17], v[194:197], v[210:213], v[14:17]
	v_mfma_f32_16x16x32_bf16 v[10:13], v[194:197], v[218:221], v[10:13]
	v_mfma_f32_16x16x32_bf16 v[6:9], v[202:205], v[210:213], v[6:9]
	v_mfma_f32_16x16x32_bf16 v[2:5], v[202:205], v[218:221], v[2:5]
	s_barrier
	ds_read_b128 v[158:161], v136
	ds_read_b128 v[162:165], v136 offset:1024
	ds_read_b128 v[166:169], v136 offset:2048
	ds_read_b128 v[170:173], v136 offset:3072
	s_add_i32 m0, s100, 0x4000
	ds_read_b128 v[174:177], v134 offset:32768
	ds_read_b128 v[178:181], v134 offset:33792
	ds_read_b128 v[182:185], v133 offset:32768
	ds_read_b128 v[186:189], v133 offset:33792
	ds_read_b128 v[190:193], v132 offset:32768
	ds_read_b128 v[194:197], v132 offset:33792
	ds_read_b128 v[198:201], v131 offset:32768
	buffer_load_dwordx4 v137, s[76:79], s34 offen lds
	s_add_i32 m0, s100, 0x6000
	ds_read_b128 v[202:205], v131 offset:33792
	buffer_load_dwordx4 v138, s[76:79], s34 offen lds
	s_waitcnt lgkmcnt(8)
	s_barrier
	s_waitcnt lgkmcnt(0)
	v_mfma_f32_16x16x32_bf16 v[126:129], v[174:177], v[158:161], v[126:129]
	v_mfma_f32_16x16x32_bf16 v[122:125], v[174:177], v[166:169], v[122:125]
	v_mfma_f32_16x16x32_bf16 v[118:121], v[182:185], v[158:161], v[118:121]
	v_mfma_f32_16x16x32_bf16 v[114:117], v[182:185], v[166:169], v[114:117]
	v_mfma_f32_16x16x32_bf16 v[110:113], v[190:193], v[158:161], v[110:113]
	v_mfma_f32_16x16x32_bf16 v[106:109], v[190:193], v[166:169], v[106:109]
	v_mfma_f32_16x16x32_bf16 v[102:105], v[198:201], v[158:161], v[102:105]
	v_mfma_f32_16x16x32_bf16 v[98:101], v[198:201], v[166:169], v[98:101]
	v_mfma_f32_16x16x32_bf16 v[126:129], v[178:181], v[162:165], v[126:129]
	v_mfma_f32_16x16x32_bf16 v[122:125], v[178:181], v[170:173], v[122:125]
	v_mfma_f32_16x16x32_bf16 v[118:121], v[186:189], v[162:165], v[118:121]
	v_mfma_f32_16x16x32_bf16 v[114:117], v[186:189], v[170:173], v[114:117]
	v_mfma_f32_16x16x32_bf16 v[110:113], v[194:197], v[162:165], v[110:113]
	v_mfma_f32_16x16x32_bf16 v[106:109], v[194:197], v[170:173], v[106:109]
	v_mfma_f32_16x16x32_bf16 v[102:105], v[202:205], v[162:165], v[102:105]
	v_mfma_f32_16x16x32_bf16 v[98:101], v[202:205], v[170:173], v[98:101]
	s_barrier
	s_addk_i32 s3, 0x180
	s_add_i32 m0, s100, 0x18000
	ds_read_b128 v[206:209], v135
	ds_read_b128 v[210:213], v135 offset:1024
	ds_read_b128 v[214:217], v135 offset:2048
	buffer_load_dwordx4 v137, s[4:7], s3 offen lds
	s_add_i32 m0, s100, 0x1a000
	ds_read_b128 v[218:221], v135 offset:3072
	buffer_load_dwordx4 v138, s[4:7], s3 offen lds
	s_barrier
	s_waitcnt lgkmcnt(0)
	v_mfma_f32_16x16x32_bf16 v[94:97], v[174:177], v[206:209], v[94:97]
	v_mfma_f32_16x16x32_bf16 v[90:93], v[174:177], v[214:217], v[90:93]
	v_mfma_f32_16x16x32_bf16 v[86:89], v[182:185], v[206:209], v[86:89]
	v_mfma_f32_16x16x32_bf16 v[82:85], v[182:185], v[214:217], v[82:85]
	v_mfma_f32_16x16x32_bf16 v[78:81], v[190:193], v[206:209], v[78:81]
	v_mfma_f32_16x16x32_bf16 v[74:77], v[190:193], v[214:217], v[74:77]
	v_mfma_f32_16x16x32_bf16 v[70:73], v[198:201], v[206:209], v[70:73]
	v_mfma_f32_16x16x32_bf16 v[66:69], v[198:201], v[214:217], v[66:69]
	v_mfma_f32_16x16x32_bf16 v[94:97], v[178:181], v[210:213], v[94:97]
	v_mfma_f32_16x16x32_bf16 v[90:93], v[178:181], v[218:221], v[90:93]
	v_mfma_f32_16x16x32_bf16 v[86:89], v[186:189], v[210:213], v[86:89]
	v_mfma_f32_16x16x32_bf16 v[82:85], v[186:189], v[218:221], v[82:85]
	v_mfma_f32_16x16x32_bf16 v[78:81], v[194:197], v[210:213], v[78:81]
	v_mfma_f32_16x16x32_bf16 v[74:77], v[194:197], v[218:221], v[74:77]
	v_mfma_f32_16x16x32_bf16 v[70:73], v[202:205], v[210:213], v[70:73]
	v_mfma_f32_16x16x32_bf16 v[66:69], v[202:205], v[218:221], v[66:69]
	s_add_i32 m0, s100, 0x8000
	s_barrier
	ds_read_b128 v[174:177], v134 offset:49152
	ds_read_b128 v[178:181], v134 offset:50176
	ds_read_b128 v[182:185], v133 offset:49152
	ds_read_b128 v[186:189], v133 offset:50176
	ds_read_b128 v[190:193], v132 offset:49152
	ds_read_b128 v[194:197], v132 offset:50176
	ds_read_b128 v[198:201], v131 offset:49152
	buffer_load_dwordx4 v137, s[76:79], s3 offen lds
	s_add_i32 m0, s100, 0xa000
	ds_read_b128 v[202:205], v131 offset:50176
	buffer_load_dwordx4 v138, s[76:79], s3 offen lds
	s_barrier
	s_waitcnt lgkmcnt(0)
	v_mfma_f32_16x16x32_bf16 v[62:65], v[174:177], v[158:161], v[62:65]
	v_mfma_f32_16x16x32_bf16 v[58:61], v[174:177], v[166:169], v[58:61]
	v_mfma_f32_16x16x32_bf16 v[54:57], v[182:185], v[158:161], v[54:57]
	v_mfma_f32_16x16x32_bf16 v[50:53], v[182:185], v[166:169], v[50:53]
	v_mfma_f32_16x16x32_bf16 v[46:49], v[190:193], v[158:161], v[46:49]
	v_mfma_f32_16x16x32_bf16 v[42:45], v[190:193], v[166:169], v[42:45]
	v_mfma_f32_16x16x32_bf16 v[38:41], v[198:201], v[158:161], v[38:41]
	v_mfma_f32_16x16x32_bf16 v[34:37], v[198:201], v[166:169], v[34:37]
	v_mfma_f32_16x16x32_bf16 v[62:65], v[178:181], v[162:165], v[62:65]
	v_mfma_f32_16x16x32_bf16 v[58:61], v[178:181], v[170:173], v[58:61]
	v_mfma_f32_16x16x32_bf16 v[54:57], v[186:189], v[162:165], v[54:57]
	v_mfma_f32_16x16x32_bf16 v[50:53], v[186:189], v[170:173], v[50:53]
	v_mfma_f32_16x16x32_bf16 v[46:49], v[194:197], v[162:165], v[46:49]
	v_mfma_f32_16x16x32_bf16 v[42:45], v[194:197], v[170:173], v[42:45]
	v_mfma_f32_16x16x32_bf16 v[38:41], v[202:205], v[162:165], v[38:41]
	v_mfma_f32_16x16x32_bf16 v[34:37], v[202:205], v[170:173], v[34:37]
	s_barrier
; #define WAIT_V(n) asm volatile("s_waitcnt vmcnt(" #n ")" ::: "memory")
; #define WAIT_L(n) asm volatile("s_waitcnt lgkmcnt(" #n ")" ::: "memory")
; #define BAR __builtin_amdgcn_s_barrier()
; __device__ __forceinline__ void mainloop_8phase(const u16* __restrict__ A, const u16* __restrict__ Bt, int K,
;                                                 f32x4 (&acc)[2][2][4][2], int wid_s, int ld) {
;     ...
;     STAGE(SB(1, 1), Bt, bcol + G_HALF, t + 3);
;     WAIT_V(6); BAR; MMA(1, 1, At, B1); BAR;
;   }
;   { LDB(B0, 0, 0); LDA(At, 0, 0); STAGE(SA(1, 1), A, brow + G_HALF, nt - 1);
;     BAR; WAIT_L(0); MMA(0, 0, At, B0); BAR;
;     LDB(B1, 0, 1); BAR; WAIT_L(0); MMA(0, 1, At, B1); BAR;
;     LDA(At, 0, 1); WAIT_V(4); BAR; WAIT_L(0); MMA(1, 0, At, B0); MMA(1, 1, At, B1); BAR; }
;   { LDB(B0, 1, 0); LDA(At, 1, 0); WAIT_V(2); BAR; WAIT_L(0); MMA(0, 0, At, B0); BAR;
	s_addk_i32 s15, 0x180
	s_add_i32 m0, s100, 0x1c000
	buffer_load_dwordx4 v137, s[4:7], s15 offen lds
	s_add_i32 m0, s100, 0x1e000
	s_nop 0
	buffer_load_dwordx4 v138, s[4:7], s15 offen lds
	s_waitcnt vmcnt(6)
	s_barrier
	v_mfma_f32_16x16x32_bf16 v[30:33], v[174:177], v[206:209], v[30:33]
	v_mfma_f32_16x16x32_bf16 v[26:29], v[174:177], v[214:217], v[26:29]
	v_mfma_f32_16x16x32_bf16 v[22:25], v[182:185], v[206:209], v[22:25]
	v_mfma_f32_16x16x32_bf16 v[18:21], v[182:185], v[214:217], v[18:21]
	v_mfma_f32_16x16x32_bf16 v[14:17], v[190:193], v[206:209], v[14:17]
	v_mfma_f32_16x16x32_bf16 v[10:13], v[190:193], v[214:217], v[10:13]
	v_mfma_f32_16x16x32_bf16 v[6:9], v[198:201], v[206:209], v[6:9]
	v_mfma_f32_16x16x32_bf16 v[2:5], v[198:201], v[214:217], v[2:5]
	v_mfma_f32_16x16x32_bf16 v[30:33], v[178:181], v[210:213], v[30:33]
	v_mfma_f32_16x16x32_bf16 v[26:29], v[178:181], v[218:221], v[26:29]
	v_mfma_f32_16x16x32_bf16 v[22:25], v[186:189], v[210:213], v[22:25]
	v_mfma_f32_16x16x32_bf16 v[18:21], v[186:189], v[218:221], v[18:21]
	v_mfma_f32_16x16x32_bf16 v[14:17], v[194:197], v[210:213], v[14:17]
	v_mfma_f32_16x16x32_bf16 v[10:13], v[194:197], v[218:221], v[10:13]
	v_mfma_f32_16x16x32_bf16 v[6:9], v[202:205], v[210:213], v[6:9]
	v_mfma_f32_16x16x32_bf16 v[2:5], v[202:205], v[218:221], v[2:5]
	s_cmp_lt_u32 s2, s29
	s_mov_b32 s3, s14
	s_barrier
	s_cbranch_scc1 .LBB0_565
	v_readfirstlane_b32 s2, v146
	s_mov_b32 m0, s2
	v_readfirstlane_b32 s2, v145
	ds_read_b128 v[140:143], v156
	ds_read_b128 v[150:153], v156 offset:1024
	ds_read_b128 v[158:161], v156 offset:2048
	ds_read_b128 v[154:157], v156 offset:3072
	ds_read_b128 v[162:165], v134
	ds_read_b128 v[166:169], v134 offset:1024
	ds_read_b128 v[170:173], v133
	ds_read_b128 v[174:177], v133 offset:1024
	ds_read_b128 v[178:181], v132
	ds_read_b128 v[182:185], v132 offset:1024
	ds_read_b128 v[186:189], v131
	ds_read_b128 v[190:193], v131 offset:1024
	buffer_load_dwordx4 v137, s[76:79], s30 offen lds
	s_mov_b32 m0, s2
	s_nop 0
	buffer_load_dwordx4 v138, s[76:79], s30 offen lds
	s_barrier
	s_waitcnt lgkmcnt(0)
	v_mfma_f32_16x16x32_bf16 v[126:129], v[162:165], v[140:143], v[126:129]
	v_mfma_f32_16x16x32_bf16 v[118:121], v[170:173], v[140:143], v[118:121]
	v_mfma_f32_16x16x32_bf16 v[110:113], v[178:181], v[140:143], v[110:113]
	v_mfma_f32_16x16x32_bf16 v[102:105], v[186:189], v[140:143], v[102:105]
	v_mfma_f32_16x16x32_bf16 v[126:129], v[166:169], v[150:153], v[126:129]
	v_mfma_f32_16x16x32_bf16 v[122:125], v[162:165], v[158:161], v[122:125]
	v_mfma_f32_16x16x32_bf16 v[118:121], v[174:177], v[150:153], v[118:121]
	v_mfma_f32_16x16x32_bf16 v[114:117], v[170:173], v[158:161], v[114:117]
	v_mfma_f32_16x16x32_bf16 v[110:113], v[182:185], v[150:153], v[110:113]
	v_mfma_f32_16x16x32_bf16 v[106:109], v[178:181], v[158:161], v[106:109]
	v_mfma_f32_16x16x32_bf16 v[102:105], v[190:193], v[150:153], v[102:105]
	v_mfma_f32_16x16x32_bf16 v[98:101], v[186:189], v[158:161], v[98:101]
	v_mfma_f32_16x16x32_bf16 v[144:147], v[166:169], v[154:157], v[122:125]
	v_mfma_f32_16x16x32_bf16 v[194:197], v[174:177], v[154:157], v[114:117]
	v_mfma_f32_16x16x32_bf16 v[198:201], v[182:185], v[154:157], v[106:109]
	v_mfma_f32_16x16x32_bf16 v[202:205], v[190:193], v[154:157], v[98:101]
	s_barrier
	s_nop 1
	ds_read_b128 v[98:101], v148
	ds_read_b128 v[106:109], v148 offset:1024
	ds_read_b128 v[114:117], v148 offset:2048
	ds_read_b128 v[122:125], v148 offset:3072
	s_barrier
	s_waitcnt lgkmcnt(0)
	v_mfma_f32_16x16x32_bf16 v[94:97], v[162:165], v[98:101], v[94:97]
	v_mfma_f32_16x16x32_bf16 v[86:89], v[170:173], v[98:101], v[86:89]
	v_mfma_f32_16x16x32_bf16 v[78:81], v[178:181], v[98:101], v[78:81]
	v_mfma_f32_16x16x32_bf16 v[70:73], v[186:189], v[98:101], v[70:73]
	v_mfma_f32_16x16x32_bf16 v[94:97], v[166:169], v[106:109], v[94:97]
	v_mfma_f32_16x16x32_bf16 v[90:93], v[162:165], v[114:117], v[90:93]
	v_mfma_f32_16x16x32_bf16 v[86:89], v[174:177], v[106:109], v[86:89]
	v_mfma_f32_16x16x32_bf16 v[82:85], v[170:173], v[114:117], v[82:85]
	v_mfma_f32_16x16x32_bf16 v[78:81], v[182:185], v[106:109], v[78:81]
	v_mfma_f32_16x16x32_bf16 v[74:77], v[178:181], v[114:117], v[74:77]
	v_mfma_f32_16x16x32_bf16 v[70:73], v[190:193], v[106:109], v[70:73]
	v_mfma_f32_16x16x32_bf16 v[66:69], v[186:189], v[114:117], v[66:69]
	v_mfma_f32_16x16x32_bf16 v[162:165], v[166:169], v[122:125], v[90:93]
	v_mfma_f32_16x16x32_bf16 v[166:169], v[174:177], v[122:125], v[82:85]
	v_mfma_f32_16x16x32_bf16 v[170:173], v[182:185], v[122:125], v[74:77]
	v_mfma_f32_16x16x32_bf16 v[174:177], v[190:193], v[122:125], v[66:69]
	s_barrier
	s_nop 0
	ds_read_b128 v[66:69], v134 offset:16384
	ds_read_b128 v[74:77], v134 offset:17408
	ds_read_b128 v[82:85], v133 offset:16384
	ds_read_b128 v[90:93], v133 offset:17408
	ds_read_b128 v[178:181], v132 offset:16384
	ds_read_b128 v[182:185], v132 offset:17408
	ds_read_b128 v[186:189], v131 offset:16384
	ds_read_b128 v[190:193], v131 offset:17408
	s_waitcnt vmcnt(4)
	s_barrier
; #define WAIT_V(n) asm volatile("s_waitcnt vmcnt(" #n ")" ::: "memory")
; #define WAIT_L(n) asm volatile("s_waitcnt lgkmcnt(" #n ")" ::: "memory")
; #define BAR __builtin_amdgcn_s_barrier()
; __device__ __forceinline__ void mainloop_8phase(const u16* __restrict__ A, const u16* __restrict__ Bt, int K,
;                                                 f32x4 (&acc)[2][2][4][2], int wid_s, int ld) {
;     ...
;     LDA(At, 0, 1); WAIT_V(4); BAR; WAIT_L(0); MMA(1, 0, At, B0); MMA(1, 1, At, B1); BAR; }
;   { LDB(B0, 1, 0); LDA(At, 1, 0); WAIT_V(2); BAR; WAIT_L(0); MMA(0, 0, At, B0); BAR;
	s_waitcnt lgkmcnt(0)
	v_mfma_f32_16x16x32_bf16 v[62:65], v[66:69], v[140:143], v[62:65]
	v_mfma_f32_16x16x32_bf16 v[54:57], v[82:85], v[140:143], v[54:57]
	v_mfma_f32_16x16x32_bf16 v[46:49], v[178:181], v[140:143], v[46:49]
	v_mfma_f32_16x16x32_bf16 v[38:41], v[186:189], v[140:143], v[38:41]
	v_mfma_f32_16x16x32_bf16 v[62:65], v[74:77], v[150:153], v[62:65]
	v_mfma_f32_16x16x32_bf16 v[58:61], v[66:69], v[158:161], v[58:61]
	v_mfma_f32_16x16x32_bf16 v[54:57], v[90:93], v[150:153], v[54:57]
	v_mfma_f32_16x16x32_bf16 v[50:53], v[82:85], v[158:161], v[50:53]
	v_mfma_f32_16x16x32_bf16 v[46:49], v[182:185], v[150:153], v[46:49]
	v_mfma_f32_16x16x32_bf16 v[42:45], v[178:181], v[158:161], v[42:45]
	v_mfma_f32_16x16x32_bf16 v[38:41], v[190:193], v[150:153], v[38:41]
	v_mfma_f32_16x16x32_bf16 v[34:37], v[186:189], v[158:161], v[34:37]
	v_mfma_f32_16x16x32_bf16 v[206:209], v[74:77], v[154:157], v[58:61]
	v_mfma_f32_16x16x32_bf16 v[210:213], v[90:93], v[154:157], v[50:53]
	v_mfma_f32_16x16x32_bf16 v[214:217], v[182:185], v[154:157], v[42:45]
	v_mfma_f32_16x16x32_bf16 v[138:141], v[190:193], v[154:157], v[34:37]
	v_mfma_f32_16x16x32_bf16 v[30:33], v[66:69], v[98:101], v[30:33]
	v_mfma_f32_16x16x32_bf16 v[22:25], v[82:85], v[98:101], v[22:25]
	v_mfma_f32_16x16x32_bf16 v[14:17], v[178:181], v[98:101], v[14:17]
	v_mfma_f32_16x16x32_bf16 v[6:9], v[186:189], v[98:101], v[6:9]
	v_mfma_f32_16x16x32_bf16 v[30:33], v[74:77], v[106:109], v[30:33]
	v_mfma_f32_16x16x32_bf16 v[26:29], v[66:69], v[114:117], v[26:29]
	v_mfma_f32_16x16x32_bf16 v[22:25], v[90:93], v[106:109], v[22:25]
	v_mfma_f32_16x16x32_bf16 v[18:21], v[82:85], v[114:117], v[18:21]
	v_mfma_f32_16x16x32_bf16 v[14:17], v[182:185], v[106:109], v[14:17]
	v_mfma_f32_16x16x32_bf16 v[10:13], v[178:181], v[114:117], v[10:13]
	v_mfma_f32_16x16x32_bf16 v[6:9], v[190:193], v[106:109], v[6:9]
	v_mfma_f32_16x16x32_bf16 v[2:5], v[186:189], v[114:117], v[2:5]
	v_mfma_f32_16x16x32_bf16 v[148:151], v[74:77], v[122:125], v[26:29]
	v_mfma_f32_16x16x32_bf16 v[152:155], v[90:93], v[122:125], v[18:21]
	v_mfma_f32_16x16x32_bf16 v[156:159], v[182:185], v[122:125], v[10:13]
	v_mfma_f32_16x16x32_bf16 v[178:181], v[190:193], v[122:125], v[2:5]
	s_barrier
	s_nop 1
	ds_read_b128 v[2:5], v136
	ds_read_b128 v[10:13], v136 offset:1024
	ds_read_b128 v[18:21], v136 offset:2048
	ds_read_b128 v[26:29], v136 offset:3072
	ds_read_b128 v[34:37], v134 offset:32768
	ds_read_b128 v[42:45], v134 offset:33792
	ds_read_b128 v[50:53], v133 offset:32768
	ds_read_b128 v[58:61], v133 offset:33792
	ds_read_b128 v[66:69], v132 offset:32768
	ds_read_b128 v[182:185], v132 offset:33792
	ds_read_b128 v[186:189], v131 offset:32768
	ds_read_b128 v[190:193], v131 offset:33792
	s_waitcnt vmcnt(2)
	s_barrier
	s_waitcnt lgkmcnt(0)
	v_mfma_f32_16x16x32_bf16 v[74:77], v[34:37], v[2:5], v[126:129]
	v_mfma_f32_16x16x32_bf16 v[122:125], v[42:45], v[10:13], v[74:77]
	v_mfma_f32_16x16x32_bf16 v[74:77], v[34:37], v[18:21], v[144:147]
	v_mfma_f32_16x16x32_bf16 v[126:129], v[42:45], v[26:29], v[74:77]
	v_mfma_f32_16x16x32_bf16 v[74:77], v[50:53], v[2:5], v[118:121]
	v_mfma_f32_16x16x32_bf16 v[114:117], v[58:61], v[10:13], v[74:77]
	v_mfma_f32_16x16x32_bf16 v[74:77], v[50:53], v[18:21], v[194:197]
	v_mfma_f32_16x16x32_bf16 v[118:121], v[58:61], v[26:29], v[74:77]
	v_mfma_f32_16x16x32_bf16 v[74:77], v[66:69], v[2:5], v[110:113]
	v_mfma_f32_16x16x32_bf16 v[106:109], v[182:185], v[10:13], v[74:77]
	v_mfma_f32_16x16x32_bf16 v[74:77], v[66:69], v[18:21], v[198:201]
	v_mfma_f32_16x16x32_bf16 v[110:113], v[182:185], v[26:29], v[74:77]
	v_mfma_f32_16x16x32_bf16 v[74:77], v[186:189], v[2:5], v[102:105]
	v_mfma_f32_16x16x32_bf16 v[98:101], v[190:193], v[10:13], v[74:77]
	v_mfma_f32_16x16x32_bf16 v[74:77], v[186:189], v[18:21], v[202:205]
	v_mfma_f32_16x16x32_bf16 v[102:105], v[190:193], v[26:29], v[74:77]
	s_barrier
; #define WAIT_V(n) asm volatile("s_waitcnt vmcnt(" #n ")" ::: "memory")
; #define WAIT_L(n) asm volatile("s_waitcnt lgkmcnt(" #n ")" ::: "memory")
; #define BAR __builtin_amdgcn_s_barrier()
; __device__ __forceinline__ void mainloop_8phase(const u16* __restrict__ A, const u16* __restrict__ Bt, int K,
;                                                 f32x4 (&acc)[2][2][4][2], int wid_s, int ld) {
;     ...
;     LDB(B1, 1, 1); WAIT_V(0); BAR; WAIT_L(0); MMA(0, 1, At, B1); BAR;
;     LDA(At, 1, 1); BAR; WAIT_L(0); MMA(1, 0, At, B0); MMA(1, 1, At, B1); BAR; }
;   if (wr == 0) BAR;
	ds_read_b128 v[142:145], v135
	ds_read_b128 v[194:197], v135 offset:1024
	ds_read_b128 v[198:201], v135 offset:2048
	ds_read_b128 v[202:205], v135 offset:3072
	s_waitcnt vmcnt(0)
	s_barrier
	s_waitcnt lgkmcnt(0)
	v_mfma_f32_16x16x32_bf16 v[74:77], v[34:37], v[142:145], v[94:97]
	v_mfma_f32_16x16x32_bf16 v[34:37], v[34:37], v[198:201], v[162:165]
	v_mfma_f32_16x16x32_bf16 v[94:97], v[42:45], v[202:205], v[34:37]
	v_mfma_f32_16x16x32_bf16 v[34:37], v[50:53], v[142:145], v[86:89]
	v_mfma_f32_16x16x32_bf16 v[82:85], v[58:61], v[194:197], v[34:37]
	v_mfma_f32_16x16x32_bf16 v[34:37], v[50:53], v[198:201], v[166:169]
	v_mfma_f32_16x16x32_bf16 v[86:89], v[58:61], v[202:205], v[34:37]
	v_mfma_f32_16x16x32_bf16 v[34:37], v[66:69], v[142:145], v[78:81]
	v_mfma_f32_16x16x32_bf16 v[90:93], v[42:45], v[194:197], v[74:77]
	v_mfma_f32_16x16x32_bf16 v[74:77], v[182:185], v[194:197], v[34:37]
	v_mfma_f32_16x16x32_bf16 v[34:37], v[66:69], v[198:201], v[170:173]
	v_mfma_f32_16x16x32_bf16 v[78:81], v[182:185], v[202:205], v[34:37]
	v_mfma_f32_16x16x32_bf16 v[34:37], v[186:189], v[142:145], v[70:73]
	v_mfma_f32_16x16x32_bf16 v[66:69], v[190:193], v[194:197], v[34:37]
	v_mfma_f32_16x16x32_bf16 v[34:37], v[186:189], v[198:201], v[174:177]
	v_mfma_f32_16x16x32_bf16 v[70:73], v[190:193], v[202:205], v[34:37]
	s_barrier
	ds_read_b128 v[160:163], v134 offset:49152
	ds_read_b128 v[134:137], v134 offset:50176
	ds_read_b128 v[164:167], v133 offset:49152
	ds_read_b128 v[168:171], v133 offset:50176
	ds_read_b128 v[172:175], v132 offset:49152
	ds_read_b128 v[182:185], v132 offset:50176
	ds_read_b128 v[186:189], v131 offset:49152
	ds_read_b128 v[190:193], v131 offset:50176
	s_barrier
	s_waitcnt lgkmcnt(0)
	v_mfma_f32_16x16x32_bf16 v[34:37], v[160:163], v[2:5], v[62:65]
	v_mfma_f32_16x16x32_bf16 v[58:61], v[134:137], v[10:13], v[34:37]
	v_mfma_f32_16x16x32_bf16 v[34:37], v[160:163], v[18:21], v[206:209]
	v_mfma_f32_16x16x32_bf16 v[62:65], v[134:137], v[26:29], v[34:37]
	v_mfma_f32_16x16x32_bf16 v[34:37], v[164:167], v[2:5], v[54:57]
	v_mfma_f32_16x16x32_bf16 v[50:53], v[168:171], v[10:13], v[34:37]
	v_mfma_f32_16x16x32_bf16 v[34:37], v[164:167], v[18:21], v[210:213]
	v_mfma_f32_16x16x32_bf16 v[54:57], v[168:171], v[26:29], v[34:37]
	v_mfma_f32_16x16x32_bf16 v[34:37], v[172:175], v[2:5], v[46:49]
	v_mfma_f32_16x16x32_bf16 v[42:45], v[182:185], v[10:13], v[34:37]
	v_mfma_f32_16x16x32_bf16 v[34:37], v[172:175], v[18:21], v[214:217]
	v_mfma_f32_16x16x32_bf16 v[2:5], v[186:189], v[2:5], v[38:41]
	v_mfma_f32_16x16x32_bf16 v[46:49], v[182:185], v[26:29], v[34:37]
	v_mfma_f32_16x16x32_bf16 v[34:37], v[190:193], v[10:13], v[2:5]
	v_mfma_f32_16x16x32_bf16 v[2:5], v[186:189], v[18:21], v[138:141]
	v_mfma_f32_16x16x32_bf16 v[38:41], v[190:193], v[26:29], v[2:5]
	v_mfma_f32_16x16x32_bf16 v[2:5], v[160:163], v[142:145], v[30:33]
	v_mfma_f32_16x16x32_bf16 v[26:29], v[134:137], v[194:197], v[2:5]
	v_mfma_f32_16x16x32_bf16 v[2:5], v[160:163], v[198:201], v[148:151]
	v_mfma_f32_16x16x32_bf16 v[30:33], v[134:137], v[202:205], v[2:5]
	v_mfma_f32_16x16x32_bf16 v[2:5], v[164:167], v[142:145], v[22:25]
	v_mfma_f32_16x16x32_bf16 v[18:21], v[168:171], v[194:197], v[2:5]
	v_mfma_f32_16x16x32_bf16 v[2:5], v[164:167], v[198:201], v[152:155]
	v_mfma_f32_16x16x32_bf16 v[22:25], v[168:171], v[202:205], v[2:5]
	v_mfma_f32_16x16x32_bf16 v[2:5], v[172:175], v[142:145], v[14:17]
	v_mfma_f32_16x16x32_bf16 v[10:13], v[182:185], v[194:197], v[2:5]
	v_mfma_f32_16x16x32_bf16 v[2:5], v[172:175], v[198:201], v[156:159]
	v_mfma_f32_16x16x32_bf16 v[14:17], v[182:185], v[202:205], v[2:5]
	v_mfma_f32_16x16x32_bf16 v[2:5], v[186:189], v[142:145], v[6:9]
	v_mfma_f32_16x16x32_bf16 v[6:9], v[186:189], v[198:201], v[178:181]
	v_mfma_f32_16x16x32_bf16 v[2:5], v[190:193], v[194:197], v[2:5]
	v_mfma_f32_16x16x32_bf16 v[6:9], v[190:193], v[202:205], v[6:9]
	s_movk_i32 s2, 0x100
	v_cmp_gt_u32_e32 vcc, s2, v0
	s_barrier
	s_and_saveexec_b64 s[2:3], vcc
	s_cbranch_execz .LBB0_568
	s_barrier

; __global__ void __launch_bounds__(512) k_mega(Params p_in) {
	.amdhsa_kernel _Z6k_mega6Params
		.amdhsa_group_segment_fixed_size 16
		.amdhsa_private_segment_fixed_size 0
		.amdhsa_kernarg_size 448
		.amdhsa_user_sgpr_count 2
		.amdhsa_user_sgpr_dispatch_ptr 0
		.amdhsa_user_sgpr_queue_ptr 0
		.amdhsa_user_sgpr_kernarg_segment_ptr 1
		.amdhsa_user_sgpr_dispatch_id 0
		.amdhsa_user_sgpr_kernarg_preload_length 0
		.amdhsa_user_sgpr_kernarg_preload_offset 0
		.amdhsa_user_sgpr_private_segment_size 0
		.amdhsa_uses_dynamic_stack 0
		.amdhsa_enable_private_segment 0
		.amdhsa_system_sgpr_workgroup_id_x 1
		.amdhsa_system_sgpr_workgroup_id_y 0
		.amdhsa_system_sgpr_workgroup_id_z 0
		.amdhsa_system_sgpr_workgroup_info 0
		.amdhsa_system_vgpr_workitem_id 2
		.amdhsa_next_free_vgpr 256
		.amdhsa_next_free_sgpr 102
		.amdhsa_accum_offset 256
		.amdhsa_reserve_vcc 1
		.amdhsa_float_round_mode_32 0
		.amdhsa_float_round_mode_16_64 0
		.amdhsa_float_denorm_mode_32 3
		.amdhsa_float_denorm_mode_16_64 3
		.amdhsa_dx10_clamp 1
		.amdhsa_ieee_mode 1
		.amdhsa_fp16_overflow 0
		.amdhsa_tg_split 0
		.amdhsa_exception_fp_ieee_invalid_op 0
		.amdhsa_exception_fp_denorm_src 0
		.amdhsa_exception_fp_ieee_div_zero 0
		.amdhsa_exception_fp_ieee_overflow 0
		.amdhsa_exception_fp_ieee_underflow 0
		.amdhsa_exception_fp_ieee_inexact 0
		.amdhsa_exception_int_div_zero 0
	.end_amdhsa_kernel
